# rename-safe N=1 handoff + loader enqueues its first MFMA before its closing barrier
# baseline (speedup 1.0000x reference)
; #define PG8_STAGE(bufoff, gbase, voff) do { _Pragma("unroll") for (int _i = 0; _i < 2; ++_i) \
;         asm volatile("s_mov_b32 m0, %2\n\ts_nop 0\n\tglobal_load_lds_dwordx4 %0, %1" :: "v"((voff)[_i]), "s"((const char*)(gbase)), "s"(ldsbase + (unsigned)(bufoff) + ldsw + (unsigned)_i * 8192u) : "memory", "m0"); } while (0)
; #define PG8_LDA(dst, b, h) do { _Pragma("unroll") for (int m = 0; m < 4; ++m) _Pragma("unroll") for (int k = 0; k < 2; ++k) dst[m][k] = *(const PG8_LAS bf16x8*)(lds + PG8_SA(b, h) + aoff + m * 2048 + k * 1024); } while (0)
; #define PG8_LDB(dst, b, h) do { _Pragma("unroll") for (int n = 0; n < 2; ++n) _Pragma("unroll") for (int k = 0; k < 2; ++k) dst[n][k] = *(const PG8_LAS bf16x8*)(lds + PG8_SB(b, h) + boff + n * 2048 + k * 1024); } while (0)
; #define PG8_MMA(ai, bj, At, Bt) do { __builtin_amdgcn_s_setprio(1); _Pragma("unroll") for (int m = 0; m < 4; ++m) _Pragma("unroll") for (int n = 0; n < 2; ++n) _Pragma("unroll") for (int k = 0; k < 2; ++k) \
;         acc[ai][bj][m][n] = __builtin_amdgcn_mfma_f32_16x16x32_bf16(Bt[n][k], At[m][k], acc[ai][bj][m][n], 0, 0, 0); __builtin_amdgcn_s_setprio(0); } while (0)
; #define PG8_WAIT_V(n) asm volatile("s_waitcnt vmcnt(" #n ")" ::: "memory")
; #define PG8_WAIT_L(n) asm volatile("s_waitcnt lgkmcnt(" #n ")" ::: "memory")
; #define PG8_BAR __builtin_amdgcn_s_barrier()
; #define PG8_SCHED __builtin_amdgcn_sched_barrier(0)
; template <class Epi, class Sched, bool ALIGN_EPI = false, bool SP2 = false>
; __device__ __forceinline__ void gemm_phase(PG8_LAS unsigned char* lds, const Gemm g, const Sched& S, const Epi& E) {
;     ...
;             PG8_LDB(B0, 0, 0); PG8_LDB(B1, 0, 1); PG8_SCHED; PG8_LDA(At, 0, 0); PG8_STAGE(PG8_SA(1, 1), a1 + hstep, voffA);
;             PG8_WAIT_V(8); PG8_WAIT_L(0); PG8_BAR; PG8_MMA(0, 0, At, B0); PG8_MMA(0, 1, At, B1); PG8_BAR; PG8_SCHED;
;             PG8_LDA(At, 0, 1); PG8_STAGE(PG8_SB(0, 0), b2, voffB); PG8_STAGE(PG8_SB(0, 1), b2 + hstep, voffB); PG8_STAGE(PG8_SA(0, 0), a2, voffA);
;             PG8_WAIT_V(8); PG8_WAIT_L(0); PG8_BAR; PG8_MMA(1, 0, At, B0); PG8_MMA(1, 1, At, B1); PG8_BAR; PG8_SCHED;
.LBB0_138:
	ds_read_b128 v[148:151], v142
	ds_read_b128 v[152:155], v142 offset:1024
	ds_read_b128 v[156:159], v142 offset:2048
	ds_read_b128 v[160:163], v142 offset:3072
	ds_read_b128 v[164:167], v143
	ds_read_b128 v[168:171], v143 offset:1024
	ds_read_b128 v[172:175], v143 offset:2048
	ds_read_b128 v[176:179], v143 offset:3072
	s_add_u32 s62, s66, 0x100
	s_addc_u32 s63, s67, 0
	s_cmp_eq_u32 s96, 60
	s_cselect_b32 s86, s92, s62
	s_cselect_b32 s87, s13, s63
	s_cselect_b32 s84, s93, s94
	s_cselect_b32 s85, s11, s95
	s_add_u32 s76, s86, 0x80
	s_addc_u32 s77, s87, 0
	ds_read_b128 v[180:183], v144
	ds_read_b128 v[184:187], v144 offset:1024
	ds_read_b128 v[188:191], v144 offset:2048
	ds_read_b128 v[192:195], v144 offset:3072
	ds_read_b128 v[196:199], v144 offset:4096
	ds_read_b128 v[200:203], v144 offset:5120
	ds_read_b128 v[204:207], v144 offset:6144
	ds_read_b128 v[208:211], v144 offset:7168
	s_add_u32 s66, s66, 0x100080
	s_addc_u32 s67, s67, 0
	s_mov_b32 m0, s83
	s_nop 0
	global_load_lds_dwordx4 v136, s[66:67]
	s_nop 0
	s_mov_b32 m0, s88
	s_nop 0
	global_load_lds_dwordx4 v138, s[66:67]
	s_waitcnt vmcnt(8)
	s_waitcnt lgkmcnt(0)
	v_mfma_f32_16x16x32_bf16 v[126:129], v[148:151], v[180:183], v[126:129]
	s_barrier
	s_setprio 1
	s_waitcnt lgkmcnt(7)
	v_mfma_f32_16x16x32_bf16 v[122:125], v[156:159], v[180:183], v[122:125]
	s_waitcnt lgkmcnt(5)
	v_mfma_f32_16x16x32_bf16 v[110:113], v[148:151], v[188:191], v[110:113]
	v_mfma_f32_16x16x32_bf16 v[106:109], v[156:159], v[188:191], v[106:109]
	s_waitcnt lgkmcnt(3)
	v_mfma_f32_16x16x32_bf16 v[94:97], v[148:151], v[196:199], v[94:97]
	v_mfma_f32_16x16x32_bf16 v[90:93], v[156:159], v[196:199], v[90:93]
	s_waitcnt lgkmcnt(1)
	v_mfma_f32_16x16x32_bf16 v[78:81], v[148:151], v[204:207], v[78:81]
	v_mfma_f32_16x16x32_bf16 v[74:77], v[156:159], v[204:207], v[74:77]
	v_mfma_f32_16x16x32_bf16 v[126:129], v[152:155], v[184:187], v[126:129]
	v_mfma_f32_16x16x32_bf16 v[122:125], v[160:163], v[184:187], v[122:125]
	v_mfma_f32_16x16x32_bf16 v[110:113], v[152:155], v[192:195], v[110:113]
	v_mfma_f32_16x16x32_bf16 v[106:109], v[160:163], v[192:195], v[106:109]
	v_mfma_f32_16x16x32_bf16 v[94:97], v[152:155], v[200:203], v[94:97]
	v_mfma_f32_16x16x32_bf16 v[90:93], v[160:163], v[200:203], v[90:93]
	s_waitcnt lgkmcnt(0)
	v_mfma_f32_16x16x32_bf16 v[78:81], v[152:155], v[208:211], v[78:81]
	v_mfma_f32_16x16x32_bf16 v[74:77], v[160:163], v[208:211], v[74:77]
	s_setprio 0
	s_setprio 1
	v_mfma_f32_16x16x32_bf16 v[118:121], v[164:167], v[180:183], v[118:121]
	v_mfma_f32_16x16x32_bf16 v[114:117], v[172:175], v[180:183], v[114:117]
	v_mfma_f32_16x16x32_bf16 v[102:105], v[164:167], v[188:191], v[102:105]
	v_mfma_f32_16x16x32_bf16 v[98:101], v[172:175], v[188:191], v[98:101]
	v_mfma_f32_16x16x32_bf16 v[86:89], v[164:167], v[196:199], v[86:89]
	v_mfma_f32_16x16x32_bf16 v[82:85], v[172:175], v[196:199], v[82:85]
	v_mfma_f32_16x16x32_bf16 v[70:73], v[164:167], v[204:207], v[70:73]
	v_mfma_f32_16x16x32_bf16 v[66:69], v[172:175], v[204:207], v[66:69]
	v_mfma_f32_16x16x32_bf16 v[118:121], v[168:171], v[184:187], v[118:121]
	v_mfma_f32_16x16x32_bf16 v[114:117], v[176:179], v[184:187], v[114:117]
	v_mfma_f32_16x16x32_bf16 v[102:105], v[168:171], v[192:195], v[102:105]
	v_mfma_f32_16x16x32_bf16 v[98:101], v[176:179], v[192:195], v[98:101]
	v_mfma_f32_16x16x32_bf16 v[86:89], v[168:171], v[200:203], v[86:89]
	v_mfma_f32_16x16x32_bf16 v[82:85], v[176:179], v[200:203], v[82:85]
	v_mfma_f32_16x16x32_bf16 v[70:73], v[168:171], v[208:211], v[70:73]
	s_setprio 2
	s_barrier
	v_mfma_f32_16x16x32_bf16 v[66:69], v[176:179], v[208:211], v[66:69]
	s_setprio 0
	ds_read_b128 v[180:183], v144 offset:16384
	ds_read_b128 v[184:187], v144 offset:17408
	ds_read_b128 v[188:191], v144 offset:18432
	ds_read_b128 v[192:195], v144 offset:19456
	ds_read_b128 v[196:199], v144 offset:20480
	ds_read_b128 v[200:203], v144 offset:21504
	ds_read_b128 v[204:207], v144 offset:22528
	ds_read_b128 v[252:255], v144 offset:23552
	s_mov_b32 m0, s55
	s_nop 0
	global_load_lds_dwordx4 v137, s[84:85]
	s_add_u32 s66, s84, 0x100000
	s_mov_b32 m0, s56
	s_nop 0
	global_load_lds_dwordx4 v139, s[84:85]
	s_addc_u32 s67, s85, 0
	s_mov_b32 m0, s57
	s_nop 0
	global_load_lds_dwordx4 v137, s[66:67]
	s_nop 0
	s_mov_b32 m0, s58
	s_nop 0
	global_load_lds_dwordx4 v139, s[66:67]
	s_nop 0
	s_mov_b32 m0, s54
	s_nop 0
	global_load_lds_dwordx4 v136, s[86:87]
	s_nop 0
	s_mov_b32 m0, s59
	s_nop 0
	global_load_lds_dwordx4 v138, s[86:87]
	s_waitcnt vmcnt(8)
	s_waitcnt lgkmcnt(0)
	v_mfma_f32_16x16x32_bf16 v[62:65], v[148:151], v[180:183], v[62:65]
	s_barrier
; #define PG8_STAGE(bufoff, gbase, voff) do { _Pragma("unroll") for (int _i = 0; _i < 2; ++_i) \
;         asm volatile("s_mov_b32 m0, %2\n\ts_nop 0\n\tglobal_load_lds_dwordx4 %0, %1" :: "v"((voff)[_i]), "s"((const char*)(gbase)), "s"(ldsbase + (unsigned)(bufoff) + ldsw + (unsigned)_i * 8192u) : "memory", "m0"); } while (0)
; #define PG8_LDA(dst, b, h) do { _Pragma("unroll") for (int m = 0; m < 4; ++m) _Pragma("unroll") for (int k = 0; k < 2; ++k) dst[m][k] = *(const PG8_LAS bf16x8*)(lds + PG8_SA(b, h) + aoff + m * 2048 + k * 1024); } while (0)
; #define PG8_LDB(dst, b, h) do { _Pragma("unroll") for (int n = 0; n < 2; ++n) _Pragma("unroll") for (int k = 0; k < 2; ++k) dst[n][k] = *(const PG8_LAS bf16x8*)(lds + PG8_SB(b, h) + boff + n * 2048 + k * 1024); } while (0)
; #define PG8_MMA(ai, bj, At, Bt) do { __builtin_amdgcn_s_setprio(1); _Pragma("unroll") for (int m = 0; m < 4; ++m) _Pragma("unroll") for (int n = 0; n < 2; ++n) _Pragma("unroll") for (int k = 0; k < 2; ++k) \
;         acc[ai][bj][m][n] = __builtin_amdgcn_mfma_f32_16x16x32_bf16(Bt[n][k], At[m][k], acc[ai][bj][m][n], 0, 0, 0); __builtin_amdgcn_s_setprio(0); } while (0)
; #define PG8_WAIT_V(n) asm volatile("s_waitcnt vmcnt(" #n ")" ::: "memory")
; #define PG8_WAIT_L(n) asm volatile("s_waitcnt lgkmcnt(" #n ")" ::: "memory")
; #define PG8_BAR __builtin_amdgcn_s_barrier()
; #define PG8_SCHED __builtin_amdgcn_sched_barrier(0)
; template <class Epi, class Sched, bool ALIGN_EPI = false, bool SP2 = false>
; __device__ __forceinline__ void gemm_phase(PG8_LAS unsigned char* lds, const Gemm g, const Sched& S, const Epi& E) {
;     ...
;             PG8_WAIT_V(8); PG8_WAIT_L(0); PG8_BAR; PG8_MMA(1, 0, At, B0); PG8_MMA(1, 1, At, B1); PG8_BAR; PG8_SCHED;
;             PG8_LDB(B0, 1, 0); PG8_LDB(B1, 1, 1); PG8_SCHED; PG8_LDA(At, 1, 0); PG8_STAGE(PG8_SA(0, 1), a2 + hstep, voffA);
;             PG8_WAIT_V(8); PG8_WAIT_L(0); PG8_BAR; PG8_MMA(0, 0, At, B0); PG8_MMA(0, 1, At, B1); PG8_BAR; PG8_SCHED;
	s_setprio 1
	s_waitcnt lgkmcnt(7)
	v_mfma_f32_16x16x32_bf16 v[58:61], v[156:159], v[180:183], v[58:61]
	s_waitcnt lgkmcnt(5)
	v_mfma_f32_16x16x32_bf16 v[46:49], v[148:151], v[188:191], v[46:49]
	v_mfma_f32_16x16x32_bf16 v[42:45], v[156:159], v[188:191], v[42:45]
	s_waitcnt lgkmcnt(3)
	v_mfma_f32_16x16x32_bf16 v[30:33], v[148:151], v[196:199], v[30:33]
	v_mfma_f32_16x16x32_bf16 v[26:29], v[156:159], v[196:199], v[26:29]
	s_waitcnt lgkmcnt(1)
	v_mfma_f32_16x16x32_bf16 v[14:17], v[148:151], v[204:207], v[14:17]
	v_mfma_f32_16x16x32_bf16 v[10:13], v[156:159], v[204:207], v[10:13]
	v_mfma_f32_16x16x32_bf16 v[62:65], v[152:155], v[184:187], v[62:65]
	v_mfma_f32_16x16x32_bf16 v[58:61], v[160:163], v[184:187], v[58:61]
	v_mfma_f32_16x16x32_bf16 v[46:49], v[152:155], v[192:195], v[46:49]
	v_mfma_f32_16x16x32_bf16 v[42:45], v[160:163], v[192:195], v[42:45]
	v_mfma_f32_16x16x32_bf16 v[30:33], v[152:155], v[200:203], v[30:33]
	v_mfma_f32_16x16x32_bf16 v[26:29], v[160:163], v[200:203], v[26:29]
	s_waitcnt lgkmcnt(0)
	v_mfma_f32_16x16x32_bf16 v[14:17], v[152:155], v[252:255], v[14:17]
	v_mfma_f32_16x16x32_bf16 v[10:13], v[160:163], v[252:255], v[10:13]
	s_setprio 0
	s_setprio 1
	v_mfma_f32_16x16x32_bf16 v[54:57], v[164:167], v[180:183], v[54:57]
	v_mfma_f32_16x16x32_bf16 v[50:53], v[172:175], v[180:183], v[50:53]
	v_mfma_f32_16x16x32_bf16 v[38:41], v[164:167], v[188:191], v[38:41]
	v_mfma_f32_16x16x32_bf16 v[34:37], v[172:175], v[188:191], v[34:37]
	v_mfma_f32_16x16x32_bf16 v[22:25], v[164:167], v[196:199], v[22:25]
	v_mfma_f32_16x16x32_bf16 v[18:21], v[172:175], v[196:199], v[18:21]
	v_mfma_f32_16x16x32_bf16 v[6:9], v[164:167], v[204:207], v[6:9]
	v_mfma_f32_16x16x32_bf16 v[2:5], v[172:175], v[204:207], v[2:5]
	v_mfma_f32_16x16x32_bf16 v[54:57], v[168:171], v[184:187], v[54:57]
	v_mfma_f32_16x16x32_bf16 v[50:53], v[176:179], v[184:187], v[50:53]
	v_mfma_f32_16x16x32_bf16 v[38:41], v[168:171], v[192:195], v[38:41]
	v_mfma_f32_16x16x32_bf16 v[34:37], v[176:179], v[192:195], v[34:37]
	v_mfma_f32_16x16x32_bf16 v[22:25], v[168:171], v[200:203], v[22:25]
	v_mfma_f32_16x16x32_bf16 v[18:21], v[176:179], v[200:203], v[18:21]
	v_mfma_f32_16x16x32_bf16 v[6:9], v[168:171], v[252:255], v[6:9]
	s_setprio 2
	s_barrier
	v_mfma_f32_16x16x32_bf16 v[2:5], v[176:179], v[252:255], v[2:5]
	s_setprio 0
	ds_read_b128 v[148:151], v145
	ds_read_b128 v[152:155], v145 offset:1024
	ds_read_b128 v[156:159], v145 offset:2048
	ds_read_b128 v[160:163], v145 offset:3072
	ds_read_b128 v[164:167], v146
	ds_read_b128 v[168:171], v146 offset:1024
	ds_read_b128 v[172:175], v146 offset:2048
	ds_read_b128 v[248:251], v146 offset:3072
	ds_read_b128 v[180:183], v144 offset:32768
	ds_read_b128 v[184:187], v144 offset:33792
	ds_read_b128 v[188:191], v144 offset:34816
	ds_read_b128 v[192:195], v144 offset:35840
	ds_read_b128 v[196:199], v144 offset:36864
	ds_read_b128 v[200:203], v144 offset:37888
	ds_read_b128 v[204:207], v144 offset:38912
	ds_read_b128 v[208:211], v144 offset:39936
	s_add_u32 s66, s86, 0x100000
	s_addc_u32 s67, s87, 0
	s_mov_b32 m0, s60
	s_nop 0
	global_load_lds_dwordx4 v136, s[66:67]
	s_nop 0
	s_mov_b32 m0, s61
	s_nop 0
	global_load_lds_dwordx4 v138, s[66:67]
	s_waitcnt vmcnt(8)
	s_waitcnt lgkmcnt(0)
	v_mfma_f32_16x16x32_bf16 v[126:129], v[148:151], v[180:183], v[126:129]
	s_barrier
	s_setprio 1
	s_waitcnt lgkmcnt(7)
	v_mfma_f32_16x16x32_bf16 v[122:125], v[156:159], v[180:183], v[122:125]
	s_waitcnt lgkmcnt(5)
	v_mfma_f32_16x16x32_bf16 v[110:113], v[148:151], v[188:191], v[110:113]
	v_mfma_f32_16x16x32_bf16 v[106:109], v[156:159], v[188:191], v[106:109]
	s_waitcnt lgkmcnt(3)
	v_mfma_f32_16x16x32_bf16 v[94:97], v[148:151], v[196:199], v[94:97]
	v_mfma_f32_16x16x32_bf16 v[90:93], v[156:159], v[196:199], v[90:93]
	s_waitcnt lgkmcnt(1)
	v_mfma_f32_16x16x32_bf16 v[78:81], v[148:151], v[204:207], v[78:81]
	v_mfma_f32_16x16x32_bf16 v[74:77], v[156:159], v[204:207], v[74:77]
	v_mfma_f32_16x16x32_bf16 v[126:129], v[152:155], v[184:187], v[126:129]
	v_mfma_f32_16x16x32_bf16 v[122:125], v[160:163], v[184:187], v[122:125]
	v_mfma_f32_16x16x32_bf16 v[110:113], v[152:155], v[192:195], v[110:113]
	v_mfma_f32_16x16x32_bf16 v[106:109], v[160:163], v[192:195], v[106:109]
	v_mfma_f32_16x16x32_bf16 v[94:97], v[152:155], v[200:203], v[94:97]
	v_mfma_f32_16x16x32_bf16 v[90:93], v[160:163], v[200:203], v[90:93]
	s_waitcnt lgkmcnt(0)
	v_mfma_f32_16x16x32_bf16 v[78:81], v[152:155], v[208:211], v[78:81]
	v_mfma_f32_16x16x32_bf16 v[74:77], v[160:163], v[208:211], v[74:77]
	s_setprio 0
	s_setprio 1
	v_mfma_f32_16x16x32_bf16 v[118:121], v[164:167], v[180:183], v[118:121]
	v_mfma_f32_16x16x32_bf16 v[114:117], v[172:175], v[180:183], v[114:117]
	v_mfma_f32_16x16x32_bf16 v[102:105], v[164:167], v[188:191], v[102:105]
	v_mfma_f32_16x16x32_bf16 v[98:101], v[172:175], v[188:191], v[98:101]
	v_mfma_f32_16x16x32_bf16 v[86:89], v[164:167], v[196:199], v[86:89]
	v_mfma_f32_16x16x32_bf16 v[82:85], v[172:175], v[196:199], v[82:85]
	v_mfma_f32_16x16x32_bf16 v[70:73], v[164:167], v[204:207], v[70:73]
	v_mfma_f32_16x16x32_bf16 v[66:69], v[172:175], v[204:207], v[66:69]
	v_mfma_f32_16x16x32_bf16 v[118:121], v[168:171], v[184:187], v[118:121]
	v_mfma_f32_16x16x32_bf16 v[114:117], v[248:251], v[184:187], v[114:117]
	v_mfma_f32_16x16x32_bf16 v[102:105], v[168:171], v[192:195], v[102:105]
	v_mfma_f32_16x16x32_bf16 v[98:101], v[248:251], v[192:195], v[98:101]
	v_mfma_f32_16x16x32_bf16 v[86:89], v[168:171], v[200:203], v[86:89]
	v_mfma_f32_16x16x32_bf16 v[82:85], v[248:251], v[200:203], v[82:85]
	v_mfma_f32_16x16x32_bf16 v[70:73], v[168:171], v[208:211], v[70:73]
	s_setprio 2
	s_barrier
; __device__ __forceinline__ unsigned cvt_pk_bf16(float lo, float hi) { unsigned r; asm volatile("v_cvt_pk_bf16_f32 %0, %1, %2" : "=v"(r) : "v"(lo), "v"(hi)); return r; }
; __device__ __forceinline__ float silu_f(float x) { return x * sigmoid_f(x); }
; #define PG8_STAGE(bufoff, gbase, voff) do { _Pragma("unroll") for (int _i = 0; _i < 2; ++_i) \
;         asm volatile("s_mov_b32 m0, %2\n\ts_nop 0\n\tglobal_load_lds_dwordx4 %0, %1" :: "v"((voff)[_i]), "s"((const char*)(gbase)), "s"(ldsbase + (unsigned)(bufoff) + ldsw + (unsigned)_i * 8192u) : "memory", "m0"); } while (0)
; #define PG8_LDA(dst, b, h) do { _Pragma("unroll") for (int m = 0; m < 4; ++m) _Pragma("unroll") for (int k = 0; k < 2; ++k) dst[m][k] = *(const PG8_LAS bf16x8*)(lds + PG8_SA(b, h) + aoff + m * 2048 + k * 1024); } while (0)
; #define PG8_WAIT_V(n) asm volatile("s_waitcnt vmcnt(" #n ")" ::: "memory")
; #define PG8_WAIT_L(n) asm volatile("s_waitcnt lgkmcnt(" #n ")" ::: "memory")
; #define PG8_BAR __builtin_amdgcn_s_barrier()
;     __device__ __forceinline__ void operator()(const f32x4 (&acc)[2][2][4][2], const Unit& u, int wr, int wc, int fr, int fq) const {
;         const int row0 = u.pm * BM + wr * 64 + fr, col0 = u.pn * HALF + wc * 32 + 8 * fq;
; #pragma unroll
;         for (int ai = 0; ai < 2; ++ai)
; #pragma unroll
;             for (int m = 0; m < 4; ++m) { bf16_t* rowp = O + (size_t)(row0 + ai * HALF + m * 16) * ldc + col0;
;                 const f32x4 g0 = acc[ai][0][m][0], g1 = acc[ai][0][m][1], u0 = acc[ai][1][m][0], u1 = acc[ai][1][m][1];
;                 f32x4 v0, v1;
; #pragma unroll
;                 for (int j = 0; j < 4; ++j) { v0[j] = silu_f(g0[j]) * u0[j]; v1[j] = silu_f(g1[j]) * u1[j]; }
;                 u32x4 w; w.x = cvt_pk_bf16(v0[0], v0[1]); w.y = cvt_pk_bf16(v0[2], v0[3]); w.z = cvt_pk_bf16(v1[0], v1[1]); w.w = cvt_pk_bf16(v1[2], v1[3]);
;                 *(u32x4*)rowp = w; }
; template <class Epi, class Sched, bool ALIGN_EPI = false, bool SP2 = false>
; __device__ __forceinline__ void gemm_phase(PG8_LAS unsigned char* lds, const Gemm g, const Sched& S, const Epi& E) {
;     ...
;             PG8_LDA(At, 1, 1); PG8_STAGE(PG8_SB(1, 0), b3, voffB); PG8_STAGE(PG8_SB(1, 1), b3 + hstep, voffB); PG8_STAGE(PG8_SA(1, 0), a3, voffA);
;             PG8_WAIT_V(8); PG8_WAIT_L(0); PG8_BAR; PG8_MMA(1, 0, At, B0); PG8_MMA(1, 1, At, B1); PG8_BAR; PG8_SCHED;
	v_mfma_f32_16x16x32_bf16 v[66:69], v[248:251], v[208:211], v[66:69]
	s_setprio 0
	ds_read_b128 v[180:183], v144 offset:49152
	ds_read_b128 v[184:187], v144 offset:50176
	ds_read_b128 v[188:191], v144 offset:51200
	ds_read_b128 v[192:195], v144 offset:52224
	ds_read_b128 v[196:199], v144 offset:53248
	ds_read_b128 v[200:203], v144 offset:54272
	ds_read_b128 v[204:207], v144 offset:55296
	ds_read_b128 v[252:255], v144 offset:56320
	s_add_u32 s66, s84, 0x80
	s_addc_u32 s67, s85, 0
	s_mov_b32 m0, s64
	s_nop 0
	global_load_lds_dwordx4 v137, s[66:67]
	s_nop 0
	s_mov_b32 m0, s65
	s_nop 0
	global_load_lds_dwordx4 v139, s[66:67]
	s_add_u32 s66, s84, 0x100080
	s_addc_u32 s67, s85, 0
	s_mov_b32 m0, s70
	s_nop 0
	global_load_lds_dwordx4 v137, s[66:67]
	s_nop 0
	s_mov_b32 m0, s71
	s_nop 0
	global_load_lds_dwordx4 v139, s[66:67]
	s_nop 0
	s_mov_b32 m0, s68
	s_nop 0
	global_load_lds_dwordx4 v136, s[76:77]
	s_nop 0
	s_mov_b32 m0, s69
	s_nop 0
	global_load_lds_dwordx4 v138, s[76:77]
	s_waitcnt vmcnt(8)
	s_waitcnt lgkmcnt(0)
	v_mfma_f32_16x16x32_bf16 v[62:65], v[148:151], v[180:183], v[62:65]
	s_barrier
	s_setprio 1
	s_waitcnt lgkmcnt(7)
	v_mfma_f32_16x16x32_bf16 v[58:61], v[156:159], v[180:183], v[58:61]
	s_waitcnt lgkmcnt(5)
	v_mfma_f32_16x16x32_bf16 v[46:49], v[148:151], v[188:191], v[46:49]
	v_mfma_f32_16x16x32_bf16 v[42:45], v[156:159], v[188:191], v[42:45]
	s_waitcnt lgkmcnt(3)
	v_mfma_f32_16x16x32_bf16 v[30:33], v[148:151], v[196:199], v[30:33]
	v_mfma_f32_16x16x32_bf16 v[26:29], v[156:159], v[196:199], v[26:29]
	s_waitcnt lgkmcnt(1)
	v_mfma_f32_16x16x32_bf16 v[14:17], v[148:151], v[204:207], v[14:17]
	v_mfma_f32_16x16x32_bf16 v[10:13], v[156:159], v[204:207], v[10:13]
	v_mfma_f32_16x16x32_bf16 v[62:65], v[152:155], v[184:187], v[62:65]
	v_mfma_f32_16x16x32_bf16 v[58:61], v[160:163], v[184:187], v[58:61]
	v_mfma_f32_16x16x32_bf16 v[46:49], v[152:155], v[192:195], v[46:49]
	v_mfma_f32_16x16x32_bf16 v[42:45], v[160:163], v[192:195], v[42:45]
	v_mfma_f32_16x16x32_bf16 v[30:33], v[152:155], v[200:203], v[30:33]
	v_mfma_f32_16x16x32_bf16 v[26:29], v[160:163], v[200:203], v[26:29]
	s_waitcnt lgkmcnt(0)
	v_mfma_f32_16x16x32_bf16 v[14:17], v[152:155], v[252:255], v[14:17]
	v_mfma_f32_16x16x32_bf16 v[10:13], v[160:163], v[252:255], v[10:13]
	s_setprio 0
	s_setprio 1
	v_mfma_f32_16x16x32_bf16 v[54:57], v[164:167], v[180:183], v[54:57]
	v_mfma_f32_16x16x32_bf16 v[50:53], v[172:175], v[180:183], v[50:53]
	v_mfma_f32_16x16x32_bf16 v[38:41], v[164:167], v[188:191], v[38:41]
	v_mfma_f32_16x16x32_bf16 v[34:37], v[172:175], v[188:191], v[34:37]
	v_mfma_f32_16x16x32_bf16 v[22:25], v[164:167], v[196:199], v[22:25]
	v_mfma_f32_16x16x32_bf16 v[18:21], v[172:175], v[196:199], v[18:21]
	v_mfma_f32_16x16x32_bf16 v[6:9], v[164:167], v[204:207], v[6:9]
	v_mfma_f32_16x16x32_bf16 v[2:5], v[172:175], v[204:207], v[2:5]
	v_mfma_f32_16x16x32_bf16 v[54:57], v[168:171], v[184:187], v[54:57]
	v_mfma_f32_16x16x32_bf16 v[50:53], v[248:251], v[184:187], v[50:53]
	v_mfma_f32_16x16x32_bf16 v[38:41], v[168:171], v[192:195], v[38:41]
	v_mfma_f32_16x16x32_bf16 v[34:37], v[248:251], v[192:195], v[34:37]
	v_mfma_f32_16x16x32_bf16 v[22:25], v[168:171], v[200:203], v[22:25]
	v_mfma_f32_16x16x32_bf16 v[18:21], v[248:251], v[200:203], v[18:21]
	v_mfma_f32_16x16x32_bf16 v[6:9], v[168:171], v[252:255], v[6:9]
	s_setprio 2
	s_barrier
	v_mfma_f32_16x16x32_bf16 v[2:5], v[248:251], v[252:255], v[2:5]
	s_setprio 0
	s_add_i32 s96, s96, 2
	s_add_u32 s94, s94, 0x100
	s_addc_u32 s95, s95, 0
	s_cmp_gt_u32 s96, 61
	s_mov_b64 s[66:67], s[62:63]
	s_cbranch_scc0 .LBB0_138
	v_mul_f32_e32 v134, 0xbfb8aa3b, v126
	v_exp_f32_e32 v150, v134
	v_mul_f32_e32 v134, 0xbfb8aa3b, v122
	v_exp_f32_e32 v151, v134
	v_lshl_or_b32 v148, s91, 7, v141
	v_add_f32_e32 v150, 1.0, v150
	v_rcp_f32_e32 v152, v150
	v_add_f32_e32 v150, 1.0, v151
	v_rcp_f32_e32 v153, v150
	v_lshl_add_u32 v147, s82, 8, v140
	v_mul_f32_e32 v126, v126, v152
	v_mul_f32_e32 v118, v126, v118
	v_mul_f32_e32 v126, 0xbfb8aa3b, v127
	v_exp_f32_e32 v126, v126
	v_mul_f32_e32 v152, 0xbfb8aa3b, v123
	v_exp_f32_e32 v152, v152
	v_mul_f32_e32 v122, v122, v153
	v_mul_f32_e32 v122, v122, v114
	v_add_f32_e32 v114, 1.0, v126
	v_rcp_f32_e32 v114, v114
	v_add_f32_e32 v126, 1.0, v152
	v_mul_f32_e32 v152, 0xbfb8aa3b, v128
	v_rcp_f32_e32 v126, v126
	v_exp_f32_e32 v152, v152
	v_mul_f32_e32 v114, v127, v114
	v_mul_f32_e32 v119, v114, v119
	v_mul_f32_e32 v114, v123, v126
	v_add_f32_e32 v123, 1.0, v152
	v_rcp_f32_e32 v123, v123
	v_mul_f32_e32 v126, 0xbfb8aa3b, v124
	v_exp_f32_e32 v126, v126
	v_mul_f32_e32 v127, v114, v115
	v_mul_f32_e32 v114, v128, v123
	v_mul_f32_e32 v115, 0xbfb8aa3b, v129
	v_mul_f32_e32 v123, v114, v120
	v_exp_f32_e32 v115, v115
	v_mul_f32_e32 v120, 0xbfb8aa3b, v125
	v_exp_f32_e32 v120, v120
	v_add_f32_e32 v114, 1.0, v126
	v_rcp_f32_e32 v114, v114
	v_add_f32_e32 v115, 1.0, v115
	v_rcp_f32_e32 v115, v115
	v_add_f32_e32 v120, 1.0, v120
	v_rcp_f32_e32 v120, v120
	v_mul_f32_e32 v114, v124, v114
	v_mul_f32_e32 v124, v114, v116
	v_mul_f32_e32 v114, v129, v115
	v_ashrrev_i32_e32 v149, 31, v148
	v_mov_b64_e32 v[134:135], s[72:73]
	v_mul_f32_e32 v126, v114, v121
	v_mul_f32_e32 v114, v125, v120
	v_mad_i64_i32 v[150:151], s[62:63], v147, s90, v[134:135]
	v_mul_f32_e32 v125, v114, v117
	v_lshlrev_b64 v[114:115], 1, v[148:149]
	v_lshl_add_u64 v[120:121], v[150:151], 0, v[114:115]
	v_cvt_pk_bf16_f32 v116, v118, v119
	v_cvt_pk_bf16_f32 v117, v123, v126
	v_cvt_pk_bf16_f32 v118, v122, v127
	v_cvt_pk_bf16_f32 v119, v124, v125
	global_store_dwordx4 v[120:121], v[116:119], off
	s_and_b64 vcc, exec, s[0:1]
	s_mov_b32 s91, s10
	v_mul_f32_e32 v116, 0xbfb8aa3b, v110
	v_exp_f32_e32 v116, v116
; __device__ __forceinline__ unsigned cvt_pk_bf16(float lo, float hi) { unsigned r; asm volatile("v_cvt_pk_bf16_f32 %0, %1, %2" : "=v"(r) : "v"(lo), "v"(hi)); return r; }
; __device__ __forceinline__ float silu_f(float x) { return x * sigmoid_f(x); }
;     __device__ __forceinline__ void operator()(const f32x4 (&acc)[2][2][4][2], const Unit& u, int wr, int wc, int fr, int fq) const {
;     ...
;             for (int m = 0; m < 4; ++m) { bf16_t* rowp = O + (size_t)(row0 + ai * HALF + m * 16) * ldc + col0;
;                 const f32x4 g0 = acc[ai][0][m][0], g1 = acc[ai][0][m][1], u0 = acc[ai][1][m][0], u1 = acc[ai][1][m][1];
;                 f32x4 v0, v1;
; #pragma unroll
;                 for (int j = 0; j < 4; ++j) { v0[j] = silu_f(g0[j]) * u0[j]; v1[j] = silu_f(g1[j]) * u1[j]; }
;                 u32x4 w; w.x = cvt_pk_bf16(v0[0], v0[1]); w.y = cvt_pk_bf16(v0[2], v0[3]); w.z = cvt_pk_bf16(v1[0], v1[1]); w.w = cvt_pk_bf16(v1[2], v1[3]);
;                 *(u32x4*)rowp = w; }
	v_mul_f32_e32 v117, 0xbfb8aa3b, v106
	v_exp_f32_e32 v117, v117
	v_or_b32_e32 v118, 16, v147
	v_add_f32_e32 v116, 1.0, v116
	v_rcp_f32_e32 v119, v116
	v_add_f32_e32 v116, 1.0, v117
	v_rcp_f32_e32 v120, v116
	v_mad_i64_i32 v[116:117], s[62:63], v118, s90, v[134:135]
	v_mul_f32_e32 v110, v110, v119
	v_mul_f32_e32 v110, v110, v102
	v_mul_f32_e32 v102, v106, v120
	v_mul_f32_e32 v106, 0xbfb8aa3b, v111
	v_exp_f32_e32 v106, v106
	v_mul_f32_e32 v118, 0xbfb8aa3b, v107
	v_mul_f32_e32 v119, v102, v98
	v_exp_f32_e32 v118, v118
	v_add_f32_e32 v98, 1.0, v106
	v_rcp_f32_e32 v98, v98
	v_mul_f32_e32 v106, 0xbfb8aa3b, v112
	v_exp_f32_e32 v106, v106
	v_add_f32_e32 v102, 1.0, v118
	v_mul_f32_e32 v98, v111, v98
	v_rcp_f32_e32 v102, v102
	v_mul_f32_e32 v98, v98, v103
	v_add_f32_e32 v103, 1.0, v106
	v_rcp_f32_e32 v103, v103
	v_mul_f32_e32 v102, v107, v102
	v_mul_f32_e32 v106, 0xbfb8aa3b, v108
	v_mul_f32_e32 v107, v102, v99
	v_mul_f32_e32 v99, v112, v103
	v_exp_f32_e32 v106, v106
	v_mul_f32_e32 v99, v99, v104
	v_mul_f32_e32 v103, 0xbfb8aa3b, v113
	v_mul_f32_e32 v104, 0xbfb8aa3b, v109
	v_exp_f32_e32 v103, v103
	v_exp_f32_e32 v104, v104
	v_add_f32_e32 v102, 1.0, v106
	v_rcp_f32_e32 v102, v102
	v_add_f32_e32 v103, 1.0, v103
	v_add_f32_e32 v104, 1.0, v104
	v_rcp_f32_e32 v103, v103
	v_rcp_f32_e32 v104, v104
	v_mul_f32_e32 v102, v108, v102
	v_mul_f32_e32 v106, v102, v100
	v_mul_f32_e32 v100, v113, v103
	v_mul_f32_e32 v102, v109, v104
	v_mul_f32_e32 v100, v100, v105
	v_mul_f32_e32 v101, v102, v101
	v_lshl_add_u64 v[102:103], v[116:117], 0, v[114:115]
	v_cvt_pk_bf16_f32 v98, v110, v98
	v_cvt_pk_bf16_f32 v99, v99, v100
	v_cvt_pk_bf16_f32 v100, v119, v107
	v_cvt_pk_bf16_f32 v101, v106, v101
	global_store_dwordx4 v[102:103], v[98:101], off
	s_mov_b32 s82, s12
	s_mov_b64 s[66:67], s[14:15]
	v_mul_f32_e32 v98, 0xbfb8aa3b, v94
	v_exp_f32_e32 v98, v98
	v_mul_f32_e32 v99, 0xbfb8aa3b, v90
	v_exp_f32_e32 v99, v99
	v_or_b32_e32 v100, 32, v147
	v_add_f32_e32 v98, 1.0, v98
	v_rcp_f32_e32 v101, v98
	v_add_f32_e32 v98, 1.0, v99
	v_rcp_f32_e32 v102, v98
	v_mad_i64_i32 v[98:99], s[62:63], v100, s90, v[134:135]
	v_mul_f32_e32 v94, v94, v101
	v_mul_f32_e32 v94, v94, v86
	v_mul_f32_e32 v86, v90, v102
	v_mul_f32_e32 v90, 0xbfb8aa3b, v95
	v_exp_f32_e32 v90, v90
	v_mul_f32_e32 v100, 0xbfb8aa3b, v91
	v_mul_f32_e32 v101, v86, v82
	v_exp_f32_e32 v100, v100
	v_add_f32_e32 v82, 1.0, v90
	v_rcp_f32_e32 v82, v82
	v_mul_f32_e32 v90, 0xbfb8aa3b, v96
	v_exp_f32_e32 v90, v90
	v_add_f32_e32 v86, 1.0, v100
	v_mul_f32_e32 v82, v95, v82
	v_rcp_f32_e32 v86, v86
	v_mul_f32_e32 v82, v82, v87
	v_add_f32_e32 v87, 1.0, v90
	v_rcp_f32_e32 v87, v87
	v_mul_f32_e32 v86, v91, v86
	v_mul_f32_e32 v90, 0xbfb8aa3b, v92
	v_mul_f32_e32 v91, v86, v83
	v_mul_f32_e32 v83, v96, v87
	v_exp_f32_e32 v90, v90
	v_mul_f32_e32 v83, v83, v88
	v_mul_f32_e32 v87, 0xbfb8aa3b, v97
	v_mul_f32_e32 v88, 0xbfb8aa3b, v93
	v_exp_f32_e32 v87, v87
	v_exp_f32_e32 v88, v88
	v_add_f32_e32 v86, 1.0, v90
	v_rcp_f32_e32 v86, v86
	v_add_f32_e32 v87, 1.0, v87
	v_add_f32_e32 v88, 1.0, v88
	v_rcp_f32_e32 v87, v87
	v_rcp_f32_e32 v88, v88
	v_mul_f32_e32 v86, v92, v86
	v_mul_f32_e32 v90, v86, v84
	v_mul_f32_e32 v84, v97, v87
	v_mul_f32_e32 v86, v93, v88
	v_mul_f32_e32 v84, v84, v89
	v_mul_f32_e32 v85, v86, v85
	v_lshl_add_u64 v[86:87], v[98:99], 0, v[114:115]
	v_cvt_pk_bf16_f32 v82, v94, v82
	v_cvt_pk_bf16_f32 v83, v83, v84
	v_cvt_pk_bf16_f32 v84, v101, v91
	v_cvt_pk_bf16_f32 v85, v90, v85
	global_store_dwordx4 v[86:87], v[82:85], off
	s_nop 1
	v_mul_f32_e32 v82, 0xbfb8aa3b, v78
	v_exp_f32_e32 v82, v82
	v_mul_f32_e32 v83, 0xbfb8aa3b, v74
	v_exp_f32_e32 v83, v83
	v_or_b32_e32 v84, 48, v147
	v_add_f32_e32 v82, 1.0, v82
	v_rcp_f32_e32 v85, v82
	v_add_f32_e32 v82, 1.0, v83
	v_rcp_f32_e32 v86, v82
	v_mad_i64_i32 v[82:83], s[62:63], v84, s90, v[134:135]
	v_mul_f32_e32 v78, v78, v85
	v_mul_f32_e32 v78, v78, v70
	v_mul_f32_e32 v70, v74, v86
	v_mul_f32_e32 v74, 0xbfb8aa3b, v79
	v_exp_f32_e32 v74, v74
	v_mul_f32_e32 v84, 0xbfb8aa3b, v75
	v_mul_f32_e32 v85, v70, v66
	v_exp_f32_e32 v84, v84
	v_add_f32_e32 v66, 1.0, v74
	v_rcp_f32_e32 v66, v66
	v_mul_f32_e32 v74, 0xbfb8aa3b, v80
	v_exp_f32_e32 v74, v74
	v_add_f32_e32 v70, 1.0, v84
	v_mul_f32_e32 v66, v79, v66
	v_rcp_f32_e32 v70, v70
	v_mul_f32_e32 v66, v66, v71
	v_add_f32_e32 v71, 1.0, v74
	v_rcp_f32_e32 v71, v71
	v_mul_f32_e32 v70, v75, v70
	v_mul_f32_e32 v74, 0xbfb8aa3b, v76
	v_mul_f32_e32 v75, v70, v67
	v_mul_f32_e32 v67, v80, v71
	v_exp_f32_e32 v74, v74
	v_mul_f32_e32 v67, v67, v72
	v_mul_f32_e32 v71, 0xbfb8aa3b, v81
	v_mul_f32_e32 v72, 0xbfb8aa3b, v77
	v_exp_f32_e32 v71, v71
	v_exp_f32_e32 v72, v72
	v_add_f32_e32 v70, 1.0, v74
	v_rcp_f32_e32 v70, v70
	v_add_f32_e32 v71, 1.0, v71
	v_add_f32_e32 v72, 1.0, v72
	v_rcp_f32_e32 v71, v71
	v_rcp_f32_e32 v72, v72
	v_mul_f32_e32 v70, v76, v70
	v_mul_f32_e32 v74, v70, v68
	v_mul_f32_e32 v68, v81, v71
	v_mul_f32_e32 v70, v77, v72
	v_mul_f32_e32 v68, v68, v73
	v_mul_f32_e32 v69, v70, v69
	v_lshl_add_u64 v[70:71], v[82:83], 0, v[114:115]
	v_cvt_pk_bf16_f32 v66, v78, v66
	v_cvt_pk_bf16_f32 v67, v67, v68
	v_cvt_pk_bf16_f32 v68, v85, v75
	v_cvt_pk_bf16_f32 v69, v74, v69
	global_store_dwordx4 v[70:71], v[66:69], off
	s_nop 1
	v_mul_f32_e32 v66, 0xbfb8aa3b, v62
	v_exp_f32_e32 v66, v66
	v_mul_f32_e32 v67, 0xbfb8aa3b, v58
	v_exp_f32_e32 v67, v67
	v_add_u32_e32 v68, 0x80, v147
	v_add_f32_e32 v66, 1.0, v66
	v_rcp_f32_e32 v69, v66
	v_add_f32_e32 v66, 1.0, v67
	v_rcp_f32_e32 v70, v66
	v_mad_i64_i32 v[66:67], s[62:63], v68, s90, v[134:135]
	v_mul_f32_e32 v62, v62, v69
	v_mul_f32_e32 v62, v62, v54
	v_mul_f32_e32 v54, v58, v70
	v_mul_f32_e32 v58, 0xbfb8aa3b, v63
	v_exp_f32_e32 v58, v58
; __device__ __forceinline__ unsigned cvt_pk_bf16(float lo, float hi) { unsigned r; asm volatile("v_cvt_pk_bf16_f32 %0, %1, %2" : "=v"(r) : "v"(lo), "v"(hi)); return r; }
; __device__ __forceinline__ float silu_f(float x) { return x * sigmoid_f(x); }
; #define PG8_WAIT_V(n) asm volatile("s_waitcnt vmcnt(" #n ")" ::: "memory")
; #define PG8_BAR __builtin_amdgcn_s_barrier()
;     __device__ __forceinline__ void operator()(const f32x4 (&acc)[2][2][4][2], const Unit& u, int wr, int wc, int fr, int fq) const {
;     ...
;             for (int m = 0; m < 4; ++m) { bf16_t* rowp = O + (size_t)(row0 + ai * HALF + m * 16) * ldc + col0;
;                 const f32x4 g0 = acc[ai][0][m][0], g1 = acc[ai][0][m][1], u0 = acc[ai][1][m][0], u1 = acc[ai][1][m][1];
;                 f32x4 v0, v1;
; #pragma unroll
;                 for (int j = 0; j < 4; ++j) { v0[j] = silu_f(g0[j]) * u0[j]; v1[j] = silu_f(g1[j]) * u1[j]; }
;                 u32x4 w; w.x = cvt_pk_bf16(v0[0], v0[1]); w.y = cvt_pk_bf16(v0[2], v0[3]); w.z = cvt_pk_bf16(v1[0], v1[1]); w.w = cvt_pk_bf16(v1[2], v1[3]);
;                 *(u32x4*)rowp = w; }
; template <class Epi, class Sched, bool ALIGN_EPI = false, bool SP2 = false>
; __device__ __forceinline__ void gemm_phase(PG8_LAS unsigned char* lds, const Gemm g, const Sched& S, const Epi& E) {
;     ...
;     PG8_WAIT_V(0);
;     if constexpr (!ALIGN_EPI) { if (wr == 0) PG8_BAR; }
;     PG8_BAR;
	v_mul_f32_e32 v68, 0xbfb8aa3b, v59
	v_mul_f32_e32 v69, v54, v50
	v_exp_f32_e32 v68, v68
	v_add_f32_e32 v50, 1.0, v58
	v_rcp_f32_e32 v50, v50
	v_mul_f32_e32 v58, 0xbfb8aa3b, v64
	v_exp_f32_e32 v58, v58
	v_add_f32_e32 v54, 1.0, v68
	v_mul_f32_e32 v50, v63, v50
	v_rcp_f32_e32 v54, v54
	v_mul_f32_e32 v50, v50, v55
	v_add_f32_e32 v55, 1.0, v58
	v_rcp_f32_e32 v55, v55
	v_mul_f32_e32 v54, v59, v54
	v_mul_f32_e32 v58, 0xbfb8aa3b, v60
	v_mul_f32_e32 v59, v54, v51
	v_mul_f32_e32 v51, v64, v55
	v_exp_f32_e32 v58, v58
	v_mul_f32_e32 v51, v51, v56
	v_mul_f32_e32 v55, 0xbfb8aa3b, v65
	v_mul_f32_e32 v56, 0xbfb8aa3b, v61
	v_exp_f32_e32 v55, v55
	v_exp_f32_e32 v56, v56
	v_add_f32_e32 v54, 1.0, v58
	v_rcp_f32_e32 v54, v54
	v_add_f32_e32 v55, 1.0, v55
	v_add_f32_e32 v56, 1.0, v56
	v_rcp_f32_e32 v55, v55
	v_rcp_f32_e32 v56, v56
	v_mul_f32_e32 v54, v60, v54
	v_mul_f32_e32 v58, v54, v52
	v_mul_f32_e32 v52, v65, v55
	v_mul_f32_e32 v54, v61, v56
	v_mul_f32_e32 v52, v52, v57
	v_mul_f32_e32 v53, v54, v53
	v_lshl_add_u64 v[54:55], v[66:67], 0, v[114:115]
	v_cvt_pk_bf16_f32 v50, v62, v50
	v_cvt_pk_bf16_f32 v51, v51, v52
	v_cvt_pk_bf16_f32 v52, v69, v59
	v_cvt_pk_bf16_f32 v53, v58, v53
	global_store_dwordx4 v[54:55], v[50:53], off
	s_nop 1
	v_mul_f32_e32 v50, 0xbfb8aa3b, v46
	v_exp_f32_e32 v50, v50
	v_mul_f32_e32 v51, 0xbfb8aa3b, v42
	v_exp_f32_e32 v51, v51
	v_add_u32_e32 v52, 0x90, v147
	v_add_f32_e32 v50, 1.0, v50
	v_rcp_f32_e32 v53, v50
	v_add_f32_e32 v50, 1.0, v51
	v_rcp_f32_e32 v54, v50
	v_mad_i64_i32 v[50:51], s[62:63], v52, s90, v[134:135]
	v_mul_f32_e32 v46, v46, v53
	v_mul_f32_e32 v46, v46, v38
	v_mul_f32_e32 v38, v42, v54
	v_mul_f32_e32 v42, 0xbfb8aa3b, v47
	v_exp_f32_e32 v42, v42
	v_mul_f32_e32 v52, 0xbfb8aa3b, v43
	v_mul_f32_e32 v53, v38, v34
	v_exp_f32_e32 v52, v52
	v_add_f32_e32 v34, 1.0, v42
	v_rcp_f32_e32 v34, v34
	v_mul_f32_e32 v42, 0xbfb8aa3b, v48
	v_exp_f32_e32 v42, v42
	v_add_f32_e32 v38, 1.0, v52
	v_mul_f32_e32 v34, v47, v34
	v_rcp_f32_e32 v38, v38
	v_mul_f32_e32 v34, v34, v39
	v_add_f32_e32 v39, 1.0, v42
	v_rcp_f32_e32 v39, v39
	v_mul_f32_e32 v38, v43, v38
	v_mul_f32_e32 v42, 0xbfb8aa3b, v44
	v_mul_f32_e32 v43, v38, v35
	v_mul_f32_e32 v35, v48, v39
	v_exp_f32_e32 v42, v42
	v_mul_f32_e32 v35, v35, v40
	v_mul_f32_e32 v39, 0xbfb8aa3b, v49
	v_mul_f32_e32 v40, 0xbfb8aa3b, v45
	v_exp_f32_e32 v39, v39
	v_exp_f32_e32 v40, v40
	v_add_f32_e32 v38, 1.0, v42
	v_rcp_f32_e32 v38, v38
	v_add_f32_e32 v39, 1.0, v39
	v_add_f32_e32 v40, 1.0, v40
	v_rcp_f32_e32 v39, v39
	v_rcp_f32_e32 v40, v40
	v_mul_f32_e32 v38, v44, v38
	v_mul_f32_e32 v42, v38, v36
	v_mul_f32_e32 v36, v49, v39
	v_mul_f32_e32 v38, v45, v40
	v_mul_f32_e32 v36, v36, v41
	v_mul_f32_e32 v37, v38, v37
	v_lshl_add_u64 v[38:39], v[50:51], 0, v[114:115]
	v_cvt_pk_bf16_f32 v34, v46, v34
	v_cvt_pk_bf16_f32 v35, v35, v36
	v_cvt_pk_bf16_f32 v36, v53, v43
	v_cvt_pk_bf16_f32 v37, v42, v37
	global_store_dwordx4 v[38:39], v[34:37], off
	s_nop 1
	v_mul_f32_e32 v34, 0xbfb8aa3b, v30
	v_exp_f32_e32 v34, v34
	v_mul_f32_e32 v35, 0xbfb8aa3b, v26
	v_exp_f32_e32 v35, v35
	v_add_u32_e32 v36, 0xa0, v147
	v_add_f32_e32 v34, 1.0, v34
	v_rcp_f32_e32 v37, v34
	v_add_f32_e32 v34, 1.0, v35
	v_rcp_f32_e32 v38, v34
	v_mad_i64_i32 v[34:35], s[62:63], v36, s90, v[134:135]
	v_mul_f32_e32 v30, v30, v37
	v_mul_f32_e32 v30, v30, v22
	v_mul_f32_e32 v22, v26, v38
	v_mul_f32_e32 v26, 0xbfb8aa3b, v31
	v_exp_f32_e32 v26, v26
	v_mul_f32_e32 v36, 0xbfb8aa3b, v27
	v_mul_f32_e32 v37, v22, v18
	v_exp_f32_e32 v36, v36
	v_add_f32_e32 v18, 1.0, v26
	v_rcp_f32_e32 v18, v18
	v_mul_f32_e32 v26, 0xbfb8aa3b, v32
	v_exp_f32_e32 v26, v26
	v_add_f32_e32 v22, 1.0, v36
	v_mul_f32_e32 v18, v31, v18
	v_rcp_f32_e32 v22, v22
	v_mul_f32_e32 v18, v18, v23
	v_add_f32_e32 v23, 1.0, v26
	v_rcp_f32_e32 v23, v23
	v_mul_f32_e32 v22, v27, v22
	v_mul_f32_e32 v26, 0xbfb8aa3b, v28
	v_mul_f32_e32 v27, v22, v19
	v_mul_f32_e32 v19, v32, v23
	v_exp_f32_e32 v26, v26
	v_mul_f32_e32 v19, v19, v24
	v_mul_f32_e32 v23, 0xbfb8aa3b, v33
	v_mul_f32_e32 v24, 0xbfb8aa3b, v29
	v_exp_f32_e32 v23, v23
	v_exp_f32_e32 v24, v24
	v_add_f32_e32 v22, 1.0, v26
	v_rcp_f32_e32 v22, v22
	v_add_f32_e32 v23, 1.0, v23
	v_add_f32_e32 v24, 1.0, v24
	v_rcp_f32_e32 v23, v23
	v_rcp_f32_e32 v24, v24
	v_mul_f32_e32 v22, v28, v22
	v_mul_f32_e32 v26, v22, v20
	v_mul_f32_e32 v20, v33, v23
	v_mul_f32_e32 v22, v29, v24
	v_mul_f32_e32 v20, v20, v25
	v_mul_f32_e32 v21, v22, v21
	v_lshl_add_u64 v[22:23], v[34:35], 0, v[114:115]
	v_cvt_pk_bf16_f32 v18, v30, v18
	v_cvt_pk_bf16_f32 v19, v19, v20
	v_cvt_pk_bf16_f32 v20, v37, v27
	v_cvt_pk_bf16_f32 v21, v26, v21
	global_store_dwordx4 v[22:23], v[18:21], off
	s_nop 1
	v_mul_f32_e32 v18, 0xbfb8aa3b, v14
	v_exp_f32_e32 v18, v18
	v_mul_f32_e32 v19, 0xbfb8aa3b, v10
	v_exp_f32_e32 v19, v19
	v_add_u32_e32 v20, 0xb0, v147
	v_add_f32_e32 v18, 1.0, v18
	v_rcp_f32_e32 v21, v18
	v_add_f32_e32 v18, 1.0, v19
	v_rcp_f32_e32 v22, v18
	v_mad_i64_i32 v[18:19], s[62:63], v20, s90, v[134:135]
	v_mul_f32_e32 v14, v14, v21
	v_mul_f32_e32 v14, v14, v6
	v_mul_f32_e32 v6, v10, v22
	v_mul_f32_e32 v10, 0xbfb8aa3b, v15
	v_exp_f32_e32 v10, v10
	v_mul_f32_e32 v20, 0xbfb8aa3b, v11
	v_mul_f32_e32 v21, v6, v2
	v_exp_f32_e32 v20, v20
	v_add_f32_e32 v2, 1.0, v10
	v_rcp_f32_e32 v2, v2
	v_mul_f32_e32 v10, 0xbfb8aa3b, v16
	v_exp_f32_e32 v10, v10
	v_add_f32_e32 v6, 1.0, v20
	v_mul_f32_e32 v2, v15, v2
	v_rcp_f32_e32 v6, v6
	v_mul_f32_e32 v2, v2, v7
	v_add_f32_e32 v7, 1.0, v10
	v_rcp_f32_e32 v7, v7
	v_mul_f32_e32 v6, v11, v6
	v_mul_f32_e32 v10, 0xbfb8aa3b, v12
	v_mul_f32_e32 v11, v6, v3
	v_mul_f32_e32 v3, v16, v7
	v_exp_f32_e32 v10, v10
	v_mul_f32_e32 v3, v3, v8
	v_mul_f32_e32 v7, 0xbfb8aa3b, v17
	v_mul_f32_e32 v8, 0xbfb8aa3b, v13
	v_exp_f32_e32 v7, v7
	v_exp_f32_e32 v8, v8
	v_add_f32_e32 v6, 1.0, v10
	v_rcp_f32_e32 v6, v6
	v_add_f32_e32 v7, 1.0, v7
	v_add_f32_e32 v8, 1.0, v8
	v_rcp_f32_e32 v7, v7
	v_rcp_f32_e32 v8, v8
	v_mul_f32_e32 v6, v12, v6
	v_mul_f32_e32 v10, v6, v4
	v_mul_f32_e32 v4, v17, v7
	v_mul_f32_e32 v6, v13, v8
	v_mul_f32_e32 v4, v4, v9
	v_mul_f32_e32 v5, v6, v5
	v_lshl_add_u64 v[6:7], v[18:19], 0, v[114:115]
	s_mov_b64 s[62:63], s[16:17]
	v_cvt_pk_bf16_f32 v2, v14, v2
	v_cvt_pk_bf16_f32 v3, v3, v4
	v_cvt_pk_bf16_f32 v4, v21, v11
	v_cvt_pk_bf16_f32 v5, v10, v5
	global_store_dwordx4 v[6:7], v[2:5], off
	s_cbranch_vccz .LBB0_135
	s_waitcnt vmcnt(0)
	s_cmpk_gt_u32 s3, 0xff
	s_cbranch_scc1 .LBB0_142
	s_barrier

; #define PG8_STAGE(bufoff, gbase, voff) do { _Pragma("unroll") for (int _i = 0; _i < 2; ++_i) \
;         asm volatile("s_mov_b32 m0, %2\n\ts_nop 0\n\tglobal_load_lds_dwordx4 %0, %1" :: "v"((voff)[_i]), "s"((const char*)(gbase)), "s"(ldsbase + (unsigned)(bufoff) + ldsw + (unsigned)_i * 8192u) : "memory", "m0"); } while (0)
; #define PG8_LDA(dst, b, h) do { _Pragma("unroll") for (int m = 0; m < 4; ++m) _Pragma("unroll") for (int k = 0; k < 2; ++k) dst[m][k] = *(const PG8_LAS bf16x8*)(lds + PG8_SA(b, h) + aoff + m * 2048 + k * 1024); } while (0)
; #define PG8_LDB(dst, b, h) do { _Pragma("unroll") for (int n = 0; n < 2; ++n) _Pragma("unroll") for (int k = 0; k < 2; ++k) dst[n][k] = *(const PG8_LAS bf16x8*)(lds + PG8_SB(b, h) + boff + n * 2048 + k * 1024); } while (0)
; #define PG8_MMA(ai, bj, At, Bt) do { __builtin_amdgcn_s_setprio(1); _Pragma("unroll") for (int m = 0; m < 4; ++m) _Pragma("unroll") for (int n = 0; n < 2; ++n) _Pragma("unroll") for (int k = 0; k < 2; ++k) \
;         acc[ai][bj][m][n] = __builtin_amdgcn_mfma_f32_16x16x32_bf16(Bt[n][k], At[m][k], acc[ai][bj][m][n], 0, 0, 0); __builtin_amdgcn_s_setprio(0); } while (0)
; template <class Epi, class Sched, bool ALIGN_EPI = false, bool SP2 = false>
; __device__ __forceinline__ void gemm_phase(PG8_LAS unsigned char* lds, const Gemm g, const Sched& S, const Epi& E) {
;     ...
;             const bool last = (t == nt - 2);
;             const char* a1 = cA + (size_t)(t + 1) * kstep;
;             const char* a2 = last ? nA : cA + (size_t)(t + 2) * kstep; const char* b2 = last ? nB : cB + (size_t)(t + 2) * kstep;
;             const char* a3 = a2 + kstep; const char* b3 = b2 + kstep;
;             if (last && has_next) S.a_ready(nxt);
;             if constexpr (epi_has_mid<Epi>::value) { if (t == Epi::MID_T) E.mid(acc, cur, wr, wc, fr, fq); }
;             if constexpr (SP2) {
;             PG8_LDB(B0, 0, 0); PG8_LDB(B1, 0, 1); PG8_SCHED; PG8_LDA(At, 0, 0); PG8_STAGE(PG8_SA(1, 1), a1 + hstep, voffA);
;             PG8_WAIT_V(8); PG8_WAIT_L(0); PG8_BAR; PG8_MMA(0, 0, At, B0); PG8_MMA(0, 1, At, B1); PG8_BAR; PG8_SCHED;
;             PG8_LDA(At, 0, 1); PG8_STAGE(PG8_SB(0, 0), b2, voffB); PG8_STAGE(PG8_SB(0, 1), b2 + hstep, voffB); PG8_STAGE(PG8_SA(0, 0), a2, voffA);
;             PG8_WAIT_V(8); PG8_WAIT_L(0); PG8_BAR; PG8_MMA(1, 0, At, B0); PG8_MMA(1, 1, At, B1); PG8_BAR; PG8_SCHED;
.LBB0_234:
	ds_read_b128 v[134:137], v145
	ds_read_b128 v[152:155], v145 offset:1024
	ds_read_b128 v[156:159], v145 offset:2048
	ds_read_b128 v[160:163], v145 offset:3072
	ds_read_b128 v[164:167], v146
	ds_read_b128 v[168:171], v146 offset:1024
	ds_read_b128 v[172:175], v146 offset:2048
	ds_read_b128 v[176:179], v146 offset:3072
	s_cmpk_eq_i32 s57, 0xa8
	s_cselect_b32 s76, s4, s53
	s_cselect_b32 s77, s5, s54
	s_cselect_b32 s66, s46, s55
	s_cselect_b32 s67, s47, s56
	s_add_u32 s62, s76, 0x80
	s_addc_u32 s63, s77, 0
	ds_read_b128 v[180:183], v147
	ds_read_b128 v[184:187], v147 offset:1024
	ds_read_b128 v[188:191], v147 offset:2048
	ds_read_b128 v[192:195], v147 offset:3072
	ds_read_b128 v[196:199], v147 offset:4096
	ds_read_b128 v[200:203], v147 offset:5120
	ds_read_b128 v[204:207], v147 offset:6144
	ds_read_b128 v[208:211], v147 offset:7168
	s_mov_b32 m0, s94
	s_nop 0
	global_load_lds_dwordx4 v1, s[50:51]
	s_nop 0
	s_mov_b32 m0, s95
	s_nop 0
	global_load_lds_dwordx4 v141, s[50:51]
	s_waitcnt vmcnt(8)
	s_waitcnt lgkmcnt(0)
	v_mfma_f32_16x16x32_bf16 v[126:129], v[134:137], v[180:183], v[126:129]
	s_barrier
	s_setprio 1
	s_waitcnt lgkmcnt(7)
	v_mfma_f32_16x16x32_bf16 v[122:125], v[156:159], v[180:183], v[122:125]
	s_waitcnt lgkmcnt(5)
	v_mfma_f32_16x16x32_bf16 v[110:113], v[134:137], v[188:191], v[110:113]
	v_mfma_f32_16x16x32_bf16 v[106:109], v[156:159], v[188:191], v[106:109]
	s_waitcnt lgkmcnt(3)
	v_mfma_f32_16x16x32_bf16 v[94:97], v[134:137], v[196:199], v[94:97]
	v_mfma_f32_16x16x32_bf16 v[90:93], v[156:159], v[196:199], v[90:93]
	s_waitcnt lgkmcnt(1)
	v_mfma_f32_16x16x32_bf16 v[78:81], v[134:137], v[204:207], v[78:81]
	v_mfma_f32_16x16x32_bf16 v[74:77], v[156:159], v[204:207], v[74:77]
	v_mfma_f32_16x16x32_bf16 v[126:129], v[152:155], v[184:187], v[126:129]
	v_mfma_f32_16x16x32_bf16 v[122:125], v[160:163], v[184:187], v[122:125]
	v_mfma_f32_16x16x32_bf16 v[110:113], v[152:155], v[192:195], v[110:113]
	v_mfma_f32_16x16x32_bf16 v[106:109], v[160:163], v[192:195], v[106:109]
	v_mfma_f32_16x16x32_bf16 v[94:97], v[152:155], v[200:203], v[94:97]
	v_mfma_f32_16x16x32_bf16 v[90:93], v[160:163], v[200:203], v[90:93]
	s_waitcnt lgkmcnt(0)
	v_mfma_f32_16x16x32_bf16 v[78:81], v[152:155], v[208:211], v[78:81]
	v_mfma_f32_16x16x32_bf16 v[74:77], v[160:163], v[208:211], v[74:77]
	s_setprio 0
	s_setprio 1
	v_mfma_f32_16x16x32_bf16 v[118:121], v[164:167], v[180:183], v[118:121]
	v_mfma_f32_16x16x32_bf16 v[114:117], v[172:175], v[180:183], v[114:117]
	v_mfma_f32_16x16x32_bf16 v[102:105], v[164:167], v[188:191], v[102:105]
	v_mfma_f32_16x16x32_bf16 v[98:101], v[172:175], v[188:191], v[98:101]
	v_mfma_f32_16x16x32_bf16 v[86:89], v[164:167], v[196:199], v[86:89]
	v_mfma_f32_16x16x32_bf16 v[82:85], v[172:175], v[196:199], v[82:85]
	v_mfma_f32_16x16x32_bf16 v[70:73], v[164:167], v[204:207], v[70:73]
	v_mfma_f32_16x16x32_bf16 v[66:69], v[172:175], v[204:207], v[66:69]
	v_mfma_f32_16x16x32_bf16 v[118:121], v[168:171], v[184:187], v[118:121]
	v_mfma_f32_16x16x32_bf16 v[114:117], v[176:179], v[184:187], v[114:117]
	v_mfma_f32_16x16x32_bf16 v[102:105], v[168:171], v[192:195], v[102:105]
	v_mfma_f32_16x16x32_bf16 v[98:101], v[176:179], v[192:195], v[98:101]
	v_mfma_f32_16x16x32_bf16 v[86:89], v[168:171], v[200:203], v[86:89]
	v_mfma_f32_16x16x32_bf16 v[82:85], v[176:179], v[200:203], v[82:85]
	v_mfma_f32_16x16x32_bf16 v[70:73], v[168:171], v[208:211], v[70:73]
	s_setprio 2
	s_barrier
	v_mfma_f32_16x16x32_bf16 v[66:69], v[176:179], v[208:211], v[66:69]
	s_setprio 0
	ds_read_b128 v[180:183], v147 offset:16384
	ds_read_b128 v[184:187], v147 offset:17408
	ds_read_b128 v[188:191], v147 offset:18432
	ds_read_b128 v[192:195], v147 offset:19456
	ds_read_b128 v[196:199], v147 offset:20480
	ds_read_b128 v[200:203], v147 offset:21504
	ds_read_b128 v[204:207], v147 offset:22528
	ds_read_b128 v[252:255], v147 offset:23552
	s_mov_b32 m0, s64
	s_nop 0
	global_load_lds_dwordx4 v140, s[66:67]
	s_add_u32 s58, s66, 0x2b0000
	s_mov_b32 m0, s65
	s_nop 0
	global_load_lds_dwordx4 v142, s[66:67]
	s_addc_u32 s59, s67, 0
	s_mov_b32 m0, s82
	s_nop 0
	global_load_lds_dwordx4 v140, s[58:59]
	s_nop 0
	s_mov_b32 m0, s83
	s_nop 0
	global_load_lds_dwordx4 v142, s[58:59]
	s_nop 0
	s_mov_b32 m0, s35
	s_nop 0
	global_load_lds_dwordx4 v1, s[76:77]
	s_nop 0
	s_mov_b32 m0, s84
	s_nop 0
	global_load_lds_dwordx4 v141, s[76:77]
	s_waitcnt vmcnt(8)
	s_waitcnt lgkmcnt(0)
	v_mfma_f32_16x16x32_bf16 v[62:65], v[134:137], v[180:183], v[62:65]
	s_barrier
	s_setprio 1
	s_waitcnt lgkmcnt(7)
	v_mfma_f32_16x16x32_bf16 v[58:61], v[156:159], v[180:183], v[58:61]
	s_waitcnt lgkmcnt(5)
	v_mfma_f32_16x16x32_bf16 v[46:49], v[134:137], v[188:191], v[46:49]
	v_mfma_f32_16x16x32_bf16 v[42:45], v[156:159], v[188:191], v[42:45]
	s_waitcnt lgkmcnt(3)
	v_mfma_f32_16x16x32_bf16 v[30:33], v[134:137], v[196:199], v[30:33]
	v_mfma_f32_16x16x32_bf16 v[26:29], v[156:159], v[196:199], v[26:29]
	s_waitcnt lgkmcnt(1)
	v_mfma_f32_16x16x32_bf16 v[14:17], v[134:137], v[204:207], v[14:17]
	v_mfma_f32_16x16x32_bf16 v[10:13], v[156:159], v[204:207], v[10:13]
	v_mfma_f32_16x16x32_bf16 v[62:65], v[152:155], v[184:187], v[62:65]
	v_mfma_f32_16x16x32_bf16 v[58:61], v[160:163], v[184:187], v[58:61]
	v_mfma_f32_16x16x32_bf16 v[46:49], v[152:155], v[192:195], v[46:49]
	v_mfma_f32_16x16x32_bf16 v[42:45], v[160:163], v[192:195], v[42:45]
	v_mfma_f32_16x16x32_bf16 v[30:33], v[152:155], v[200:203], v[30:33]
	v_mfma_f32_16x16x32_bf16 v[26:29], v[160:163], v[200:203], v[26:29]
	s_waitcnt lgkmcnt(0)
	v_mfma_f32_16x16x32_bf16 v[14:17], v[152:155], v[252:255], v[14:17]
	v_mfma_f32_16x16x32_bf16 v[10:13], v[160:163], v[252:255], v[10:13]
	s_setprio 0
	s_setprio 1
	v_mfma_f32_16x16x32_bf16 v[54:57], v[164:167], v[180:183], v[54:57]
	v_mfma_f32_16x16x32_bf16 v[50:53], v[172:175], v[180:183], v[50:53]
	v_mfma_f32_16x16x32_bf16 v[38:41], v[164:167], v[188:191], v[38:41]
	v_mfma_f32_16x16x32_bf16 v[34:37], v[172:175], v[188:191], v[34:37]
	v_mfma_f32_16x16x32_bf16 v[22:25], v[164:167], v[196:199], v[22:25]
	v_mfma_f32_16x16x32_bf16 v[18:21], v[172:175], v[196:199], v[18:21]
	v_mfma_f32_16x16x32_bf16 v[6:9], v[164:167], v[204:207], v[6:9]
	v_mfma_f32_16x16x32_bf16 v[2:5], v[172:175], v[204:207], v[2:5]
	v_mfma_f32_16x16x32_bf16 v[54:57], v[168:171], v[184:187], v[54:57]
	v_mfma_f32_16x16x32_bf16 v[50:53], v[176:179], v[184:187], v[50:53]
	v_mfma_f32_16x16x32_bf16 v[38:41], v[168:171], v[192:195], v[38:41]
	v_mfma_f32_16x16x32_bf16 v[34:37], v[176:179], v[192:195], v[34:37]
	v_mfma_f32_16x16x32_bf16 v[22:25], v[168:171], v[200:203], v[22:25]
	v_mfma_f32_16x16x32_bf16 v[18:21], v[176:179], v[200:203], v[18:21]
	v_mfma_f32_16x16x32_bf16 v[6:9], v[168:171], v[252:255], v[6:9]
	s_setprio 2
	s_barrier
; #define PG8_STAGE(bufoff, gbase, voff) do { _Pragma("unroll") for (int _i = 0; _i < 2; ++_i) \
;         asm volatile("s_mov_b32 m0, %2\n\ts_nop 0\n\tglobal_load_lds_dwordx4 %0, %1" :: "v"((voff)[_i]), "s"((const char*)(gbase)), "s"(ldsbase + (unsigned)(bufoff) + ldsw + (unsigned)_i * 8192u) : "memory", "m0"); } while (0)
; #define PG8_LDA(dst, b, h) do { _Pragma("unroll") for (int m = 0; m < 4; ++m) _Pragma("unroll") for (int k = 0; k < 2; ++k) dst[m][k] = *(const PG8_LAS bf16x8*)(lds + PG8_SA(b, h) + aoff + m * 2048 + k * 1024); } while (0)
; #define PG8_LDB(dst, b, h) do { _Pragma("unroll") for (int n = 0; n < 2; ++n) _Pragma("unroll") for (int k = 0; k < 2; ++k) dst[n][k] = *(const PG8_LAS bf16x8*)(lds + PG8_SB(b, h) + boff + n * 2048 + k * 1024); } while (0)
; #define PG8_MMA(ai, bj, At, Bt) do { __builtin_amdgcn_s_setprio(1); _Pragma("unroll") for (int m = 0; m < 4; ++m) _Pragma("unroll") for (int n = 0; n < 2; ++n) _Pragma("unroll") for (int k = 0; k < 2; ++k) \
;         acc[ai][bj][m][n] = __builtin_amdgcn_mfma_f32_16x16x32_bf16(Bt[n][k], At[m][k], acc[ai][bj][m][n], 0, 0, 0); __builtin_amdgcn_s_setprio(0); } while (0)
; #define PG8_WAIT_V(n) asm volatile("s_waitcnt vmcnt(" #n ")" ::: "memory")
; #define PG8_WAIT_L(n) asm volatile("s_waitcnt lgkmcnt(" #n ")" ::: "memory")
; #define PG8_BAR __builtin_amdgcn_s_barrier()
; #define PG8_SCHED __builtin_amdgcn_sched_barrier(0)
; template <class Epi, class Sched, bool ALIGN_EPI = false, bool SP2 = false>
; __device__ __forceinline__ void gemm_phase(PG8_LAS unsigned char* lds, const Gemm g, const Sched& S, const Epi& E) {
;     ...
;             PG8_LDB(B0, 1, 0); PG8_LDB(B1, 1, 1); PG8_SCHED; PG8_LDA(At, 1, 0); PG8_STAGE(PG8_SA(0, 1), a2 + hstep, voffA);
;             PG8_WAIT_V(8); PG8_WAIT_L(0); PG8_BAR; PG8_MMA(0, 0, At, B0); PG8_MMA(0, 1, At, B1); PG8_BAR; PG8_SCHED;
	v_mfma_f32_16x16x32_bf16 v[2:5], v[176:179], v[252:255], v[2:5]
	s_setprio 0
	ds_read_b128 v[134:137], v148
	ds_read_b128 v[152:155], v148 offset:1024
	ds_read_b128 v[156:159], v148 offset:2048
	ds_read_b128 v[160:163], v148 offset:3072
	ds_read_b128 v[164:167], v149
	ds_read_b128 v[168:171], v149 offset:1024
	ds_read_b128 v[172:175], v149 offset:2048
	ds_read_b128 v[248:251], v149 offset:3072
	ds_read_b128 v[180:183], v147 offset:32768
	ds_read_b128 v[184:187], v147 offset:33792
	ds_read_b128 v[188:191], v147 offset:34816
	ds_read_b128 v[192:195], v147 offset:35840
	ds_read_b128 v[196:199], v147 offset:36864
	ds_read_b128 v[200:203], v147 offset:37888
	ds_read_b128 v[204:207], v147 offset:38912
	ds_read_b128 v[208:211], v147 offset:39936
	s_add_u32 s58, s76, 0x2b0000
	s_addc_u32 s59, s77, 0
	s_mov_b32 m0, s85
	s_nop 0
	global_load_lds_dwordx4 v1, s[58:59]
	s_nop 0
	s_mov_b32 m0, s86
	s_nop 0
	global_load_lds_dwordx4 v141, s[58:59]
	s_waitcnt vmcnt(8)
	s_waitcnt lgkmcnt(0)
	v_mfma_f32_16x16x32_bf16 v[126:129], v[134:137], v[180:183], v[126:129]
	s_barrier
	s_setprio 1
	s_waitcnt lgkmcnt(7)
	v_mfma_f32_16x16x32_bf16 v[122:125], v[156:159], v[180:183], v[122:125]
	s_waitcnt lgkmcnt(5)
	v_mfma_f32_16x16x32_bf16 v[110:113], v[134:137], v[188:191], v[110:113]
	v_mfma_f32_16x16x32_bf16 v[106:109], v[156:159], v[188:191], v[106:109]
	s_waitcnt lgkmcnt(3)
	v_mfma_f32_16x16x32_bf16 v[94:97], v[134:137], v[196:199], v[94:97]
	v_mfma_f32_16x16x32_bf16 v[90:93], v[156:159], v[196:199], v[90:93]
	s_waitcnt lgkmcnt(1)
	v_mfma_f32_16x16x32_bf16 v[78:81], v[134:137], v[204:207], v[78:81]
	v_mfma_f32_16x16x32_bf16 v[74:77], v[156:159], v[204:207], v[74:77]
	v_mfma_f32_16x16x32_bf16 v[126:129], v[152:155], v[184:187], v[126:129]
	v_mfma_f32_16x16x32_bf16 v[122:125], v[160:163], v[184:187], v[122:125]
	v_mfma_f32_16x16x32_bf16 v[110:113], v[152:155], v[192:195], v[110:113]
	v_mfma_f32_16x16x32_bf16 v[106:109], v[160:163], v[192:195], v[106:109]
	v_mfma_f32_16x16x32_bf16 v[94:97], v[152:155], v[200:203], v[94:97]
	v_mfma_f32_16x16x32_bf16 v[90:93], v[160:163], v[200:203], v[90:93]
	s_waitcnt lgkmcnt(0)
	v_mfma_f32_16x16x32_bf16 v[78:81], v[152:155], v[208:211], v[78:81]
	v_mfma_f32_16x16x32_bf16 v[74:77], v[160:163], v[208:211], v[74:77]
	s_setprio 0
	s_setprio 1
	v_mfma_f32_16x16x32_bf16 v[118:121], v[164:167], v[180:183], v[118:121]
	v_mfma_f32_16x16x32_bf16 v[114:117], v[172:175], v[180:183], v[114:117]
	v_mfma_f32_16x16x32_bf16 v[102:105], v[164:167], v[188:191], v[102:105]
	v_mfma_f32_16x16x32_bf16 v[98:101], v[172:175], v[188:191], v[98:101]
	v_mfma_f32_16x16x32_bf16 v[86:89], v[164:167], v[196:199], v[86:89]
	v_mfma_f32_16x16x32_bf16 v[82:85], v[172:175], v[196:199], v[82:85]
	v_mfma_f32_16x16x32_bf16 v[70:73], v[164:167], v[204:207], v[70:73]
	v_mfma_f32_16x16x32_bf16 v[66:69], v[172:175], v[204:207], v[66:69]
	v_mfma_f32_16x16x32_bf16 v[118:121], v[168:171], v[184:187], v[118:121]
	v_mfma_f32_16x16x32_bf16 v[114:117], v[248:251], v[184:187], v[114:117]
	v_mfma_f32_16x16x32_bf16 v[102:105], v[168:171], v[192:195], v[102:105]
	v_mfma_f32_16x16x32_bf16 v[98:101], v[248:251], v[192:195], v[98:101]
	v_mfma_f32_16x16x32_bf16 v[86:89], v[168:171], v[200:203], v[86:89]
	v_mfma_f32_16x16x32_bf16 v[82:85], v[248:251], v[200:203], v[82:85]
	v_mfma_f32_16x16x32_bf16 v[70:73], v[168:171], v[208:211], v[70:73]
	s_setprio 2
	s_barrier
; #define PG8_STAGE(bufoff, gbase, voff) do { _Pragma("unroll") for (int _i = 0; _i < 2; ++_i) \
;         asm volatile("s_mov_b32 m0, %2\n\ts_nop 0\n\tglobal_load_lds_dwordx4 %0, %1" :: "v"((voff)[_i]), "s"((const char*)(gbase)), "s"(ldsbase + (unsigned)(bufoff) + ldsw + (unsigned)_i * 8192u) : "memory", "m0"); } while (0)
; #define PG8_LDA(dst, b, h) do { _Pragma("unroll") for (int m = 0; m < 4; ++m) _Pragma("unroll") for (int k = 0; k < 2; ++k) dst[m][k] = *(const PG8_LAS bf16x8*)(lds + PG8_SA(b, h) + aoff + m * 2048 + k * 1024); } while (0)
; #define PG8_MMA(ai, bj, At, Bt) do { __builtin_amdgcn_s_setprio(1); _Pragma("unroll") for (int m = 0; m < 4; ++m) _Pragma("unroll") for (int n = 0; n < 2; ++n) _Pragma("unroll") for (int k = 0; k < 2; ++k) \
;         acc[ai][bj][m][n] = __builtin_amdgcn_mfma_f32_16x16x32_bf16(Bt[n][k], At[m][k], acc[ai][bj][m][n], 0, 0, 0); __builtin_amdgcn_s_setprio(0); } while (0)
; #define PG8_WAIT_V(n) asm volatile("s_waitcnt vmcnt(" #n ")" ::: "memory")
; #define PG8_WAIT_L(n) asm volatile("s_waitcnt lgkmcnt(" #n ")" ::: "memory")
; #define PG8_BAR __builtin_amdgcn_s_barrier()
; #define PG8_SCHED __builtin_amdgcn_sched_barrier(0)
; template <class Epi, class Sched, bool ALIGN_EPI = false, bool SP2 = false>
; __device__ __forceinline__ void gemm_phase(PG8_LAS unsigned char* lds, const Gemm g, const Sched& S, const Epi& E) {
;     ...
;             PG8_LDA(At, 1, 1); PG8_STAGE(PG8_SB(1, 0), b3, voffB); PG8_STAGE(PG8_SB(1, 1), b3 + hstep, voffB); PG8_STAGE(PG8_SA(1, 0), a3, voffA);
;             PG8_WAIT_V(8); PG8_WAIT_L(0); PG8_BAR; PG8_MMA(1, 0, At, B0); PG8_MMA(1, 1, At, B1); PG8_BAR; PG8_SCHED;
;     ...
;         if constexpr (ALIGN_EPI) { if (wr == 0) PG8_BAR; }
	v_mfma_f32_16x16x32_bf16 v[66:69], v[248:251], v[208:211], v[66:69]
	s_setprio 0
	ds_read_b128 v[180:183], v147 offset:49152
	ds_read_b128 v[184:187], v147 offset:50176
	ds_read_b128 v[188:191], v147 offset:51200
	ds_read_b128 v[192:195], v147 offset:52224
	ds_read_b128 v[196:199], v147 offset:53248
	ds_read_b128 v[200:203], v147 offset:54272
	ds_read_b128 v[204:207], v147 offset:55296
	ds_read_b128 v[252:255], v147 offset:56320
	s_add_u32 s58, s66, 0x80
	s_addc_u32 s59, s67, 0
	s_mov_b32 m0, s88
	s_nop 0
	global_load_lds_dwordx4 v140, s[58:59]
	s_nop 0
	s_mov_b32 m0, s89
	s_nop 0
	global_load_lds_dwordx4 v142, s[58:59]
	s_add_u32 s58, s66, 0x2b0080
	s_addc_u32 s59, s67, 0
	s_mov_b32 m0, s92
	s_nop 0
	global_load_lds_dwordx4 v140, s[58:59]
	s_nop 0
	s_mov_b32 m0, s93
	s_nop 0
	global_load_lds_dwordx4 v142, s[58:59]
	s_nop 0
	s_mov_b32 m0, s90
	s_nop 0
	global_load_lds_dwordx4 v1, s[62:63]
	s_nop 0
	s_mov_b32 m0, s91
	s_nop 0
	global_load_lds_dwordx4 v141, s[62:63]
	s_waitcnt vmcnt(8)
	s_waitcnt lgkmcnt(0)
	v_mfma_f32_16x16x32_bf16 v[62:65], v[134:137], v[180:183], v[62:65]
	s_barrier
	s_setprio 1
	s_waitcnt lgkmcnt(7)
	v_mfma_f32_16x16x32_bf16 v[58:61], v[156:159], v[180:183], v[58:61]
	s_waitcnt lgkmcnt(5)
	v_mfma_f32_16x16x32_bf16 v[46:49], v[134:137], v[188:191], v[46:49]
	v_mfma_f32_16x16x32_bf16 v[42:45], v[156:159], v[188:191], v[42:45]
	s_waitcnt lgkmcnt(3)
	v_mfma_f32_16x16x32_bf16 v[30:33], v[134:137], v[196:199], v[30:33]
	v_mfma_f32_16x16x32_bf16 v[26:29], v[156:159], v[196:199], v[26:29]
	s_waitcnt lgkmcnt(1)
	v_mfma_f32_16x16x32_bf16 v[14:17], v[134:137], v[204:207], v[14:17]
	v_mfma_f32_16x16x32_bf16 v[10:13], v[156:159], v[204:207], v[10:13]
	v_mfma_f32_16x16x32_bf16 v[62:65], v[152:155], v[184:187], v[62:65]
	v_mfma_f32_16x16x32_bf16 v[58:61], v[160:163], v[184:187], v[58:61]
	v_mfma_f32_16x16x32_bf16 v[46:49], v[152:155], v[192:195], v[46:49]
	v_mfma_f32_16x16x32_bf16 v[42:45], v[160:163], v[192:195], v[42:45]
	v_mfma_f32_16x16x32_bf16 v[30:33], v[152:155], v[200:203], v[30:33]
	v_mfma_f32_16x16x32_bf16 v[26:29], v[160:163], v[200:203], v[26:29]
	s_waitcnt lgkmcnt(0)
	v_mfma_f32_16x16x32_bf16 v[14:17], v[152:155], v[252:255], v[14:17]
	v_mfma_f32_16x16x32_bf16 v[10:13], v[160:163], v[252:255], v[10:13]
	s_setprio 0
	s_setprio 1
	v_mfma_f32_16x16x32_bf16 v[54:57], v[164:167], v[180:183], v[54:57]
	v_mfma_f32_16x16x32_bf16 v[50:53], v[172:175], v[180:183], v[50:53]
	v_mfma_f32_16x16x32_bf16 v[38:41], v[164:167], v[188:191], v[38:41]
	v_mfma_f32_16x16x32_bf16 v[34:37], v[172:175], v[188:191], v[34:37]
	v_mfma_f32_16x16x32_bf16 v[22:25], v[164:167], v[196:199], v[22:25]
	v_mfma_f32_16x16x32_bf16 v[18:21], v[172:175], v[196:199], v[18:21]
	v_mfma_f32_16x16x32_bf16 v[6:9], v[164:167], v[204:207], v[6:9]
	v_mfma_f32_16x16x32_bf16 v[2:5], v[172:175], v[204:207], v[2:5]
	v_mfma_f32_16x16x32_bf16 v[54:57], v[168:171], v[184:187], v[54:57]
	v_mfma_f32_16x16x32_bf16 v[50:53], v[248:251], v[184:187], v[50:53]
	v_mfma_f32_16x16x32_bf16 v[38:41], v[168:171], v[192:195], v[38:41]
	v_mfma_f32_16x16x32_bf16 v[34:37], v[248:251], v[192:195], v[34:37]
	v_mfma_f32_16x16x32_bf16 v[22:25], v[168:171], v[200:203], v[22:25]
	v_mfma_f32_16x16x32_bf16 v[18:21], v[248:251], v[200:203], v[18:21]
	v_mfma_f32_16x16x32_bf16 v[6:9], v[168:171], v[252:255], v[6:9]
	s_setprio 2
	s_barrier
	v_mfma_f32_16x16x32_bf16 v[2:5], v[248:251], v[252:255], v[2:5]
	s_setprio 0
	s_add_i32 s57, s57, 2
	s_add_u32 s53, s53, 0x100
	s_addc_u32 s54, s54, 0
	s_add_u32 s55, s55, 0x100
	s_addc_u32 s56, s56, 0
	s_add_u32 s50, s50, 0x100
	s_addc_u32 s51, s51, 0
	s_cmpk_gt_u32 s57, 0xa9
	s_cbranch_scc0 .LBB0_234
	s_and_b64 vcc, exec, s[16:17]
	s_cbranch_vccz .LBB0_237
	s_barrier

; #define PG8_STAGE(bufoff, gbase, voff) do { _Pragma("unroll") for (int _i = 0; _i < 2; ++_i) \
;         asm volatile("s_mov_b32 m0, %2\n\ts_nop 0\n\tglobal_load_lds_dwordx4 %0, %1" :: "v"((voff)[_i]), "s"((const char*)(gbase)), "s"(ldsbase + (unsigned)(bufoff) + ldsw + (unsigned)_i * 8192u) : "memory", "m0"); } while (0)
; #define PG8_LDA(dst, b, h) do { _Pragma("unroll") for (int m = 0; m < 4; ++m) _Pragma("unroll") for (int k = 0; k < 2; ++k) dst[m][k] = *(const PG8_LAS bf16x8*)(lds + PG8_SA(b, h) + aoff + m * 2048 + k * 1024); } while (0)
; #define PG8_LDB(dst, b, h) do { _Pragma("unroll") for (int n = 0; n < 2; ++n) _Pragma("unroll") for (int k = 0; k < 2; ++k) dst[n][k] = *(const PG8_LAS bf16x8*)(lds + PG8_SB(b, h) + boff + n * 2048 + k * 1024); } while (0)
; #define PG8_MMA(ai, bj, At, Bt) do { __builtin_amdgcn_s_setprio(1); _Pragma("unroll") for (int m = 0; m < 4; ++m) _Pragma("unroll") for (int n = 0; n < 2; ++n) _Pragma("unroll") for (int k = 0; k < 2; ++k) \
;         acc[ai][bj][m][n] = __builtin_amdgcn_mfma_f32_16x16x32_bf16(Bt[n][k], At[m][k], acc[ai][bj][m][n], 0, 0, 0); __builtin_amdgcn_s_setprio(0); } while (0)
; template <class Epi, class Sched, bool ALIGN_EPI = false, bool SP2 = false>
; __device__ __forceinline__ void gemm_phase(PG8_LAS unsigned char* lds, const Gemm g, const Sched& S, const Epi& E) {
;     ...
;             const bool last = (t == nt - 2);
;             const char* a1 = cA + (size_t)(t + 1) * kstep;
;             const char* a2 = last ? nA : cA + (size_t)(t + 2) * kstep; const char* b2 = last ? nB : cB + (size_t)(t + 2) * kstep;
;             const char* a3 = a2 + kstep; const char* b3 = b2 + kstep;
;             if (last && has_next) S.a_ready(nxt);
;             if constexpr (epi_has_mid<Epi>::value) { if (t == Epi::MID_T) E.mid(acc, cur, wr, wc, fr, fq); }
;             if constexpr (SP2) {
;             PG8_LDB(B0, 0, 0); PG8_LDB(B1, 0, 1); PG8_SCHED; PG8_LDA(At, 0, 0); PG8_STAGE(PG8_SA(1, 1), a1 + hstep, voffA);
;             PG8_WAIT_V(8); PG8_WAIT_L(0); PG8_BAR; PG8_MMA(0, 0, At, B0); PG8_MMA(0, 1, At, B1); PG8_BAR; PG8_SCHED;
;             PG8_LDA(At, 0, 1); PG8_STAGE(PG8_SB(0, 0), b2, voffB); PG8_STAGE(PG8_SB(0, 1), b2 + hstep, voffB); PG8_STAGE(PG8_SA(0, 0), a2, voffA);
;             PG8_WAIT_V(8); PG8_WAIT_L(0); PG8_BAR; PG8_MMA(1, 0, At, B0); PG8_MMA(1, 1, At, B1); PG8_BAR; PG8_SCHED;
.LBB0_325:
	v_add_u32_e32 v138, 0x10000, v151
	ds_read_b128 v[154:157], v138
	ds_read_b128 v[158:161], v138 offset:1024
	ds_read_b128 v[162:165], v138 offset:2048
	ds_read_b128 v[166:169], v138 offset:3072
	v_add_u32_e32 v138, 0x14000, v151
	s_add_u32 s8, s82, 0x100
	ds_read_b128 v[170:173], v138
	ds_read_b128 v[174:177], v138 offset:1024
	ds_read_b128 v[178:181], v138 offset:2048
	ds_read_b128 v[182:185], v138 offset:3072
	s_addc_u32 s9, s83, 0
	s_and_b64 s[60:61], s[62:63], exec
	s_cselect_b32 s84, s54, s8
	s_cselect_b32 s85, s19, s9
	s_cselect_b32 s63, s17, s57
	s_cselect_b32 s62, s55, s56
	s_add_u32 s66, s84, 0x80
	s_addc_u32 s67, s85, 0
	s_add_u32 s76, s62, 0x80
	s_addc_u32 s77, s63, 0
	ds_read_b128 v[186:189], v152
	ds_read_b128 v[190:193], v152 offset:1024
	ds_read_b128 v[194:197], v152 offset:2048
	ds_read_b128 v[198:201], v152 offset:3072
	ds_read_b128 v[202:205], v152 offset:4096
	ds_read_b128 v[206:209], v152 offset:5120
	ds_read_b128 v[210:213], v152 offset:6144
	ds_read_b128 v[214:217], v152 offset:7168
	s_add_u32 s60, s82, 0x100080
	s_addc_u32 s61, s83, 0
	s_mov_b32 m0, s97
	s_nop 0
	global_load_lds_dwordx4 v141, s[60:61]
	s_nop 0
	s_mov_b32 m0, s70
	s_nop 0
	global_load_lds_dwordx4 v143, s[60:61]
	s_waitcnt vmcnt(8)
	s_waitcnt lgkmcnt(0)
	v_mfma_f32_16x16x32_bf16 v[126:129], v[154:157], v[186:189], v[126:129]
	s_barrier
	s_setprio 1
	s_waitcnt lgkmcnt(7)
	v_mfma_f32_16x16x32_bf16 v[122:125], v[162:165], v[186:189], v[122:125]
	s_waitcnt lgkmcnt(5)
	v_mfma_f32_16x16x32_bf16 v[110:113], v[154:157], v[194:197], v[110:113]
	v_mfma_f32_16x16x32_bf16 v[106:109], v[162:165], v[194:197], v[106:109]
	s_waitcnt lgkmcnt(3)
	v_mfma_f32_16x16x32_bf16 v[94:97], v[154:157], v[202:205], v[94:97]
	v_mfma_f32_16x16x32_bf16 v[90:93], v[162:165], v[202:205], v[90:93]
	s_waitcnt lgkmcnt(1)
	v_mfma_f32_16x16x32_bf16 v[78:81], v[154:157], v[210:213], v[78:81]
	v_mfma_f32_16x16x32_bf16 v[74:77], v[162:165], v[210:213], v[74:77]
	v_mfma_f32_16x16x32_bf16 v[126:129], v[158:161], v[190:193], v[126:129]
	v_mfma_f32_16x16x32_bf16 v[122:125], v[166:169], v[190:193], v[122:125]
	v_mfma_f32_16x16x32_bf16 v[110:113], v[158:161], v[198:201], v[110:113]
	v_mfma_f32_16x16x32_bf16 v[106:109], v[166:169], v[198:201], v[106:109]
	v_mfma_f32_16x16x32_bf16 v[94:97], v[158:161], v[206:209], v[94:97]
	v_mfma_f32_16x16x32_bf16 v[90:93], v[166:169], v[206:209], v[90:93]
	s_waitcnt lgkmcnt(0)
	v_mfma_f32_16x16x32_bf16 v[78:81], v[158:161], v[214:217], v[78:81]
	v_mfma_f32_16x16x32_bf16 v[74:77], v[166:169], v[214:217], v[74:77]
	s_setprio 0
	s_setprio 1
	v_mfma_f32_16x16x32_bf16 v[118:121], v[170:173], v[186:189], v[118:121]
	v_mfma_f32_16x16x32_bf16 v[114:117], v[178:181], v[186:189], v[114:117]
	v_mfma_f32_16x16x32_bf16 v[102:105], v[170:173], v[194:197], v[102:105]
	v_mfma_f32_16x16x32_bf16 v[98:101], v[178:181], v[194:197], v[98:101]
	v_mfma_f32_16x16x32_bf16 v[86:89], v[170:173], v[202:205], v[86:89]
	v_mfma_f32_16x16x32_bf16 v[82:85], v[178:181], v[202:205], v[82:85]
	v_mfma_f32_16x16x32_bf16 v[70:73], v[170:173], v[210:213], v[70:73]
	v_mfma_f32_16x16x32_bf16 v[66:69], v[178:181], v[210:213], v[66:69]
	v_mfma_f32_16x16x32_bf16 v[118:121], v[174:177], v[190:193], v[118:121]
	v_mfma_f32_16x16x32_bf16 v[114:117], v[182:185], v[190:193], v[114:117]
	v_mfma_f32_16x16x32_bf16 v[102:105], v[174:177], v[198:201], v[102:105]
	v_mfma_f32_16x16x32_bf16 v[98:101], v[182:185], v[198:201], v[98:101]
	v_mfma_f32_16x16x32_bf16 v[86:89], v[174:177], v[206:209], v[86:89]
	v_mfma_f32_16x16x32_bf16 v[82:85], v[182:185], v[206:209], v[82:85]
	v_mfma_f32_16x16x32_bf16 v[70:73], v[174:177], v[214:217], v[70:73]
	s_setprio 2
	s_barrier
	v_mfma_f32_16x16x32_bf16 v[66:69], v[182:185], v[214:217], v[66:69]
	s_setprio 0
	ds_read_b128 v[186:189], v152 offset:16384
	ds_read_b128 v[190:193], v152 offset:17408
	ds_read_b128 v[194:197], v152 offset:18432
	ds_read_b128 v[198:201], v152 offset:19456
	ds_read_b128 v[202:205], v152 offset:20480
	ds_read_b128 v[206:209], v152 offset:21504
	ds_read_b128 v[210:213], v152 offset:22528
	ds_read_b128 v[252:255], v152 offset:23552
	s_mov_b32 m0, s68
	s_nop 0
	global_load_lds_dwordx4 v142, s[62:63]
	s_add_u32 s60, s62, 0x100000
	s_mov_b32 m0, s69
	s_nop 0
	global_load_lds_dwordx4 v144, s[62:63]
	s_addc_u32 s61, s63, 0
	s_mov_b32 m0, s81
	s_nop 0
	global_load_lds_dwordx4 v142, s[60:61]
	s_nop 0
	s_mov_b32 m0, s86
	s_nop 0
	global_load_lds_dwordx4 v144, s[60:61]
	s_nop 0
	s_mov_b32 m0, s65
	s_nop 0
	global_load_lds_dwordx4 v141, s[84:85]
	s_nop 0
	s_mov_b32 m0, s87
	s_nop 0
	global_load_lds_dwordx4 v143, s[84:85]
	s_waitcnt vmcnt(8)
	s_waitcnt lgkmcnt(0)
	v_mfma_f32_16x16x32_bf16 v[62:65], v[154:157], v[186:189], v[62:65]
	s_barrier
; #define PG8_STAGE(bufoff, gbase, voff) do { _Pragma("unroll") for (int _i = 0; _i < 2; ++_i) \
;         asm volatile("s_mov_b32 m0, %2\n\ts_nop 0\n\tglobal_load_lds_dwordx4 %0, %1" :: "v"((voff)[_i]), "s"((const char*)(gbase)), "s"(ldsbase + (unsigned)(bufoff) + ldsw + (unsigned)_i * 8192u) : "memory", "m0"); } while (0)
; #define PG8_LDA(dst, b, h) do { _Pragma("unroll") for (int m = 0; m < 4; ++m) _Pragma("unroll") for (int k = 0; k < 2; ++k) dst[m][k] = *(const PG8_LAS bf16x8*)(lds + PG8_SA(b, h) + aoff + m * 2048 + k * 1024); } while (0)
; #define PG8_LDB(dst, b, h) do { _Pragma("unroll") for (int n = 0; n < 2; ++n) _Pragma("unroll") for (int k = 0; k < 2; ++k) dst[n][k] = *(const PG8_LAS bf16x8*)(lds + PG8_SB(b, h) + boff + n * 2048 + k * 1024); } while (0)
; #define PG8_MMA(ai, bj, At, Bt) do { __builtin_amdgcn_s_setprio(1); _Pragma("unroll") for (int m = 0; m < 4; ++m) _Pragma("unroll") for (int n = 0; n < 2; ++n) _Pragma("unroll") for (int k = 0; k < 2; ++k) \
;         acc[ai][bj][m][n] = __builtin_amdgcn_mfma_f32_16x16x32_bf16(Bt[n][k], At[m][k], acc[ai][bj][m][n], 0, 0, 0); __builtin_amdgcn_s_setprio(0); } while (0)
; #define PG8_WAIT_V(n) asm volatile("s_waitcnt vmcnt(" #n ")" ::: "memory")
; #define PG8_WAIT_L(n) asm volatile("s_waitcnt lgkmcnt(" #n ")" ::: "memory")
; #define PG8_BAR __builtin_amdgcn_s_barrier()
; #define PG8_SCHED __builtin_amdgcn_sched_barrier(0)
; template <class Epi, class Sched, bool ALIGN_EPI = false, bool SP2 = false>
; __device__ __forceinline__ void gemm_phase(PG8_LAS unsigned char* lds, const Gemm g, const Sched& S, const Epi& E) {
;     ...
;             PG8_WAIT_V(8); PG8_WAIT_L(0); PG8_BAR; PG8_MMA(0, 0, At, B0); PG8_MMA(0, 1, At, B1); PG8_BAR; PG8_SCHED;
;             PG8_LDA(At, 0, 1); PG8_STAGE(PG8_SB(0, 0), b2, voffB); PG8_STAGE(PG8_SB(0, 1), b2 + hstep, voffB); PG8_STAGE(PG8_SA(0, 0), a2, voffA);
;             PG8_WAIT_V(8); PG8_WAIT_L(0); PG8_BAR; PG8_MMA(1, 0, At, B0); PG8_MMA(1, 1, At, B1); PG8_BAR; PG8_SCHED;
;             PG8_LDB(B0, 1, 0); PG8_LDB(B1, 1, 1); PG8_SCHED; PG8_LDA(At, 1, 0); PG8_STAGE(PG8_SA(0, 1), a2 + hstep, voffA);
;             PG8_WAIT_V(8); PG8_WAIT_L(0); PG8_BAR; PG8_MMA(0, 0, At, B0); PG8_MMA(0, 1, At, B1); PG8_BAR; PG8_SCHED;
	s_setprio 1
	s_waitcnt lgkmcnt(7)
	v_mfma_f32_16x16x32_bf16 v[58:61], v[162:165], v[186:189], v[58:61]
	s_waitcnt lgkmcnt(5)
	v_mfma_f32_16x16x32_bf16 v[46:49], v[154:157], v[194:197], v[46:49]
	v_mfma_f32_16x16x32_bf16 v[42:45], v[162:165], v[194:197], v[42:45]
	s_waitcnt lgkmcnt(3)
	v_mfma_f32_16x16x32_bf16 v[30:33], v[154:157], v[202:205], v[30:33]
	v_mfma_f32_16x16x32_bf16 v[26:29], v[162:165], v[202:205], v[26:29]
	s_waitcnt lgkmcnt(1)
	v_mfma_f32_16x16x32_bf16 v[14:17], v[154:157], v[210:213], v[14:17]
	v_mfma_f32_16x16x32_bf16 v[10:13], v[162:165], v[210:213], v[10:13]
	v_mfma_f32_16x16x32_bf16 v[62:65], v[158:161], v[190:193], v[62:65]
	v_mfma_f32_16x16x32_bf16 v[58:61], v[166:169], v[190:193], v[58:61]
	v_mfma_f32_16x16x32_bf16 v[46:49], v[158:161], v[198:201], v[46:49]
	v_mfma_f32_16x16x32_bf16 v[42:45], v[166:169], v[198:201], v[42:45]
	v_mfma_f32_16x16x32_bf16 v[30:33], v[158:161], v[206:209], v[30:33]
	v_mfma_f32_16x16x32_bf16 v[26:29], v[166:169], v[206:209], v[26:29]
	s_waitcnt lgkmcnt(0)
	v_mfma_f32_16x16x32_bf16 v[14:17], v[158:161], v[252:255], v[14:17]
	v_mfma_f32_16x16x32_bf16 v[10:13], v[166:169], v[252:255], v[10:13]
	s_setprio 0
	s_setprio 1
	v_mfma_f32_16x16x32_bf16 v[54:57], v[170:173], v[186:189], v[54:57]
	v_mfma_f32_16x16x32_bf16 v[50:53], v[178:181], v[186:189], v[50:53]
	v_mfma_f32_16x16x32_bf16 v[38:41], v[170:173], v[194:197], v[38:41]
	v_mfma_f32_16x16x32_bf16 v[34:37], v[178:181], v[194:197], v[34:37]
	v_mfma_f32_16x16x32_bf16 v[22:25], v[170:173], v[202:205], v[22:25]
	v_mfma_f32_16x16x32_bf16 v[18:21], v[178:181], v[202:205], v[18:21]
	v_mfma_f32_16x16x32_bf16 v[6:9], v[170:173], v[210:213], v[6:9]
	v_mfma_f32_16x16x32_bf16 v[2:5], v[178:181], v[210:213], v[2:5]
	v_mfma_f32_16x16x32_bf16 v[54:57], v[174:177], v[190:193], v[54:57]
	v_mfma_f32_16x16x32_bf16 v[50:53], v[182:185], v[190:193], v[50:53]
	v_mfma_f32_16x16x32_bf16 v[38:41], v[174:177], v[198:201], v[38:41]
	v_mfma_f32_16x16x32_bf16 v[34:37], v[182:185], v[198:201], v[34:37]
	v_mfma_f32_16x16x32_bf16 v[22:25], v[174:177], v[206:209], v[22:25]
	v_mfma_f32_16x16x32_bf16 v[18:21], v[182:185], v[206:209], v[18:21]
	v_mfma_f32_16x16x32_bf16 v[6:9], v[174:177], v[252:255], v[6:9]
	s_setprio 2
	s_barrier
	v_mfma_f32_16x16x32_bf16 v[2:5], v[182:185], v[252:255], v[2:5]
	s_setprio 0
	v_add_u32_e32 v138, 0x18000, v151
	ds_read_b128 v[154:157], v138
	ds_read_b128 v[158:161], v138 offset:1024
	ds_read_b128 v[162:165], v138 offset:2048
	ds_read_b128 v[166:169], v138 offset:3072
	v_add_u32_e32 v138, 0x1c000, v151
	ds_read_b128 v[170:173], v138
	ds_read_b128 v[174:177], v138 offset:1024
	ds_read_b128 v[178:181], v138 offset:2048
	ds_read_b128 v[248:251], v138 offset:3072
	ds_read_b128 v[186:189], v152 offset:32768
	ds_read_b128 v[190:193], v152 offset:33792
	ds_read_b128 v[194:197], v152 offset:34816
	ds_read_b128 v[198:201], v152 offset:35840
	ds_read_b128 v[202:205], v152 offset:36864
	ds_read_b128 v[206:209], v152 offset:37888
	ds_read_b128 v[210:213], v152 offset:38912
	ds_read_b128 v[214:217], v152 offset:39936
	s_add_u32 s60, s84, 0x100000
	s_addc_u32 s61, s85, 0
	s_mov_b32 m0, s88
	s_nop 0
	global_load_lds_dwordx4 v141, s[60:61]
	s_nop 0
	s_mov_b32 m0, s89
	s_nop 0
	global_load_lds_dwordx4 v143, s[60:61]
	s_waitcnt vmcnt(8)
	s_waitcnt lgkmcnt(0)
	v_mfma_f32_16x16x32_bf16 v[126:129], v[154:157], v[186:189], v[126:129]
	s_barrier
	s_setprio 1
	s_waitcnt lgkmcnt(7)
	v_mfma_f32_16x16x32_bf16 v[122:125], v[162:165], v[186:189], v[122:125]
	s_waitcnt lgkmcnt(5)
	v_mfma_f32_16x16x32_bf16 v[110:113], v[154:157], v[194:197], v[110:113]
	v_mfma_f32_16x16x32_bf16 v[106:109], v[162:165], v[194:197], v[106:109]
	s_waitcnt lgkmcnt(3)
	v_mfma_f32_16x16x32_bf16 v[94:97], v[154:157], v[202:205], v[94:97]
	v_mfma_f32_16x16x32_bf16 v[90:93], v[162:165], v[202:205], v[90:93]
	s_waitcnt lgkmcnt(1)
	v_mfma_f32_16x16x32_bf16 v[78:81], v[154:157], v[210:213], v[78:81]
	v_mfma_f32_16x16x32_bf16 v[74:77], v[162:165], v[210:213], v[74:77]
	v_mfma_f32_16x16x32_bf16 v[126:129], v[158:161], v[190:193], v[126:129]
	v_mfma_f32_16x16x32_bf16 v[122:125], v[166:169], v[190:193], v[122:125]
	v_mfma_f32_16x16x32_bf16 v[110:113], v[158:161], v[198:201], v[110:113]
	v_mfma_f32_16x16x32_bf16 v[106:109], v[166:169], v[198:201], v[106:109]
	v_mfma_f32_16x16x32_bf16 v[94:97], v[158:161], v[206:209], v[94:97]
	v_mfma_f32_16x16x32_bf16 v[90:93], v[166:169], v[206:209], v[90:93]
	s_waitcnt lgkmcnt(0)
	v_mfma_f32_16x16x32_bf16 v[78:81], v[158:161], v[214:217], v[78:81]
	v_mfma_f32_16x16x32_bf16 v[74:77], v[166:169], v[214:217], v[74:77]
	s_setprio 0
	s_setprio 1
	v_mfma_f32_16x16x32_bf16 v[118:121], v[170:173], v[186:189], v[118:121]
	v_mfma_f32_16x16x32_bf16 v[114:117], v[178:181], v[186:189], v[114:117]
	v_mfma_f32_16x16x32_bf16 v[102:105], v[170:173], v[194:197], v[102:105]
	v_mfma_f32_16x16x32_bf16 v[98:101], v[178:181], v[194:197], v[98:101]
	v_mfma_f32_16x16x32_bf16 v[86:89], v[170:173], v[202:205], v[86:89]
	v_mfma_f32_16x16x32_bf16 v[82:85], v[178:181], v[202:205], v[82:85]
	v_mfma_f32_16x16x32_bf16 v[70:73], v[170:173], v[210:213], v[70:73]
	v_mfma_f32_16x16x32_bf16 v[66:69], v[178:181], v[210:213], v[66:69]
	v_mfma_f32_16x16x32_bf16 v[118:121], v[174:177], v[190:193], v[118:121]
	v_mfma_f32_16x16x32_bf16 v[114:117], v[248:251], v[190:193], v[114:117]
	v_mfma_f32_16x16x32_bf16 v[102:105], v[174:177], v[198:201], v[102:105]
	v_mfma_f32_16x16x32_bf16 v[98:101], v[248:251], v[198:201], v[98:101]
	v_mfma_f32_16x16x32_bf16 v[86:89], v[174:177], v[206:209], v[86:89]
	v_mfma_f32_16x16x32_bf16 v[82:85], v[248:251], v[206:209], v[82:85]
	v_mfma_f32_16x16x32_bf16 v[70:73], v[174:177], v[214:217], v[70:73]
	s_setprio 2
	s_barrier
; #define PG8_STAGE(bufoff, gbase, voff) do { _Pragma("unroll") for (int _i = 0; _i < 2; ++_i) \
;         asm volatile("s_mov_b32 m0, %2\n\ts_nop 0\n\tglobal_load_lds_dwordx4 %0, %1" :: "v"((voff)[_i]), "s"((const char*)(gbase)), "s"(ldsbase + (unsigned)(bufoff) + ldsw + (unsigned)_i * 8192u) : "memory", "m0"); } while (0)
; #define PG8_LDA(dst, b, h) do { _Pragma("unroll") for (int m = 0; m < 4; ++m) _Pragma("unroll") for (int k = 0; k < 2; ++k) dst[m][k] = *(const PG8_LAS bf16x8*)(lds + PG8_SA(b, h) + aoff + m * 2048 + k * 1024); } while (0)
; #define PG8_MMA(ai, bj, At, Bt) do { __builtin_amdgcn_s_setprio(1); _Pragma("unroll") for (int m = 0; m < 4; ++m) _Pragma("unroll") for (int n = 0; n < 2; ++n) _Pragma("unroll") for (int k = 0; k < 2; ++k) \
;         acc[ai][bj][m][n] = __builtin_amdgcn_mfma_f32_16x16x32_bf16(Bt[n][k], At[m][k], acc[ai][bj][m][n], 0, 0, 0); __builtin_amdgcn_s_setprio(0); } while (0)
; #define PG8_WAIT_V(n) asm volatile("s_waitcnt vmcnt(" #n ")" ::: "memory")
; #define PG8_WAIT_L(n) asm volatile("s_waitcnt lgkmcnt(" #n ")" ::: "memory")
; #define PG8_BAR __builtin_amdgcn_s_barrier()
; #define PG8_SCHED __builtin_amdgcn_sched_barrier(0)
; template <class Epi, class Sched, bool ALIGN_EPI = false, bool SP2 = false>
; __device__ __forceinline__ void gemm_phase(PG8_LAS unsigned char* lds, const Gemm g, const Sched& S, const Epi& E) {
;     ...
;             PG8_LDA(At, 1, 1); PG8_STAGE(PG8_SB(1, 0), b3, voffB); PG8_STAGE(PG8_SB(1, 1), b3 + hstep, voffB); PG8_STAGE(PG8_SA(1, 0), a3, voffA);
;             PG8_WAIT_V(8); PG8_WAIT_L(0); PG8_BAR; PG8_MMA(1, 0, At, B0); PG8_MMA(1, 1, At, B1); PG8_BAR; PG8_SCHED;
	v_mfma_f32_16x16x32_bf16 v[66:69], v[248:251], v[214:217], v[66:69]
	s_setprio 0
	ds_read_b128 v[186:189], v152 offset:49152
	ds_read_b128 v[190:193], v152 offset:50176
	ds_read_b128 v[194:197], v152 offset:51200
	ds_read_b128 v[198:201], v152 offset:52224
	ds_read_b128 v[202:205], v152 offset:53248
	ds_read_b128 v[206:209], v152 offset:54272
	ds_read_b128 v[210:213], v152 offset:55296
	ds_read_b128 v[252:255], v152 offset:56320
	s_mov_b32 m0, s90
	s_nop 0
	global_load_lds_dwordx4 v142, s[76:77]
	s_add_u32 s60, s62, 0x100080
	s_mov_b32 m0, s91
	s_nop 0
	global_load_lds_dwordx4 v144, s[76:77]
	s_addc_u32 s61, s63, 0
	s_mov_b32 m0, s95
	s_nop 0
	global_load_lds_dwordx4 v142, s[60:61]
	s_nop 0
	s_mov_b32 m0, s96
	s_nop 0
	global_load_lds_dwordx4 v144, s[60:61]
	s_nop 0
	s_mov_b32 m0, s92
	s_nop 0
	global_load_lds_dwordx4 v141, s[66:67]
	s_nop 0
	s_mov_b32 m0, s94
	s_nop 0
	global_load_lds_dwordx4 v143, s[66:67]
	s_waitcnt vmcnt(8)
	s_waitcnt lgkmcnt(0)
	v_mfma_f32_16x16x32_bf16 v[62:65], v[154:157], v[186:189], v[62:65]
	s_barrier
	s_setprio 1
	s_waitcnt lgkmcnt(7)
	v_mfma_f32_16x16x32_bf16 v[58:61], v[162:165], v[186:189], v[58:61]
	s_waitcnt lgkmcnt(5)
	v_mfma_f32_16x16x32_bf16 v[46:49], v[154:157], v[194:197], v[46:49]
	v_mfma_f32_16x16x32_bf16 v[42:45], v[162:165], v[194:197], v[42:45]
	s_waitcnt lgkmcnt(3)
	v_mfma_f32_16x16x32_bf16 v[30:33], v[154:157], v[202:205], v[30:33]
	v_mfma_f32_16x16x32_bf16 v[26:29], v[162:165], v[202:205], v[26:29]
	s_waitcnt lgkmcnt(1)
	v_mfma_f32_16x16x32_bf16 v[14:17], v[154:157], v[210:213], v[14:17]
	v_mfma_f32_16x16x32_bf16 v[10:13], v[162:165], v[210:213], v[10:13]
	v_mfma_f32_16x16x32_bf16 v[62:65], v[158:161], v[190:193], v[62:65]
	v_mfma_f32_16x16x32_bf16 v[58:61], v[166:169], v[190:193], v[58:61]
	v_mfma_f32_16x16x32_bf16 v[46:49], v[158:161], v[198:201], v[46:49]
	v_mfma_f32_16x16x32_bf16 v[42:45], v[166:169], v[198:201], v[42:45]
	v_mfma_f32_16x16x32_bf16 v[30:33], v[158:161], v[206:209], v[30:33]
	v_mfma_f32_16x16x32_bf16 v[26:29], v[166:169], v[206:209], v[26:29]
	s_waitcnt lgkmcnt(0)
	v_mfma_f32_16x16x32_bf16 v[14:17], v[158:161], v[252:255], v[14:17]
	v_mfma_f32_16x16x32_bf16 v[10:13], v[166:169], v[252:255], v[10:13]
	s_setprio 0
	s_setprio 1
	v_mfma_f32_16x16x32_bf16 v[54:57], v[170:173], v[186:189], v[54:57]
	v_mfma_f32_16x16x32_bf16 v[50:53], v[178:181], v[186:189], v[50:53]
	v_mfma_f32_16x16x32_bf16 v[38:41], v[170:173], v[194:197], v[38:41]
	v_mfma_f32_16x16x32_bf16 v[34:37], v[178:181], v[194:197], v[34:37]
	v_mfma_f32_16x16x32_bf16 v[22:25], v[170:173], v[202:205], v[22:25]
	v_mfma_f32_16x16x32_bf16 v[18:21], v[178:181], v[202:205], v[18:21]
	v_mfma_f32_16x16x32_bf16 v[6:9], v[170:173], v[210:213], v[6:9]
	v_mfma_f32_16x16x32_bf16 v[2:5], v[178:181], v[210:213], v[2:5]
	v_mfma_f32_16x16x32_bf16 v[54:57], v[174:177], v[190:193], v[54:57]
	v_mfma_f32_16x16x32_bf16 v[50:53], v[248:251], v[190:193], v[50:53]
	v_mfma_f32_16x16x32_bf16 v[38:41], v[174:177], v[198:201], v[38:41]
	v_mfma_f32_16x16x32_bf16 v[34:37], v[248:251], v[198:201], v[34:37]
	v_mfma_f32_16x16x32_bf16 v[22:25], v[174:177], v[206:209], v[22:25]
	v_mfma_f32_16x16x32_bf16 v[18:21], v[248:251], v[206:209], v[18:21]
	v_mfma_f32_16x16x32_bf16 v[6:9], v[174:177], v[252:255], v[6:9]
	s_setprio 2
	s_barrier
	v_mfma_f32_16x16x32_bf16 v[2:5], v[248:251], v[252:255], v[2:5]
	s_setprio 0
	s_add_i32 s58, s58, 2
	s_add_u32 s56, s56, 0x100
	s_addc_u32 s57, s57, 0
	s_cmp_gt_u32 s58, 61
	s_cbranch_scc1 .LBB0_316
	s_mov_b64 s[82:83], s[8:9]
	s_branch .LBB0_320

; #define PG8_STAGE(bufoff, gbase, voff) do { _Pragma("unroll") for (int _i = 0; _i < 2; ++_i) \
;         asm volatile("s_mov_b32 m0, %2\n\ts_nop 0\n\tglobal_load_lds_dwordx4 %0, %1" :: "v"((voff)[_i]), "s"((const char*)(gbase)), "s"(ldsbase + (unsigned)(bufoff) + ldsw + (unsigned)_i * 8192u) : "memory", "m0"); } while (0)
; #define PG8_LDA(dst, b, h) do { _Pragma("unroll") for (int m = 0; m < 4; ++m) _Pragma("unroll") for (int k = 0; k < 2; ++k) dst[m][k] = *(const PG8_LAS bf16x8*)(lds + PG8_SA(b, h) + aoff + m * 2048 + k * 1024); } while (0)
; #define PG8_LDB(dst, b, h) do { _Pragma("unroll") for (int n = 0; n < 2; ++n) _Pragma("unroll") for (int k = 0; k < 2; ++k) dst[n][k] = *(const PG8_LAS bf16x8*)(lds + PG8_SB(b, h) + boff + n * 2048 + k * 1024); } while (0)
; #define PG8_MMA(ai, bj, At, Bt) do { __builtin_amdgcn_s_setprio(1); _Pragma("unroll") for (int m = 0; m < 4; ++m) _Pragma("unroll") for (int n = 0; n < 2; ++n) _Pragma("unroll") for (int k = 0; k < 2; ++k) \
;         acc[ai][bj][m][n] = __builtin_amdgcn_mfma_f32_16x16x32_bf16(Bt[n][k], At[m][k], acc[ai][bj][m][n], 0, 0, 0); __builtin_amdgcn_s_setprio(0); } while (0)
; template <class Epi, class Sched, bool ALIGN_EPI = false, bool SP2 = false>
; __device__ __forceinline__ void gemm_phase(PG8_LAS unsigned char* lds, const Gemm g, const Sched& S, const Epi& E) {
;     ...
;             const bool last = (t == nt - 2);
;             const char* a1 = cA + (size_t)(t + 1) * kstep;
;             const char* a2 = last ? nA : cA + (size_t)(t + 2) * kstep; const char* b2 = last ? nB : cB + (size_t)(t + 2) * kstep;
;             const char* a3 = a2 + kstep; const char* b3 = b2 + kstep;
;             if (last && has_next) S.a_ready(nxt);
;             if constexpr (epi_has_mid<Epi>::value) { if (t == Epi::MID_T) E.mid(acc, cur, wr, wc, fr, fq); }
;             if constexpr (SP2) {
;             PG8_LDB(B0, 0, 0); PG8_LDB(B1, 0, 1); PG8_SCHED; PG8_LDA(At, 0, 0); PG8_STAGE(PG8_SA(1, 1), a1 + hstep, voffA);
;             PG8_WAIT_V(8); PG8_WAIT_L(0); PG8_BAR; PG8_MMA(0, 0, At, B0); PG8_MMA(0, 1, At, B1); PG8_BAR; PG8_SCHED;
;             PG8_LDA(At, 0, 1); PG8_STAGE(PG8_SB(0, 0), b2, voffB); PG8_STAGE(PG8_SB(0, 1), b2 + hstep, voffB); PG8_STAGE(PG8_SA(0, 0), a2, voffA);
;             PG8_WAIT_V(8); PG8_WAIT_L(0); PG8_BAR; PG8_MMA(1, 0, At, B0); PG8_MMA(1, 1, At, B1); PG8_BAR; PG8_SCHED;
.LBB0_620:
	v_add_u32_e32 v3, 0x10000, v199
	ds_read_b128 v[134:137], v3
	ds_read_b128 v[138:141], v3 offset:1024
	ds_read_b128 v[142:145], v3 offset:2048
	ds_read_b128 v[146:149], v3 offset:3072
	v_add_u32_e32 v3, 0x14000, v199
	s_add_u32 s44, s42, 0x100
	ds_read_b128 v[158:161], v3
	ds_read_b128 v[162:165], v3 offset:1024
	ds_read_b128 v[166:169], v3 offset:2048
	ds_read_b128 v[170:173], v3 offset:3072
	s_addc_u32 s45, s43, 0
	s_cmp_eq_u32 s92, 60
	s_cselect_b32 s56, s88, s44
	s_cselect_b32 s57, s23, s45
	s_cselect_b32 s47, s19, s91
	s_cselect_b32 s46, s89, s90
	s_add_u32 s50, s56, 0x80
	s_addc_u32 s51, s57, 0
	s_add_u32 s54, s46, 0x80
	s_addc_u32 s55, s47, 0
	ds_read_b128 v[174:177], v200
	ds_read_b128 v[178:181], v200 offset:1024
	ds_read_b128 v[182:185], v200 offset:2048
	ds_read_b128 v[186:189], v200 offset:3072
	ds_read_b128 v[190:193], v200 offset:4096
	ds_read_b128 v[202:205], v200 offset:5120
	ds_read_b128 v[206:209], v200 offset:6144
	ds_read_b128 v[210:213], v200 offset:7168
	s_add_u32 s42, s42, 0x100080
	s_addc_u32 s43, s43, 0
	s_mov_b32 m0, s85
	s_nop 0
	global_load_lds_dwordx4 v1, s[42:43]
	s_nop 0
	s_mov_b32 m0, s86
	s_nop 0
	global_load_lds_dwordx4 v195, s[42:43]
	s_waitcnt vmcnt(8)
	s_waitcnt lgkmcnt(0)
	v_mfma_f32_16x16x32_bf16 v[130:133], v[134:137], v[174:177], v[130:133]
	s_barrier
	s_setprio 1
	s_waitcnt lgkmcnt(7)
	v_mfma_f32_16x16x32_bf16 v[126:129], v[142:145], v[174:177], v[126:129]
	s_waitcnt lgkmcnt(5)
	v_mfma_f32_16x16x32_bf16 v[122:125], v[134:137], v[182:185], v[122:125]
	v_mfma_f32_16x16x32_bf16 v[118:121], v[142:145], v[182:185], v[118:121]
	s_waitcnt lgkmcnt(3)
	v_mfma_f32_16x16x32_bf16 v[114:117], v[134:137], v[190:193], v[114:117]
	v_mfma_f32_16x16x32_bf16 v[110:113], v[142:145], v[190:193], v[110:113]
	s_waitcnt lgkmcnt(1)
	v_mfma_f32_16x16x32_bf16 v[106:109], v[134:137], v[206:209], v[106:109]
	v_mfma_f32_16x16x32_bf16 v[102:105], v[142:145], v[206:209], v[102:105]
	v_mfma_f32_16x16x32_bf16 v[130:133], v[138:141], v[178:181], v[130:133]
	v_mfma_f32_16x16x32_bf16 v[126:129], v[146:149], v[178:181], v[126:129]
	v_mfma_f32_16x16x32_bf16 v[122:125], v[138:141], v[186:189], v[122:125]
	v_mfma_f32_16x16x32_bf16 v[118:121], v[146:149], v[186:189], v[118:121]
	v_mfma_f32_16x16x32_bf16 v[114:117], v[138:141], v[202:205], v[114:117]
	v_mfma_f32_16x16x32_bf16 v[110:113], v[146:149], v[202:205], v[110:113]
	s_waitcnt lgkmcnt(0)
	v_mfma_f32_16x16x32_bf16 v[106:109], v[138:141], v[210:213], v[106:109]
	v_mfma_f32_16x16x32_bf16 v[102:105], v[146:149], v[210:213], v[102:105]
	s_setprio 0
	s_setprio 1
	v_mfma_f32_16x16x32_bf16 v[66:69], v[158:161], v[174:177], v[66:69]
	v_mfma_f32_16x16x32_bf16 v[62:65], v[166:169], v[174:177], v[62:65]
	v_mfma_f32_16x16x32_bf16 v[58:61], v[158:161], v[182:185], v[58:61]
	v_mfma_f32_16x16x32_bf16 v[54:57], v[166:169], v[182:185], v[54:57]
	v_mfma_f32_16x16x32_bf16 v[50:53], v[158:161], v[190:193], v[50:53]
	v_mfma_f32_16x16x32_bf16 v[46:49], v[166:169], v[190:193], v[46:49]
	v_mfma_f32_16x16x32_bf16 v[42:45], v[158:161], v[206:209], v[42:45]
	v_mfma_f32_16x16x32_bf16 v[38:41], v[166:169], v[206:209], v[38:41]
	v_mfma_f32_16x16x32_bf16 v[66:69], v[162:165], v[178:181], v[66:69]
	v_mfma_f32_16x16x32_bf16 v[62:65], v[170:173], v[178:181], v[62:65]
	v_mfma_f32_16x16x32_bf16 v[58:61], v[162:165], v[186:189], v[58:61]
	v_mfma_f32_16x16x32_bf16 v[54:57], v[170:173], v[186:189], v[54:57]
	v_mfma_f32_16x16x32_bf16 v[50:53], v[162:165], v[202:205], v[50:53]
	v_mfma_f32_16x16x32_bf16 v[46:49], v[170:173], v[202:205], v[46:49]
	v_mfma_f32_16x16x32_bf16 v[42:45], v[162:165], v[210:213], v[42:45]
	s_setprio 2
	s_barrier
	v_mfma_f32_16x16x32_bf16 v[38:41], v[170:173], v[210:213], v[38:41]
	s_setprio 0
	ds_read_b128 v[174:177], v200 offset:16384
	ds_read_b128 v[178:181], v200 offset:17408
	ds_read_b128 v[182:185], v200 offset:18432
	ds_read_b128 v[186:189], v200 offset:19456
	ds_read_b128 v[190:193], v200 offset:20480
	ds_read_b128 v[202:205], v200 offset:21504
	ds_read_b128 v[206:209], v200 offset:22528
	ds_read_b128 v[252:255], v200 offset:23552
	s_mov_b32 m0, s63
	s_nop 0
	global_load_lds_dwordx4 v194, s[46:47]
	s_add_u32 s42, s46, 0x100000
	s_mov_b32 m0, s64
	s_nop 0
	global_load_lds_dwordx4 v196, s[46:47]
	s_addc_u32 s43, s47, 0
	s_mov_b32 m0, s65
	s_nop 0
	global_load_lds_dwordx4 v194, s[42:43]
	s_nop 0
	s_mov_b32 m0, s66
	s_nop 0
	global_load_lds_dwordx4 v196, s[42:43]
	s_nop 0
	s_mov_b32 m0, s62
	s_nop 0
	global_load_lds_dwordx4 v1, s[56:57]
	s_nop 0
	s_mov_b32 m0, s67
	s_nop 0
	global_load_lds_dwordx4 v195, s[56:57]
	s_waitcnt vmcnt(8)
	s_waitcnt lgkmcnt(0)
	v_mfma_f32_16x16x32_bf16 v[98:101], v[134:137], v[174:177], v[98:101]
	s_barrier
; #define PG8_STAGE(bufoff, gbase, voff) do { _Pragma("unroll") for (int _i = 0; _i < 2; ++_i) \
;         asm volatile("s_mov_b32 m0, %2\n\ts_nop 0\n\tglobal_load_lds_dwordx4 %0, %1" :: "v"((voff)[_i]), "s"((const char*)(gbase)), "s"(ldsbase + (unsigned)(bufoff) + ldsw + (unsigned)_i * 8192u) : "memory", "m0"); } while (0)
; #define PG8_LDA(dst, b, h) do { _Pragma("unroll") for (int m = 0; m < 4; ++m) _Pragma("unroll") for (int k = 0; k < 2; ++k) dst[m][k] = *(const PG8_LAS bf16x8*)(lds + PG8_SA(b, h) + aoff + m * 2048 + k * 1024); } while (0)
; #define PG8_LDB(dst, b, h) do { _Pragma("unroll") for (int n = 0; n < 2; ++n) _Pragma("unroll") for (int k = 0; k < 2; ++k) dst[n][k] = *(const PG8_LAS bf16x8*)(lds + PG8_SB(b, h) + boff + n * 2048 + k * 1024); } while (0)
; #define PG8_MMA(ai, bj, At, Bt) do { __builtin_amdgcn_s_setprio(1); _Pragma("unroll") for (int m = 0; m < 4; ++m) _Pragma("unroll") for (int n = 0; n < 2; ++n) _Pragma("unroll") for (int k = 0; k < 2; ++k) \
;         acc[ai][bj][m][n] = __builtin_amdgcn_mfma_f32_16x16x32_bf16(Bt[n][k], At[m][k], acc[ai][bj][m][n], 0, 0, 0); __builtin_amdgcn_s_setprio(0); } while (0)
; #define PG8_WAIT_V(n) asm volatile("s_waitcnt vmcnt(" #n ")" ::: "memory")
; #define PG8_WAIT_L(n) asm volatile("s_waitcnt lgkmcnt(" #n ")" ::: "memory")
; #define PG8_BAR __builtin_amdgcn_s_barrier()
; #define PG8_SCHED __builtin_amdgcn_sched_barrier(0)
; template <class Epi, class Sched, bool ALIGN_EPI = false, bool SP2 = false>
; __device__ __forceinline__ void gemm_phase(PG8_LAS unsigned char* lds, const Gemm g, const Sched& S, const Epi& E) {
;     ...
;             PG8_WAIT_V(8); PG8_WAIT_L(0); PG8_BAR; PG8_MMA(0, 0, At, B0); PG8_MMA(0, 1, At, B1); PG8_BAR; PG8_SCHED;
;             PG8_LDA(At, 0, 1); PG8_STAGE(PG8_SB(0, 0), b2, voffB); PG8_STAGE(PG8_SB(0, 1), b2 + hstep, voffB); PG8_STAGE(PG8_SA(0, 0), a2, voffA);
;             PG8_WAIT_V(8); PG8_WAIT_L(0); PG8_BAR; PG8_MMA(1, 0, At, B0); PG8_MMA(1, 1, At, B1); PG8_BAR; PG8_SCHED;
;             PG8_LDB(B0, 1, 0); PG8_LDB(B1, 1, 1); PG8_SCHED; PG8_LDA(At, 1, 0); PG8_STAGE(PG8_SA(0, 1), a2 + hstep, voffA);
;             PG8_WAIT_V(8); PG8_WAIT_L(0); PG8_BAR; PG8_MMA(0, 0, At, B0); PG8_MMA(0, 1, At, B1); PG8_BAR; PG8_SCHED;
	s_setprio 1
	s_waitcnt lgkmcnt(7)
	v_mfma_f32_16x16x32_bf16 v[94:97], v[142:145], v[174:177], v[94:97]
	s_waitcnt lgkmcnt(5)
	v_mfma_f32_16x16x32_bf16 v[90:93], v[134:137], v[182:185], v[90:93]
	v_mfma_f32_16x16x32_bf16 v[86:89], v[142:145], v[182:185], v[86:89]
	s_waitcnt lgkmcnt(3)
	v_mfma_f32_16x16x32_bf16 v[82:85], v[134:137], v[190:193], v[82:85]
	v_mfma_f32_16x16x32_bf16 v[78:81], v[142:145], v[190:193], v[78:81]
	s_waitcnt lgkmcnt(1)
	v_mfma_f32_16x16x32_bf16 v[74:77], v[134:137], v[206:209], v[74:77]
	v_mfma_f32_16x16x32_bf16 v[70:73], v[142:145], v[206:209], v[70:73]
	v_mfma_f32_16x16x32_bf16 v[98:101], v[138:141], v[178:181], v[98:101]
	v_mfma_f32_16x16x32_bf16 v[94:97], v[146:149], v[178:181], v[94:97]
	v_mfma_f32_16x16x32_bf16 v[90:93], v[138:141], v[186:189], v[90:93]
	v_mfma_f32_16x16x32_bf16 v[86:89], v[146:149], v[186:189], v[86:89]
	v_mfma_f32_16x16x32_bf16 v[82:85], v[138:141], v[202:205], v[82:85]
	v_mfma_f32_16x16x32_bf16 v[78:81], v[146:149], v[202:205], v[78:81]
	s_waitcnt lgkmcnt(0)
	v_mfma_f32_16x16x32_bf16 v[74:77], v[138:141], v[252:255], v[74:77]
	v_mfma_f32_16x16x32_bf16 v[70:73], v[146:149], v[252:255], v[70:73]
	s_setprio 0
	s_setprio 1
	v_mfma_f32_16x16x32_bf16 v[34:37], v[158:161], v[174:177], v[34:37]
	v_mfma_f32_16x16x32_bf16 v[30:33], v[166:169], v[174:177], v[30:33]
	v_mfma_f32_16x16x32_bf16 v[26:29], v[158:161], v[182:185], v[26:29]
	v_mfma_f32_16x16x32_bf16 v[22:25], v[166:169], v[182:185], v[22:25]
	v_mfma_f32_16x16x32_bf16 v[18:21], v[158:161], v[190:193], v[18:21]
	v_mfma_f32_16x16x32_bf16 v[14:17], v[166:169], v[190:193], v[14:17]
	v_mfma_f32_16x16x32_bf16 v[10:13], v[158:161], v[206:209], v[10:13]
	v_mfma_f32_16x16x32_bf16 v[4:7], v[166:169], v[206:209], v[6:9]
	v_mfma_f32_16x16x32_bf16 v[34:37], v[162:165], v[178:181], v[34:37]
	v_mfma_f32_16x16x32_bf16 v[30:33], v[170:173], v[178:181], v[30:33]
	v_mfma_f32_16x16x32_bf16 v[26:29], v[162:165], v[186:189], v[26:29]
	v_mfma_f32_16x16x32_bf16 v[22:25], v[170:173], v[186:189], v[22:25]
	v_mfma_f32_16x16x32_bf16 v[18:21], v[162:165], v[202:205], v[18:21]
	v_mfma_f32_16x16x32_bf16 v[14:17], v[170:173], v[202:205], v[14:17]
	v_mfma_f32_16x16x32_bf16 v[10:13], v[162:165], v[252:255], v[10:13]
	s_setprio 2
	s_barrier
	v_mfma_f32_16x16x32_bf16 v[4:7], v[170:173], v[252:255], v[4:7]
	s_setprio 0
	v_add_u32_e32 v3, 0x18000, v199
	ds_read_b128 v[134:137], v3
	ds_read_b128 v[138:141], v3 offset:1024
	ds_read_b128 v[142:145], v3 offset:2048
	ds_read_b128 v[146:149], v3 offset:3072
	v_add_u32_e32 v3, 0x1c000, v199
	ds_read_b128 v[158:161], v3
	ds_read_b128 v[162:165], v3 offset:1024
	ds_read_b128 v[166:169], v3 offset:2048
	ds_read_b128 v[248:251], v3 offset:3072
	ds_read_b128 v[174:177], v200 offset:32768
	ds_read_b128 v[178:181], v200 offset:33792
	ds_read_b128 v[182:185], v200 offset:34816
	ds_read_b128 v[186:189], v200 offset:35840
	ds_read_b128 v[190:193], v200 offset:36864
	ds_read_b128 v[202:205], v200 offset:37888
	ds_read_b128 v[206:209], v200 offset:38912
	ds_read_b128 v[210:213], v200 offset:39936
	s_add_u32 s42, s56, 0x100000
	s_addc_u32 s43, s57, 0
	s_mov_b32 m0, s76
	s_nop 0
	global_load_lds_dwordx4 v1, s[42:43]
	s_nop 0
	s_mov_b32 m0, s77
	s_nop 0
	global_load_lds_dwordx4 v195, s[42:43]
	s_waitcnt vmcnt(8)
	s_waitcnt lgkmcnt(0)
	v_mfma_f32_16x16x32_bf16 v[130:133], v[134:137], v[174:177], v[130:133]
	s_barrier
	s_setprio 1
	s_waitcnt lgkmcnt(7)
	v_mfma_f32_16x16x32_bf16 v[126:129], v[142:145], v[174:177], v[126:129]
	s_waitcnt lgkmcnt(5)
	v_mfma_f32_16x16x32_bf16 v[122:125], v[134:137], v[182:185], v[122:125]
	v_mfma_f32_16x16x32_bf16 v[118:121], v[142:145], v[182:185], v[118:121]
	s_waitcnt lgkmcnt(3)
	v_mfma_f32_16x16x32_bf16 v[114:117], v[134:137], v[190:193], v[114:117]
	v_mfma_f32_16x16x32_bf16 v[110:113], v[142:145], v[190:193], v[110:113]
	s_waitcnt lgkmcnt(1)
	v_mfma_f32_16x16x32_bf16 v[106:109], v[134:137], v[206:209], v[106:109]
	v_mfma_f32_16x16x32_bf16 v[102:105], v[142:145], v[206:209], v[102:105]
	v_mfma_f32_16x16x32_bf16 v[130:133], v[138:141], v[178:181], v[130:133]
	v_mfma_f32_16x16x32_bf16 v[126:129], v[146:149], v[178:181], v[126:129]
	v_mfma_f32_16x16x32_bf16 v[122:125], v[138:141], v[186:189], v[122:125]
	v_mfma_f32_16x16x32_bf16 v[118:121], v[146:149], v[186:189], v[118:121]
	v_mfma_f32_16x16x32_bf16 v[114:117], v[138:141], v[202:205], v[114:117]
	v_mfma_f32_16x16x32_bf16 v[110:113], v[146:149], v[202:205], v[110:113]
	s_waitcnt lgkmcnt(0)
	v_mfma_f32_16x16x32_bf16 v[106:109], v[138:141], v[210:213], v[106:109]
	v_mfma_f32_16x16x32_bf16 v[102:105], v[146:149], v[210:213], v[102:105]
	s_setprio 0
	s_setprio 1
	v_mfma_f32_16x16x32_bf16 v[66:69], v[158:161], v[174:177], v[66:69]
	v_mfma_f32_16x16x32_bf16 v[62:65], v[166:169], v[174:177], v[62:65]
	v_mfma_f32_16x16x32_bf16 v[58:61], v[158:161], v[182:185], v[58:61]
	v_mfma_f32_16x16x32_bf16 v[54:57], v[166:169], v[182:185], v[54:57]
	v_mfma_f32_16x16x32_bf16 v[50:53], v[158:161], v[190:193], v[50:53]
	v_mfma_f32_16x16x32_bf16 v[46:49], v[166:169], v[190:193], v[46:49]
	v_mfma_f32_16x16x32_bf16 v[42:45], v[158:161], v[206:209], v[42:45]
	v_mfma_f32_16x16x32_bf16 v[38:41], v[166:169], v[206:209], v[38:41]
	v_mfma_f32_16x16x32_bf16 v[66:69], v[162:165], v[178:181], v[66:69]
	v_mfma_f32_16x16x32_bf16 v[62:65], v[248:251], v[178:181], v[62:65]
	v_mfma_f32_16x16x32_bf16 v[58:61], v[162:165], v[186:189], v[58:61]
	v_mfma_f32_16x16x32_bf16 v[54:57], v[248:251], v[186:189], v[54:57]
	v_mfma_f32_16x16x32_bf16 v[50:53], v[162:165], v[202:205], v[50:53]
	v_mfma_f32_16x16x32_bf16 v[46:49], v[248:251], v[202:205], v[46:49]
	v_mfma_f32_16x16x32_bf16 v[42:45], v[162:165], v[210:213], v[42:45]
	s_setprio 2
	s_barrier
; #define PG8_STAGE(bufoff, gbase, voff) do { _Pragma("unroll") for (int _i = 0; _i < 2; ++_i) \
;         asm volatile("s_mov_b32 m0, %2\n\ts_nop 0\n\tglobal_load_lds_dwordx4 %0, %1" :: "v"((voff)[_i]), "s"((const char*)(gbase)), "s"(ldsbase + (unsigned)(bufoff) + ldsw + (unsigned)_i * 8192u) : "memory", "m0"); } while (0)
; #define PG8_LDA(dst, b, h) do { _Pragma("unroll") for (int m = 0; m < 4; ++m) _Pragma("unroll") for (int k = 0; k < 2; ++k) dst[m][k] = *(const PG8_LAS bf16x8*)(lds + PG8_SA(b, h) + aoff + m * 2048 + k * 1024); } while (0)
; #define PG8_MMA(ai, bj, At, Bt) do { __builtin_amdgcn_s_setprio(1); _Pragma("unroll") for (int m = 0; m < 4; ++m) _Pragma("unroll") for (int n = 0; n < 2; ++n) _Pragma("unroll") for (int k = 0; k < 2; ++k) \
;         acc[ai][bj][m][n] = __builtin_amdgcn_mfma_f32_16x16x32_bf16(Bt[n][k], At[m][k], acc[ai][bj][m][n], 0, 0, 0); __builtin_amdgcn_s_setprio(0); } while (0)
; #define PG8_WAIT_V(n) asm volatile("s_waitcnt vmcnt(" #n ")" ::: "memory")
; #define PG8_WAIT_L(n) asm volatile("s_waitcnt lgkmcnt(" #n ")" ::: "memory")
; #define PG8_BAR __builtin_amdgcn_s_barrier()
; #define PG8_SCHED __builtin_amdgcn_sched_barrier(0)
; template <class Epi, class Sched, bool ALIGN_EPI = false, bool SP2 = false>
; __device__ __forceinline__ void gemm_phase(PG8_LAS unsigned char* lds, const Gemm g, const Sched& S, const Epi& E) {
;     ...
;             if constexpr (epi_has_mid<Epi>::value) { if (t == Epi::MID_T) E.mid(acc, cur, wr, wc, fr, fq); }
;     ...
;             PG8_LDA(At, 1, 1); PG8_STAGE(PG8_SB(1, 0), b3, voffB); PG8_STAGE(PG8_SB(1, 1), b3 + hstep, voffB); PG8_STAGE(PG8_SA(1, 0), a3, voffA);
;             PG8_WAIT_V(8); PG8_WAIT_L(0); PG8_BAR; PG8_MMA(1, 0, At, B0); PG8_MMA(1, 1, At, B1); PG8_BAR; PG8_SCHED;
	v_mfma_f32_16x16x32_bf16 v[38:41], v[248:251], v[210:213], v[38:41]
	s_setprio 0
	ds_read_b128 v[174:177], v200 offset:49152
	ds_read_b128 v[178:181], v200 offset:50176
	ds_read_b128 v[182:185], v200 offset:51200
	ds_read_b128 v[186:189], v200 offset:52224
	ds_read_b128 v[190:193], v200 offset:53248
	ds_read_b128 v[202:205], v200 offset:54272
	ds_read_b128 v[206:209], v200 offset:55296
	ds_read_b128 v[252:255], v200 offset:56320
	s_mov_b32 m0, s78
	s_nop 0
	global_load_lds_dwordx4 v194, s[54:55]
	s_add_u32 s42, s46, 0x100080
	s_mov_b32 m0, s79
	s_nop 0
	global_load_lds_dwordx4 v196, s[54:55]
	s_addc_u32 s43, s47, 0
	s_mov_b32 m0, s83
	s_nop 0
	global_load_lds_dwordx4 v194, s[42:43]
	s_nop 0
	s_mov_b32 m0, s84
	s_nop 0
	global_load_lds_dwordx4 v196, s[42:43]
	s_nop 0
	s_mov_b32 m0, s80
	s_nop 0
	global_load_lds_dwordx4 v1, s[50:51]
	s_nop 0
	s_mov_b32 m0, s82
	s_nop 0
	global_load_lds_dwordx4 v195, s[50:51]
	s_waitcnt vmcnt(8)
	s_waitcnt lgkmcnt(0)
	v_mfma_f32_16x16x32_bf16 v[98:101], v[134:137], v[174:177], v[98:101]
	s_barrier
	s_setprio 1
	s_waitcnt lgkmcnt(7)
	v_mfma_f32_16x16x32_bf16 v[94:97], v[142:145], v[174:177], v[94:97]
	s_waitcnt lgkmcnt(5)
	v_mfma_f32_16x16x32_bf16 v[90:93], v[134:137], v[182:185], v[90:93]
	v_mfma_f32_16x16x32_bf16 v[86:89], v[142:145], v[182:185], v[86:89]
	s_waitcnt lgkmcnt(3)
	v_mfma_f32_16x16x32_bf16 v[82:85], v[134:137], v[190:193], v[82:85]
	v_mfma_f32_16x16x32_bf16 v[78:81], v[142:145], v[190:193], v[78:81]
	s_waitcnt lgkmcnt(1)
	v_mfma_f32_16x16x32_bf16 v[74:77], v[134:137], v[206:209], v[74:77]
	v_mfma_f32_16x16x32_bf16 v[70:73], v[142:145], v[206:209], v[70:73]
	v_mfma_f32_16x16x32_bf16 v[98:101], v[138:141], v[178:181], v[98:101]
	v_mfma_f32_16x16x32_bf16 v[94:97], v[146:149], v[178:181], v[94:97]
	v_mfma_f32_16x16x32_bf16 v[90:93], v[138:141], v[186:189], v[90:93]
	v_mfma_f32_16x16x32_bf16 v[86:89], v[146:149], v[186:189], v[86:89]
	v_mfma_f32_16x16x32_bf16 v[82:85], v[138:141], v[202:205], v[82:85]
	v_mfma_f32_16x16x32_bf16 v[78:81], v[146:149], v[202:205], v[78:81]
	s_waitcnt lgkmcnt(0)
	v_mfma_f32_16x16x32_bf16 v[74:77], v[138:141], v[252:255], v[74:77]
	v_mfma_f32_16x16x32_bf16 v[70:73], v[146:149], v[252:255], v[70:73]
	s_setprio 0
	s_setprio 1
	v_mfma_f32_16x16x32_bf16 v[34:37], v[158:161], v[174:177], v[34:37]
	v_mfma_f32_16x16x32_bf16 v[30:33], v[166:169], v[174:177], v[30:33]
	v_mfma_f32_16x16x32_bf16 v[26:29], v[158:161], v[182:185], v[26:29]
	v_mfma_f32_16x16x32_bf16 v[22:25], v[166:169], v[182:185], v[22:25]
	v_mfma_f32_16x16x32_bf16 v[18:21], v[158:161], v[190:193], v[18:21]
	v_mfma_f32_16x16x32_bf16 v[14:17], v[166:169], v[190:193], v[14:17]
	v_mfma_f32_16x16x32_bf16 v[8:11], v[158:161], v[206:209], v[10:13]
	v_mfma_f32_16x16x32_bf16 v[4:7], v[166:169], v[206:209], v[4:7]
	v_mfma_f32_16x16x32_bf16 v[34:37], v[162:165], v[178:181], v[34:37]
	v_mfma_f32_16x16x32_bf16 v[30:33], v[248:251], v[178:181], v[30:33]
	v_mfma_f32_16x16x32_bf16 v[26:29], v[162:165], v[186:189], v[26:29]
	v_mfma_f32_16x16x32_bf16 v[22:25], v[248:251], v[186:189], v[22:25]
	v_mfma_f32_16x16x32_bf16 v[18:21], v[162:165], v[202:205], v[18:21]
	v_mfma_f32_16x16x32_bf16 v[14:17], v[248:251], v[202:205], v[14:17]
	v_mfma_f32_16x16x32_bf16 v[10:13], v[162:165], v[252:255], v[8:11]
	s_setprio 2
	s_barrier
	v_mfma_f32_16x16x32_bf16 v[6:9], v[248:251], v[252:255], v[4:7]
	s_setprio 0
	s_add_i32 s92, s92, 2
	s_add_u32 s90, s90, 0x100
	s_addc_u32 s91, s91, 0
	s_cmp_gt_u32 s92, 61
	s_cbranch_scc1 .LBB0_622
	s_mov_b64 s[42:43], s[44:45]
	s_cmp_lg_u32 s92, 30
	s_cbranch_scc0 .LBB0_619
	s_branch .LBB0_620

; #define PG8_STAGE(bufoff, gbase, voff) do { _Pragma("unroll") for (int _i = 0; _i < 2; ++_i) \
;         asm volatile("s_mov_b32 m0, %2\n\ts_nop 0\n\tglobal_load_lds_dwordx4 %0, %1" :: "v"((voff)[_i]), "s"((const char*)(gbase)), "s"(ldsbase + (unsigned)(bufoff) + ldsw + (unsigned)_i * 8192u) : "memory", "m0"); } while (0)
; #define PG8_LDA(dst, b, h) do { _Pragma("unroll") for (int m = 0; m < 4; ++m) _Pragma("unroll") for (int k = 0; k < 2; ++k) dst[m][k] = *(const PG8_LAS bf16x8*)(lds + PG8_SA(b, h) + aoff + m * 2048 + k * 1024); } while (0)
; #define PG8_LDB(dst, b, h) do { _Pragma("unroll") for (int n = 0; n < 2; ++n) _Pragma("unroll") for (int k = 0; k < 2; ++k) dst[n][k] = *(const PG8_LAS bf16x8*)(lds + PG8_SB(b, h) + boff + n * 2048 + k * 1024); } while (0)
; #define PG8_MMA(ai, bj, At, Bt) do { __builtin_amdgcn_s_setprio(1); _Pragma("unroll") for (int m = 0; m < 4; ++m) _Pragma("unroll") for (int n = 0; n < 2; ++n) _Pragma("unroll") for (int k = 0; k < 2; ++k) \
;         acc[ai][bj][m][n] = __builtin_amdgcn_mfma_f32_16x16x32_bf16(Bt[n][k], At[m][k], acc[ai][bj][m][n], 0, 0, 0); __builtin_amdgcn_s_setprio(0); } while (0)
; template <class Epi, class Sched, bool ALIGN_EPI = false, bool SP2 = false>
; __device__ __forceinline__ void gemm_phase(PG8_LAS unsigned char* lds, const Gemm g, const Sched& S, const Epi& E) {
;     ...
;             const bool last = (t == nt - 2);
;             const char* a1 = cA + (size_t)(t + 1) * kstep;
;             const char* a2 = last ? nA : cA + (size_t)(t + 2) * kstep; const char* b2 = last ? nB : cB + (size_t)(t + 2) * kstep;
;             const char* a3 = a2 + kstep; const char* b3 = b2 + kstep;
;             if (last && has_next) S.a_ready(nxt);
;             if constexpr (epi_has_mid<Epi>::value) { if (t == Epi::MID_T) E.mid(acc, cur, wr, wc, fr, fq); }
;             if constexpr (SP2) {
;             PG8_LDB(B0, 0, 0); PG8_LDB(B1, 0, 1); PG8_SCHED; PG8_LDA(At, 0, 0); PG8_STAGE(PG8_SA(1, 1), a1 + hstep, voffA);
;             PG8_WAIT_V(8); PG8_WAIT_L(0); PG8_BAR; PG8_MMA(0, 0, At, B0); PG8_MMA(0, 1, At, B1); PG8_BAR; PG8_SCHED;
;             PG8_LDA(At, 0, 1); PG8_STAGE(PG8_SB(0, 0), b2, voffB); PG8_STAGE(PG8_SB(0, 1), b2 + hstep, voffB); PG8_STAGE(PG8_SA(0, 0), a2, voffA);
;             PG8_WAIT_V(8); PG8_WAIT_L(0); PG8_BAR; PG8_MMA(1, 0, At, B0); PG8_MMA(1, 1, At, B1); PG8_BAR; PG8_SCHED;
.LBB0_698:
	ds_read_b128 v[134:137], v145
	ds_read_b128 v[152:155], v145 offset:1024
	ds_read_b128 v[156:159], v145 offset:2048
	ds_read_b128 v[160:163], v145 offset:3072
	ds_read_b128 v[164:167], v146
	ds_read_b128 v[168:171], v146 offset:1024
	ds_read_b128 v[172:175], v146 offset:2048
	ds_read_b128 v[176:179], v146 offset:3072
	s_cmp_eq_u32 s69, 60
	s_cselect_b32 s48, s41, s53
	s_cselect_b32 s49, s19, s58
	s_cselect_b32 s46, s52, s59
	s_cselect_b32 s47, s17, s68
	s_add_u32 s44, s48, 0x80
	s_addc_u32 s45, s49, 0
	ds_read_b128 v[180:183], v147
	ds_read_b128 v[184:187], v147 offset:1024
	ds_read_b128 v[188:191], v147 offset:2048
	ds_read_b128 v[192:195], v147 offset:3072
	ds_read_b128 v[196:199], v147 offset:4096
	ds_read_b128 v[200:203], v147 offset:5120
	ds_read_b128 v[204:207], v147 offset:6144
	ds_read_b128 v[208:211], v147 offset:7168
	s_mov_b32 m0, s67
	s_nop 0
	global_load_lds_dwordx4 v1, s[42:43]
	s_nop 0
	s_mov_b32 m0, s74
	s_nop 0
	global_load_lds_dwordx4 v141, s[42:43]
	s_waitcnt vmcnt(8)
	s_waitcnt lgkmcnt(0)
	v_mfma_f32_16x16x32_bf16 v[126:129], v[134:137], v[180:183], v[126:129]
	s_barrier
	s_setprio 1
	s_waitcnt lgkmcnt(7)
	v_mfma_f32_16x16x32_bf16 v[122:125], v[156:159], v[180:183], v[122:125]
	s_waitcnt lgkmcnt(5)
	v_mfma_f32_16x16x32_bf16 v[110:113], v[134:137], v[188:191], v[110:113]
	v_mfma_f32_16x16x32_bf16 v[106:109], v[156:159], v[188:191], v[106:109]
	s_waitcnt lgkmcnt(3)
	v_mfma_f32_16x16x32_bf16 v[94:97], v[134:137], v[196:199], v[94:97]
	v_mfma_f32_16x16x32_bf16 v[90:93], v[156:159], v[196:199], v[90:93]
	s_waitcnt lgkmcnt(1)
	v_mfma_f32_16x16x32_bf16 v[78:81], v[134:137], v[204:207], v[78:81]
	v_mfma_f32_16x16x32_bf16 v[74:77], v[156:159], v[204:207], v[74:77]
	v_mfma_f32_16x16x32_bf16 v[126:129], v[152:155], v[184:187], v[126:129]
	v_mfma_f32_16x16x32_bf16 v[122:125], v[160:163], v[184:187], v[122:125]
	v_mfma_f32_16x16x32_bf16 v[110:113], v[152:155], v[192:195], v[110:113]
	v_mfma_f32_16x16x32_bf16 v[106:109], v[160:163], v[192:195], v[106:109]
	v_mfma_f32_16x16x32_bf16 v[94:97], v[152:155], v[200:203], v[94:97]
	v_mfma_f32_16x16x32_bf16 v[90:93], v[160:163], v[200:203], v[90:93]
	s_waitcnt lgkmcnt(0)
	v_mfma_f32_16x16x32_bf16 v[78:81], v[152:155], v[208:211], v[78:81]
	v_mfma_f32_16x16x32_bf16 v[74:77], v[160:163], v[208:211], v[74:77]
	s_setprio 0
	s_setprio 1
	v_mfma_f32_16x16x32_bf16 v[118:121], v[164:167], v[180:183], v[118:121]
	v_mfma_f32_16x16x32_bf16 v[114:117], v[172:175], v[180:183], v[114:117]
	v_mfma_f32_16x16x32_bf16 v[102:105], v[164:167], v[188:191], v[102:105]
	v_mfma_f32_16x16x32_bf16 v[98:101], v[172:175], v[188:191], v[98:101]
	v_mfma_f32_16x16x32_bf16 v[86:89], v[164:167], v[196:199], v[86:89]
	v_mfma_f32_16x16x32_bf16 v[82:85], v[172:175], v[196:199], v[82:85]
	v_mfma_f32_16x16x32_bf16 v[70:73], v[164:167], v[204:207], v[70:73]
	v_mfma_f32_16x16x32_bf16 v[66:69], v[172:175], v[204:207], v[66:69]
	v_mfma_f32_16x16x32_bf16 v[118:121], v[168:171], v[184:187], v[118:121]
	v_mfma_f32_16x16x32_bf16 v[114:117], v[176:179], v[184:187], v[114:117]
	v_mfma_f32_16x16x32_bf16 v[102:105], v[168:171], v[192:195], v[102:105]
	v_mfma_f32_16x16x32_bf16 v[98:101], v[176:179], v[192:195], v[98:101]
	v_mfma_f32_16x16x32_bf16 v[86:89], v[168:171], v[200:203], v[86:89]
	v_mfma_f32_16x16x32_bf16 v[82:85], v[176:179], v[200:203], v[82:85]
	v_mfma_f32_16x16x32_bf16 v[70:73], v[168:171], v[208:211], v[70:73]
	s_setprio 2
	s_barrier
	v_mfma_f32_16x16x32_bf16 v[66:69], v[176:179], v[208:211], v[66:69]
	s_setprio 0
	ds_read_b128 v[180:183], v147 offset:16384
	ds_read_b128 v[184:187], v147 offset:17408
	ds_read_b128 v[188:191], v147 offset:18432
	ds_read_b128 v[192:195], v147 offset:19456
	ds_read_b128 v[196:199], v147 offset:20480
	ds_read_b128 v[200:203], v147 offset:21504
	ds_read_b128 v[204:207], v147 offset:22528
	ds_read_b128 v[252:255], v147 offset:23552
	s_mov_b32 m0, s35
	s_nop 0
	global_load_lds_dwordx4 v140, s[46:47]
	s_add_u32 s70, s46, 0x100000
	s_mov_b32 m0, s50
	s_nop 0
	global_load_lds_dwordx4 v142, s[46:47]
	s_addc_u32 s71, s47, 0
	s_mov_b32 m0, s51
	s_nop 0
	global_load_lds_dwordx4 v140, s[70:71]
	s_nop 0
	s_mov_b32 m0, s54
	s_nop 0
	global_load_lds_dwordx4 v142, s[70:71]
	s_nop 0
	s_mov_b32 m0, s3
	s_nop 0
	global_load_lds_dwordx4 v1, s[48:49]
	s_nop 0
	s_mov_b32 m0, s55
	s_nop 0
	global_load_lds_dwordx4 v141, s[48:49]
	s_waitcnt vmcnt(8)
	s_waitcnt lgkmcnt(0)
	v_mfma_f32_16x16x32_bf16 v[62:65], v[134:137], v[180:183], v[62:65]
	s_barrier
	s_setprio 1
	s_waitcnt lgkmcnt(7)
	v_mfma_f32_16x16x32_bf16 v[58:61], v[156:159], v[180:183], v[58:61]
	s_waitcnt lgkmcnt(5)
	v_mfma_f32_16x16x32_bf16 v[46:49], v[134:137], v[188:191], v[46:49]
	v_mfma_f32_16x16x32_bf16 v[42:45], v[156:159], v[188:191], v[42:45]
	s_waitcnt lgkmcnt(3)
	v_mfma_f32_16x16x32_bf16 v[30:33], v[134:137], v[196:199], v[30:33]
	v_mfma_f32_16x16x32_bf16 v[26:29], v[156:159], v[196:199], v[26:29]
	s_waitcnt lgkmcnt(1)
	v_mfma_f32_16x16x32_bf16 v[14:17], v[134:137], v[204:207], v[14:17]
	v_mfma_f32_16x16x32_bf16 v[10:13], v[156:159], v[204:207], v[10:13]
	v_mfma_f32_16x16x32_bf16 v[62:65], v[152:155], v[184:187], v[62:65]
	v_mfma_f32_16x16x32_bf16 v[58:61], v[160:163], v[184:187], v[58:61]
	v_mfma_f32_16x16x32_bf16 v[46:49], v[152:155], v[192:195], v[46:49]
	v_mfma_f32_16x16x32_bf16 v[42:45], v[160:163], v[192:195], v[42:45]
	v_mfma_f32_16x16x32_bf16 v[30:33], v[152:155], v[200:203], v[30:33]
	v_mfma_f32_16x16x32_bf16 v[26:29], v[160:163], v[200:203], v[26:29]
	s_waitcnt lgkmcnt(0)
	v_mfma_f32_16x16x32_bf16 v[14:17], v[152:155], v[252:255], v[14:17]
	v_mfma_f32_16x16x32_bf16 v[10:13], v[160:163], v[252:255], v[10:13]
	s_setprio 0
	s_setprio 1
	v_mfma_f32_16x16x32_bf16 v[54:57], v[164:167], v[180:183], v[54:57]
	v_mfma_f32_16x16x32_bf16 v[50:53], v[172:175], v[180:183], v[50:53]
	v_mfma_f32_16x16x32_bf16 v[38:41], v[164:167], v[188:191], v[38:41]
	v_mfma_f32_16x16x32_bf16 v[34:37], v[172:175], v[188:191], v[34:37]
	v_mfma_f32_16x16x32_bf16 v[22:25], v[164:167], v[196:199], v[22:25]
	v_mfma_f32_16x16x32_bf16 v[18:21], v[172:175], v[196:199], v[18:21]
	v_mfma_f32_16x16x32_bf16 v[6:9], v[164:167], v[204:207], v[6:9]
	v_mfma_f32_16x16x32_bf16 v[2:5], v[172:175], v[204:207], v[2:5]
	v_mfma_f32_16x16x32_bf16 v[54:57], v[168:171], v[184:187], v[54:57]
	v_mfma_f32_16x16x32_bf16 v[50:53], v[176:179], v[184:187], v[50:53]
	v_mfma_f32_16x16x32_bf16 v[38:41], v[168:171], v[192:195], v[38:41]
	v_mfma_f32_16x16x32_bf16 v[34:37], v[176:179], v[192:195], v[34:37]
	v_mfma_f32_16x16x32_bf16 v[22:25], v[168:171], v[200:203], v[22:25]
	v_mfma_f32_16x16x32_bf16 v[18:21], v[176:179], v[200:203], v[18:21]
	v_mfma_f32_16x16x32_bf16 v[6:9], v[168:171], v[252:255], v[6:9]
	s_setprio 2
	s_barrier
; #define PG8_STAGE(bufoff, gbase, voff) do { _Pragma("unroll") for (int _i = 0; _i < 2; ++_i) \
;         asm volatile("s_mov_b32 m0, %2\n\ts_nop 0\n\tglobal_load_lds_dwordx4 %0, %1" :: "v"((voff)[_i]), "s"((const char*)(gbase)), "s"(ldsbase + (unsigned)(bufoff) + ldsw + (unsigned)_i * 8192u) : "memory", "m0"); } while (0)
; #define PG8_LDA(dst, b, h) do { _Pragma("unroll") for (int m = 0; m < 4; ++m) _Pragma("unroll") for (int k = 0; k < 2; ++k) dst[m][k] = *(const PG8_LAS bf16x8*)(lds + PG8_SA(b, h) + aoff + m * 2048 + k * 1024); } while (0)
; #define PG8_LDB(dst, b, h) do { _Pragma("unroll") for (int n = 0; n < 2; ++n) _Pragma("unroll") for (int k = 0; k < 2; ++k) dst[n][k] = *(const PG8_LAS bf16x8*)(lds + PG8_SB(b, h) + boff + n * 2048 + k * 1024); } while (0)
; #define PG8_MMA(ai, bj, At, Bt) do { __builtin_amdgcn_s_setprio(1); _Pragma("unroll") for (int m = 0; m < 4; ++m) _Pragma("unroll") for (int n = 0; n < 2; ++n) _Pragma("unroll") for (int k = 0; k < 2; ++k) \
;         acc[ai][bj][m][n] = __builtin_amdgcn_mfma_f32_16x16x32_bf16(Bt[n][k], At[m][k], acc[ai][bj][m][n], 0, 0, 0); __builtin_amdgcn_s_setprio(0); } while (0)
; #define PG8_WAIT_V(n) asm volatile("s_waitcnt vmcnt(" #n ")" ::: "memory")
; #define PG8_WAIT_L(n) asm volatile("s_waitcnt lgkmcnt(" #n ")" ::: "memory")
; #define PG8_BAR __builtin_amdgcn_s_barrier()
; #define PG8_SCHED __builtin_amdgcn_sched_barrier(0)
; template <class Epi, class Sched, bool ALIGN_EPI = false, bool SP2 = false>
; __device__ __forceinline__ void gemm_phase(PG8_LAS unsigned char* lds, const Gemm g, const Sched& S, const Epi& E) {
;     ...
;             PG8_LDB(B0, 1, 0); PG8_LDB(B1, 1, 1); PG8_SCHED; PG8_LDA(At, 1, 0); PG8_STAGE(PG8_SA(0, 1), a2 + hstep, voffA);
;             PG8_WAIT_V(8); PG8_WAIT_L(0); PG8_BAR; PG8_MMA(0, 0, At, B0); PG8_MMA(0, 1, At, B1); PG8_BAR; PG8_SCHED;
	v_mfma_f32_16x16x32_bf16 v[2:5], v[176:179], v[252:255], v[2:5]
	s_setprio 0
	ds_read_b128 v[134:137], v148
	ds_read_b128 v[152:155], v148 offset:1024
	ds_read_b128 v[156:159], v148 offset:2048
	ds_read_b128 v[160:163], v148 offset:3072
	ds_read_b128 v[164:167], v149
	ds_read_b128 v[168:171], v149 offset:1024
	ds_read_b128 v[172:175], v149 offset:2048
	ds_read_b128 v[248:251], v149 offset:3072
	ds_read_b128 v[180:183], v147 offset:32768
	ds_read_b128 v[184:187], v147 offset:33792
	ds_read_b128 v[188:191], v147 offset:34816
	ds_read_b128 v[192:195], v147 offset:35840
	ds_read_b128 v[196:199], v147 offset:36864
	ds_read_b128 v[200:203], v147 offset:37888
	ds_read_b128 v[204:207], v147 offset:38912
	ds_read_b128 v[208:211], v147 offset:39936
	s_add_u32 s48, s48, 0x100000
	s_addc_u32 s49, s49, 0
	s_mov_b32 m0, s56
	s_nop 0
	global_load_lds_dwordx4 v1, s[48:49]
	s_nop 0
	s_mov_b32 m0, s57
	s_nop 0
	global_load_lds_dwordx4 v141, s[48:49]
	s_waitcnt vmcnt(8)
	s_waitcnt lgkmcnt(0)
	v_mfma_f32_16x16x32_bf16 v[126:129], v[134:137], v[180:183], v[126:129]
	s_barrier
	s_setprio 1
	s_waitcnt lgkmcnt(7)
	v_mfma_f32_16x16x32_bf16 v[122:125], v[156:159], v[180:183], v[122:125]
	s_waitcnt lgkmcnt(5)
	v_mfma_f32_16x16x32_bf16 v[110:113], v[134:137], v[188:191], v[110:113]
	v_mfma_f32_16x16x32_bf16 v[106:109], v[156:159], v[188:191], v[106:109]
	s_waitcnt lgkmcnt(3)
	v_mfma_f32_16x16x32_bf16 v[94:97], v[134:137], v[196:199], v[94:97]
	v_mfma_f32_16x16x32_bf16 v[90:93], v[156:159], v[196:199], v[90:93]
	s_waitcnt lgkmcnt(1)
	v_mfma_f32_16x16x32_bf16 v[78:81], v[134:137], v[204:207], v[78:81]
	v_mfma_f32_16x16x32_bf16 v[74:77], v[156:159], v[204:207], v[74:77]
	v_mfma_f32_16x16x32_bf16 v[126:129], v[152:155], v[184:187], v[126:129]
	v_mfma_f32_16x16x32_bf16 v[122:125], v[160:163], v[184:187], v[122:125]
	v_mfma_f32_16x16x32_bf16 v[110:113], v[152:155], v[192:195], v[110:113]
	v_mfma_f32_16x16x32_bf16 v[106:109], v[160:163], v[192:195], v[106:109]
	v_mfma_f32_16x16x32_bf16 v[94:97], v[152:155], v[200:203], v[94:97]
	v_mfma_f32_16x16x32_bf16 v[90:93], v[160:163], v[200:203], v[90:93]
	s_waitcnt lgkmcnt(0)
	v_mfma_f32_16x16x32_bf16 v[78:81], v[152:155], v[208:211], v[78:81]
	v_mfma_f32_16x16x32_bf16 v[74:77], v[160:163], v[208:211], v[74:77]
	s_setprio 0
	s_setprio 1
	v_mfma_f32_16x16x32_bf16 v[118:121], v[164:167], v[180:183], v[118:121]
	v_mfma_f32_16x16x32_bf16 v[114:117], v[172:175], v[180:183], v[114:117]
	v_mfma_f32_16x16x32_bf16 v[102:105], v[164:167], v[188:191], v[102:105]
	v_mfma_f32_16x16x32_bf16 v[98:101], v[172:175], v[188:191], v[98:101]
	v_mfma_f32_16x16x32_bf16 v[86:89], v[164:167], v[196:199], v[86:89]
	v_mfma_f32_16x16x32_bf16 v[82:85], v[172:175], v[196:199], v[82:85]
	v_mfma_f32_16x16x32_bf16 v[70:73], v[164:167], v[204:207], v[70:73]
	v_mfma_f32_16x16x32_bf16 v[66:69], v[172:175], v[204:207], v[66:69]
	v_mfma_f32_16x16x32_bf16 v[118:121], v[168:171], v[184:187], v[118:121]
	v_mfma_f32_16x16x32_bf16 v[114:117], v[248:251], v[184:187], v[114:117]
	v_mfma_f32_16x16x32_bf16 v[102:105], v[168:171], v[192:195], v[102:105]
	v_mfma_f32_16x16x32_bf16 v[98:101], v[248:251], v[192:195], v[98:101]
	v_mfma_f32_16x16x32_bf16 v[86:89], v[168:171], v[200:203], v[86:89]
	v_mfma_f32_16x16x32_bf16 v[82:85], v[248:251], v[200:203], v[82:85]
	v_mfma_f32_16x16x32_bf16 v[70:73], v[168:171], v[208:211], v[70:73]
	s_setprio 2
	s_barrier
; #define PG8_STAGE(bufoff, gbase, voff) do { _Pragma("unroll") for (int _i = 0; _i < 2; ++_i) \
;         asm volatile("s_mov_b32 m0, %2\n\ts_nop 0\n\tglobal_load_lds_dwordx4 %0, %1" :: "v"((voff)[_i]), "s"((const char*)(gbase)), "s"(ldsbase + (unsigned)(bufoff) + ldsw + (unsigned)_i * 8192u) : "memory", "m0"); } while (0)
; #define PG8_LDA(dst, b, h) do { _Pragma("unroll") for (int m = 0; m < 4; ++m) _Pragma("unroll") for (int k = 0; k < 2; ++k) dst[m][k] = *(const PG8_LAS bf16x8*)(lds + PG8_SA(b, h) + aoff + m * 2048 + k * 1024); } while (0)
; #define PG8_MMA(ai, bj, At, Bt) do { __builtin_amdgcn_s_setprio(1); _Pragma("unroll") for (int m = 0; m < 4; ++m) _Pragma("unroll") for (int n = 0; n < 2; ++n) _Pragma("unroll") for (int k = 0; k < 2; ++k) \
;         acc[ai][bj][m][n] = __builtin_amdgcn_mfma_f32_16x16x32_bf16(Bt[n][k], At[m][k], acc[ai][bj][m][n], 0, 0, 0); __builtin_amdgcn_s_setprio(0); } while (0)
; #define PG8_WAIT_V(n) asm volatile("s_waitcnt vmcnt(" #n ")" ::: "memory")
; #define PG8_WAIT_L(n) asm volatile("s_waitcnt lgkmcnt(" #n ")" ::: "memory")
; #define PG8_BAR __builtin_amdgcn_s_barrier()
; #define PG8_SCHED __builtin_amdgcn_sched_barrier(0)
; template <class Epi, class Sched, bool ALIGN_EPI = false, bool SP2 = false>
; __device__ __forceinline__ void gemm_phase(PG8_LAS unsigned char* lds, const Gemm g, const Sched& S, const Epi& E) {
;     ...
;             PG8_LDA(At, 1, 1); PG8_STAGE(PG8_SB(1, 0), b3, voffB); PG8_STAGE(PG8_SB(1, 1), b3 + hstep, voffB); PG8_STAGE(PG8_SA(1, 0), a3, voffA);
;             PG8_WAIT_V(8); PG8_WAIT_L(0); PG8_BAR; PG8_MMA(1, 0, At, B0); PG8_MMA(1, 1, At, B1); PG8_BAR; PG8_SCHED;
;     ...
;         if constexpr (ALIGN_EPI) { if (wr == 0) PG8_BAR; }
	v_mfma_f32_16x16x32_bf16 v[66:69], v[248:251], v[208:211], v[66:69]
	s_setprio 0
	ds_read_b128 v[180:183], v147 offset:49152
	ds_read_b128 v[184:187], v147 offset:50176
	ds_read_b128 v[188:191], v147 offset:51200
	ds_read_b128 v[192:195], v147 offset:52224
	ds_read_b128 v[196:199], v147 offset:53248
	ds_read_b128 v[200:203], v147 offset:54272
	ds_read_b128 v[204:207], v147 offset:55296
	ds_read_b128 v[252:255], v147 offset:56320
	s_add_u32 s48, s46, 0x80
	s_addc_u32 s49, s47, 0
	s_mov_b32 m0, s61
	s_nop 0
	global_load_lds_dwordx4 v140, s[48:49]
	s_add_u32 s46, s46, 0x100080
	s_mov_b32 m0, s62
	s_nop 0
	global_load_lds_dwordx4 v142, s[48:49]
	s_addc_u32 s47, s47, 0
	s_mov_b32 m0, s65
	s_nop 0
	global_load_lds_dwordx4 v140, s[46:47]
	s_nop 0
	s_mov_b32 m0, s66
	s_nop 0
	global_load_lds_dwordx4 v142, s[46:47]
	s_nop 0
	s_mov_b32 m0, s63
	s_nop 0
	global_load_lds_dwordx4 v1, s[44:45]
	s_nop 0
	s_mov_b32 m0, s64
	s_nop 0
	global_load_lds_dwordx4 v141, s[44:45]
	s_waitcnt vmcnt(8)
	s_waitcnt lgkmcnt(0)
	v_mfma_f32_16x16x32_bf16 v[62:65], v[134:137], v[180:183], v[62:65]
	s_barrier
	s_setprio 1
	s_waitcnt lgkmcnt(7)
	v_mfma_f32_16x16x32_bf16 v[58:61], v[156:159], v[180:183], v[58:61]
	s_waitcnt lgkmcnt(5)
	v_mfma_f32_16x16x32_bf16 v[46:49], v[134:137], v[188:191], v[46:49]
	v_mfma_f32_16x16x32_bf16 v[42:45], v[156:159], v[188:191], v[42:45]
	s_waitcnt lgkmcnt(3)
	v_mfma_f32_16x16x32_bf16 v[30:33], v[134:137], v[196:199], v[30:33]
	v_mfma_f32_16x16x32_bf16 v[26:29], v[156:159], v[196:199], v[26:29]
	s_waitcnt lgkmcnt(1)
	v_mfma_f32_16x16x32_bf16 v[14:17], v[134:137], v[204:207], v[14:17]
	v_mfma_f32_16x16x32_bf16 v[10:13], v[156:159], v[204:207], v[10:13]
	v_mfma_f32_16x16x32_bf16 v[62:65], v[152:155], v[184:187], v[62:65]
	v_mfma_f32_16x16x32_bf16 v[58:61], v[160:163], v[184:187], v[58:61]
	v_mfma_f32_16x16x32_bf16 v[46:49], v[152:155], v[192:195], v[46:49]
	v_mfma_f32_16x16x32_bf16 v[42:45], v[160:163], v[192:195], v[42:45]
	v_mfma_f32_16x16x32_bf16 v[30:33], v[152:155], v[200:203], v[30:33]
	v_mfma_f32_16x16x32_bf16 v[26:29], v[160:163], v[200:203], v[26:29]
	s_waitcnt lgkmcnt(0)
	v_mfma_f32_16x16x32_bf16 v[14:17], v[152:155], v[252:255], v[14:17]
	v_mfma_f32_16x16x32_bf16 v[10:13], v[160:163], v[252:255], v[10:13]
	s_setprio 0
	s_setprio 1
	v_mfma_f32_16x16x32_bf16 v[54:57], v[164:167], v[180:183], v[54:57]
	v_mfma_f32_16x16x32_bf16 v[50:53], v[172:175], v[180:183], v[50:53]
	v_mfma_f32_16x16x32_bf16 v[38:41], v[164:167], v[188:191], v[38:41]
	v_mfma_f32_16x16x32_bf16 v[34:37], v[172:175], v[188:191], v[34:37]
	v_mfma_f32_16x16x32_bf16 v[22:25], v[164:167], v[196:199], v[22:25]
	v_mfma_f32_16x16x32_bf16 v[18:21], v[172:175], v[196:199], v[18:21]
	v_mfma_f32_16x16x32_bf16 v[6:9], v[164:167], v[204:207], v[6:9]
	v_mfma_f32_16x16x32_bf16 v[2:5], v[172:175], v[204:207], v[2:5]
	v_mfma_f32_16x16x32_bf16 v[54:57], v[168:171], v[184:187], v[54:57]
	v_mfma_f32_16x16x32_bf16 v[50:53], v[248:251], v[184:187], v[50:53]
	v_mfma_f32_16x16x32_bf16 v[38:41], v[168:171], v[192:195], v[38:41]
	v_mfma_f32_16x16x32_bf16 v[34:37], v[248:251], v[192:195], v[34:37]
	v_mfma_f32_16x16x32_bf16 v[22:25], v[168:171], v[200:203], v[22:25]
	v_mfma_f32_16x16x32_bf16 v[18:21], v[248:251], v[200:203], v[18:21]
	v_mfma_f32_16x16x32_bf16 v[6:9], v[168:171], v[252:255], v[6:9]
	s_setprio 2
	s_barrier
	v_mfma_f32_16x16x32_bf16 v[2:5], v[248:251], v[252:255], v[2:5]
	s_setprio 0
	s_add_i32 s69, s69, 2
	s_add_u32 s53, s53, 0x100
	s_addc_u32 s58, s58, 0
	s_add_u32 s59, s59, 0x100
	s_addc_u32 s68, s68, 0
	s_add_u32 s42, s42, 0x100
	s_addc_u32 s43, s43, 0
	s_cmp_gt_u32 s69, 61
	s_cbranch_scc0 .LBB0_698
	s_and_b64 vcc, exec, s[14:15]
	s_cbranch_vccz .LBB0_701
	s_barrier

; #define PG8_STAGE(bufoff, gbase, voff) do { _Pragma("unroll") for (int _i = 0; _i < 2; ++_i) \
;         asm volatile("s_mov_b32 m0, %2\n\ts_nop 0\n\tglobal_load_lds_dwordx4 %0, %1" :: "v"((voff)[_i]), "s"((const char*)(gbase)), "s"(ldsbase + (unsigned)(bufoff) + ldsw + (unsigned)_i * 8192u) : "memory", "m0"); } while (0)
; #define PG8_LDA(dst, b, h) do { _Pragma("unroll") for (int m = 0; m < 4; ++m) _Pragma("unroll") for (int k = 0; k < 2; ++k) dst[m][k] = *(const PG8_LAS bf16x8*)(lds + PG8_SA(b, h) + aoff + m * 2048 + k * 1024); } while (0)
; #define PG8_LDB(dst, b, h) do { _Pragma("unroll") for (int n = 0; n < 2; ++n) _Pragma("unroll") for (int k = 0; k < 2; ++k) dst[n][k] = *(const PG8_LAS bf16x8*)(lds + PG8_SB(b, h) + boff + n * 2048 + k * 1024); } while (0)
; #define PG8_MMA(ai, bj, At, Bt) do { __builtin_amdgcn_s_setprio(1); _Pragma("unroll") for (int m = 0; m < 4; ++m) _Pragma("unroll") for (int n = 0; n < 2; ++n) _Pragma("unroll") for (int k = 0; k < 2; ++k) \
;         acc[ai][bj][m][n] = __builtin_amdgcn_mfma_f32_16x16x32_bf16(Bt[n][k], At[m][k], acc[ai][bj][m][n], 0, 0, 0); __builtin_amdgcn_s_setprio(0); } while (0)
; template <class Epi, class Sched, bool ALIGN_EPI = false, bool SP2 = false>
; __device__ __forceinline__ void gemm_phase(PG8_LAS unsigned char* lds, const Gemm g, const Sched& S, const Epi& E) {
;     ...
;             const bool last = (t == nt - 2);
;             const char* a1 = cA + (size_t)(t + 1) * kstep;
;             const char* a2 = last ? nA : cA + (size_t)(t + 2) * kstep; const char* b2 = last ? nB : cB + (size_t)(t + 2) * kstep;
;             const char* a3 = a2 + kstep; const char* b3 = b2 + kstep;
;             if (last && has_next) S.a_ready(nxt);
;             if constexpr (epi_has_mid<Epi>::value) { if (t == Epi::MID_T) E.mid(acc, cur, wr, wc, fr, fq); }
;             if constexpr (SP2) {
;             PG8_LDB(B0, 0, 0); PG8_LDB(B1, 0, 1); PG8_SCHED; PG8_LDA(At, 0, 0); PG8_STAGE(PG8_SA(1, 1), a1 + hstep, voffA);
;             PG8_WAIT_V(8); PG8_WAIT_L(0); PG8_BAR; PG8_MMA(0, 0, At, B0); PG8_MMA(0, 1, At, B1); PG8_BAR; PG8_SCHED;
;             PG8_LDA(At, 0, 1); PG8_STAGE(PG8_SB(0, 0), b2, voffB); PG8_STAGE(PG8_SB(0, 1), b2 + hstep, voffB); PG8_STAGE(PG8_SA(0, 0), a2, voffA);
;             PG8_WAIT_V(8); PG8_WAIT_L(0); PG8_BAR; PG8_MMA(1, 0, At, B0); PG8_MMA(1, 1, At, B1); PG8_BAR; PG8_SCHED;
.LBB0_789:
	v_add_u32_e32 v164, 0x10000, v149
	v_add_u32_e32 v180, 0x14000, v149
	s_add_u32 s8, s40, 0x100
	s_waitcnt lgkmcnt(0)
	ds_read_b128 v[152:155], v164
	ds_read_b128 v[156:159], v164 offset:1024
	ds_read_b128 v[160:163], v164 offset:2048
	ds_read_b128 v[164:167], v164 offset:3072
	ds_read_b128 v[168:171], v180
	ds_read_b128 v[172:175], v180 offset:1024
	ds_read_b128 v[176:179], v180 offset:2048
	ds_read_b128 v[180:183], v180 offset:3072
	s_addc_u32 s9, s41, 0
	s_and_b64 s[38:39], s[38:39], exec
	s_cselect_b32 s46, s59, s8
	s_cselect_b32 s47, s17, s9
	s_cselect_b32 s39, s15, s75
	s_cselect_b32 s38, s71, s74
	s_add_u32 s42, s46, 0x80
	s_addc_u32 s43, s47, 0
	s_add_u32 s44, s38, 0x80
	s_addc_u32 s45, s39, 0
	ds_read_b128 v[184:187], v150
	ds_read_b128 v[188:191], v150 offset:1024
	ds_read_b128 v[192:195], v150 offset:2048
	ds_read_b128 v[196:199], v150 offset:3072
	ds_read_b128 v[200:203], v150 offset:4096
	ds_read_b128 v[204:207], v150 offset:5120
	ds_read_b128 v[208:211], v150 offset:6144
	ds_read_b128 v[212:215], v150 offset:7168
	s_add_u32 s40, s40, 0x100080
	s_addc_u32 s41, s41, 0
	s_mov_b32 m0, s64
	s_nop 0
	global_load_lds_dwordx4 v139, s[40:41]
	s_nop 0
	s_mov_b32 m0, s65
	s_nop 0
	global_load_lds_dwordx4 v141, s[40:41]
	s_waitcnt vmcnt(8)
	s_waitcnt lgkmcnt(0)
	v_mfma_f32_16x16x32_bf16 v[126:129], v[152:155], v[184:187], v[126:129]
	s_barrier
	s_setprio 1
	s_waitcnt lgkmcnt(7)
	v_mfma_f32_16x16x32_bf16 v[122:125], v[160:163], v[184:187], v[122:125]
	s_waitcnt lgkmcnt(5)
	v_mfma_f32_16x16x32_bf16 v[110:113], v[152:155], v[192:195], v[110:113]
	v_mfma_f32_16x16x32_bf16 v[106:109], v[160:163], v[192:195], v[106:109]
	s_waitcnt lgkmcnt(3)
	v_mfma_f32_16x16x32_bf16 v[94:97], v[152:155], v[200:203], v[94:97]
	v_mfma_f32_16x16x32_bf16 v[90:93], v[160:163], v[200:203], v[90:93]
	s_waitcnt lgkmcnt(1)
	v_mfma_f32_16x16x32_bf16 v[78:81], v[152:155], v[208:211], v[78:81]
	v_mfma_f32_16x16x32_bf16 v[74:77], v[160:163], v[208:211], v[74:77]
	v_mfma_f32_16x16x32_bf16 v[126:129], v[156:159], v[188:191], v[126:129]
	v_mfma_f32_16x16x32_bf16 v[122:125], v[164:167], v[188:191], v[122:125]
	v_mfma_f32_16x16x32_bf16 v[110:113], v[156:159], v[196:199], v[110:113]
	v_mfma_f32_16x16x32_bf16 v[106:109], v[164:167], v[196:199], v[106:109]
	v_mfma_f32_16x16x32_bf16 v[94:97], v[156:159], v[204:207], v[94:97]
	v_mfma_f32_16x16x32_bf16 v[90:93], v[164:167], v[204:207], v[90:93]
	s_waitcnt lgkmcnt(0)
	v_mfma_f32_16x16x32_bf16 v[78:81], v[156:159], v[212:215], v[78:81]
	v_mfma_f32_16x16x32_bf16 v[74:77], v[164:167], v[212:215], v[74:77]
	s_setprio 0
	s_setprio 1
	v_mfma_f32_16x16x32_bf16 v[118:121], v[168:171], v[184:187], v[118:121]
	v_mfma_f32_16x16x32_bf16 v[114:117], v[176:179], v[184:187], v[114:117]
	v_mfma_f32_16x16x32_bf16 v[102:105], v[168:171], v[192:195], v[102:105]
	v_mfma_f32_16x16x32_bf16 v[98:101], v[176:179], v[192:195], v[98:101]
	v_mfma_f32_16x16x32_bf16 v[86:89], v[168:171], v[200:203], v[86:89]
	v_mfma_f32_16x16x32_bf16 v[82:85], v[176:179], v[200:203], v[82:85]
	v_mfma_f32_16x16x32_bf16 v[70:73], v[168:171], v[208:211], v[70:73]
	v_mfma_f32_16x16x32_bf16 v[66:69], v[176:179], v[208:211], v[66:69]
	v_mfma_f32_16x16x32_bf16 v[118:121], v[172:175], v[188:191], v[118:121]
	v_mfma_f32_16x16x32_bf16 v[114:117], v[180:183], v[188:191], v[114:117]
	v_mfma_f32_16x16x32_bf16 v[102:105], v[172:175], v[196:199], v[102:105]
	v_mfma_f32_16x16x32_bf16 v[98:101], v[180:183], v[196:199], v[98:101]
	v_mfma_f32_16x16x32_bf16 v[86:89], v[172:175], v[204:207], v[86:89]
	v_mfma_f32_16x16x32_bf16 v[82:85], v[180:183], v[204:207], v[82:85]
	v_mfma_f32_16x16x32_bf16 v[70:73], v[172:175], v[212:215], v[70:73]
	s_setprio 2
	s_barrier
	v_mfma_f32_16x16x32_bf16 v[66:69], v[180:183], v[212:215], v[66:69]
	s_setprio 0
	ds_read_b128 v[184:187], v150 offset:16384
	ds_read_b128 v[188:191], v150 offset:17408
	ds_read_b128 v[192:195], v150 offset:18432
	ds_read_b128 v[196:199], v150 offset:19456
	ds_read_b128 v[200:203], v150 offset:20480
	ds_read_b128 v[204:207], v150 offset:21504
	ds_read_b128 v[208:211], v150 offset:22528
	ds_read_b128 v[252:255], v150 offset:23552
	s_mov_b32 m0, s49
	s_nop 0
	global_load_lds_dwordx4 v140, s[38:39]
	s_add_u32 s40, s38, 0x100000
	s_mov_b32 m0, s50
	s_nop 0
	global_load_lds_dwordx4 v142, s[38:39]
	s_addc_u32 s41, s39, 0
	s_mov_b32 m0, s51
	s_nop 0
	global_load_lds_dwordx4 v140, s[40:41]
	s_nop 0
	s_mov_b32 m0, s52
	s_nop 0
	global_load_lds_dwordx4 v142, s[40:41]
	s_nop 0
	s_mov_b32 m0, s37
	s_nop 0
	global_load_lds_dwordx4 v139, s[46:47]
	s_nop 0
	s_mov_b32 m0, s53
	s_nop 0
	global_load_lds_dwordx4 v141, s[46:47]
	s_waitcnt vmcnt(8)
	s_waitcnt lgkmcnt(0)
	v_mfma_f32_16x16x32_bf16 v[62:65], v[152:155], v[184:187], v[62:65]
	s_barrier
; #define PG8_STAGE(bufoff, gbase, voff) do { _Pragma("unroll") for (int _i = 0; _i < 2; ++_i) \
;         asm volatile("s_mov_b32 m0, %2\n\ts_nop 0\n\tglobal_load_lds_dwordx4 %0, %1" :: "v"((voff)[_i]), "s"((const char*)(gbase)), "s"(ldsbase + (unsigned)(bufoff) + ldsw + (unsigned)_i * 8192u) : "memory", "m0"); } while (0)
; #define PG8_LDA(dst, b, h) do { _Pragma("unroll") for (int m = 0; m < 4; ++m) _Pragma("unroll") for (int k = 0; k < 2; ++k) dst[m][k] = *(const PG8_LAS bf16x8*)(lds + PG8_SA(b, h) + aoff + m * 2048 + k * 1024); } while (0)
; #define PG8_LDB(dst, b, h) do { _Pragma("unroll") for (int n = 0; n < 2; ++n) _Pragma("unroll") for (int k = 0; k < 2; ++k) dst[n][k] = *(const PG8_LAS bf16x8*)(lds + PG8_SB(b, h) + boff + n * 2048 + k * 1024); } while (0)
; #define PG8_MMA(ai, bj, At, Bt) do { __builtin_amdgcn_s_setprio(1); _Pragma("unroll") for (int m = 0; m < 4; ++m) _Pragma("unroll") for (int n = 0; n < 2; ++n) _Pragma("unroll") for (int k = 0; k < 2; ++k) \
;         acc[ai][bj][m][n] = __builtin_amdgcn_mfma_f32_16x16x32_bf16(Bt[n][k], At[m][k], acc[ai][bj][m][n], 0, 0, 0); __builtin_amdgcn_s_setprio(0); } while (0)
; #define PG8_WAIT_V(n) asm volatile("s_waitcnt vmcnt(" #n ")" ::: "memory")
; #define PG8_WAIT_L(n) asm volatile("s_waitcnt lgkmcnt(" #n ")" ::: "memory")
; #define PG8_BAR __builtin_amdgcn_s_barrier()
; #define PG8_SCHED __builtin_amdgcn_sched_barrier(0)
; template <class Epi, class Sched, bool ALIGN_EPI = false, bool SP2 = false>
; __device__ __forceinline__ void gemm_phase(PG8_LAS unsigned char* lds, const Gemm g, const Sched& S, const Epi& E) {
;     ...
;             PG8_WAIT_V(8); PG8_WAIT_L(0); PG8_BAR; PG8_MMA(0, 0, At, B0); PG8_MMA(0, 1, At, B1); PG8_BAR; PG8_SCHED;
;             PG8_LDA(At, 0, 1); PG8_STAGE(PG8_SB(0, 0), b2, voffB); PG8_STAGE(PG8_SB(0, 1), b2 + hstep, voffB); PG8_STAGE(PG8_SA(0, 0), a2, voffA);
;             PG8_WAIT_V(8); PG8_WAIT_L(0); PG8_BAR; PG8_MMA(1, 0, At, B0); PG8_MMA(1, 1, At, B1); PG8_BAR; PG8_SCHED;
;             PG8_LDB(B0, 1, 0); PG8_LDB(B1, 1, 1); PG8_SCHED; PG8_LDA(At, 1, 0); PG8_STAGE(PG8_SA(0, 1), a2 + hstep, voffA);
;             PG8_WAIT_V(8); PG8_WAIT_L(0); PG8_BAR; PG8_MMA(0, 0, At, B0); PG8_MMA(0, 1, At, B1); PG8_BAR; PG8_SCHED;
	s_setprio 1
	s_waitcnt lgkmcnt(7)
	v_mfma_f32_16x16x32_bf16 v[58:61], v[160:163], v[184:187], v[58:61]
	s_waitcnt lgkmcnt(5)
	v_mfma_f32_16x16x32_bf16 v[46:49], v[152:155], v[192:195], v[46:49]
	v_mfma_f32_16x16x32_bf16 v[42:45], v[160:163], v[192:195], v[42:45]
	s_waitcnt lgkmcnt(3)
	v_mfma_f32_16x16x32_bf16 v[30:33], v[152:155], v[200:203], v[30:33]
	v_mfma_f32_16x16x32_bf16 v[26:29], v[160:163], v[200:203], v[26:29]
	s_waitcnt lgkmcnt(1)
	v_mfma_f32_16x16x32_bf16 v[14:17], v[152:155], v[208:211], v[14:17]
	v_mfma_f32_16x16x32_bf16 v[10:13], v[160:163], v[208:211], v[10:13]
	v_mfma_f32_16x16x32_bf16 v[62:65], v[156:159], v[188:191], v[62:65]
	v_mfma_f32_16x16x32_bf16 v[58:61], v[164:167], v[188:191], v[58:61]
	v_mfma_f32_16x16x32_bf16 v[46:49], v[156:159], v[196:199], v[46:49]
	v_mfma_f32_16x16x32_bf16 v[42:45], v[164:167], v[196:199], v[42:45]
	v_mfma_f32_16x16x32_bf16 v[30:33], v[156:159], v[204:207], v[30:33]
	v_mfma_f32_16x16x32_bf16 v[26:29], v[164:167], v[204:207], v[26:29]
	s_waitcnt lgkmcnt(0)
	v_mfma_f32_16x16x32_bf16 v[14:17], v[156:159], v[252:255], v[14:17]
	v_mfma_f32_16x16x32_bf16 v[10:13], v[164:167], v[252:255], v[10:13]
	s_setprio 0
	s_setprio 1
	v_mfma_f32_16x16x32_bf16 v[54:57], v[168:171], v[184:187], v[54:57]
	v_mfma_f32_16x16x32_bf16 v[50:53], v[176:179], v[184:187], v[50:53]
	v_mfma_f32_16x16x32_bf16 v[38:41], v[168:171], v[192:195], v[38:41]
	v_mfma_f32_16x16x32_bf16 v[34:37], v[176:179], v[192:195], v[34:37]
	v_mfma_f32_16x16x32_bf16 v[22:25], v[168:171], v[200:203], v[22:25]
	v_mfma_f32_16x16x32_bf16 v[18:21], v[176:179], v[200:203], v[18:21]
	v_mfma_f32_16x16x32_bf16 v[6:9], v[168:171], v[208:211], v[6:9]
	v_mfma_f32_16x16x32_bf16 v[2:5], v[176:179], v[208:211], v[2:5]
	v_mfma_f32_16x16x32_bf16 v[54:57], v[172:175], v[188:191], v[54:57]
	v_mfma_f32_16x16x32_bf16 v[50:53], v[180:183], v[188:191], v[50:53]
	v_mfma_f32_16x16x32_bf16 v[38:41], v[172:175], v[196:199], v[38:41]
	v_mfma_f32_16x16x32_bf16 v[34:37], v[180:183], v[196:199], v[34:37]
	v_mfma_f32_16x16x32_bf16 v[22:25], v[172:175], v[204:207], v[22:25]
	v_mfma_f32_16x16x32_bf16 v[18:21], v[180:183], v[204:207], v[18:21]
	v_mfma_f32_16x16x32_bf16 v[6:9], v[172:175], v[252:255], v[6:9]
	s_setprio 2
	s_barrier
	v_mfma_f32_16x16x32_bf16 v[2:5], v[180:183], v[252:255], v[2:5]
	s_setprio 0
	v_add_u32_e32 v164, 0x18000, v149
	v_add_u32_e32 v180, 0x1c000, v149
	ds_read_b128 v[152:155], v164
	ds_read_b128 v[156:159], v164 offset:1024
	ds_read_b128 v[160:163], v164 offset:2048
	ds_read_b128 v[164:167], v164 offset:3072
	ds_read_b128 v[168:171], v180
	ds_read_b128 v[172:175], v180 offset:1024
	ds_read_b128 v[176:179], v180 offset:2048
	ds_read_b128 v[248:251], v180 offset:3072
	ds_read_b128 v[184:187], v150 offset:32768
	ds_read_b128 v[188:191], v150 offset:33792
	ds_read_b128 v[192:195], v150 offset:34816
	ds_read_b128 v[196:199], v150 offset:35840
	ds_read_b128 v[200:203], v150 offset:36864
	ds_read_b128 v[204:207], v150 offset:37888
	ds_read_b128 v[208:211], v150 offset:38912
	ds_read_b128 v[212:215], v150 offset:39936
	s_add_u32 s40, s46, 0x100000
	s_addc_u32 s41, s47, 0
	s_mov_b32 m0, s54
	s_nop 0
	global_load_lds_dwordx4 v139, s[40:41]
	s_nop 0
	s_mov_b32 m0, s55
	s_nop 0
	global_load_lds_dwordx4 v141, s[40:41]
	s_waitcnt vmcnt(8)
	s_waitcnt lgkmcnt(0)
	v_mfma_f32_16x16x32_bf16 v[126:129], v[152:155], v[184:187], v[126:129]
	s_barrier
	s_setprio 1
	s_waitcnt lgkmcnt(7)
	v_mfma_f32_16x16x32_bf16 v[122:125], v[160:163], v[184:187], v[122:125]
	s_waitcnt lgkmcnt(5)
	v_mfma_f32_16x16x32_bf16 v[110:113], v[152:155], v[192:195], v[110:113]
	v_mfma_f32_16x16x32_bf16 v[106:109], v[160:163], v[192:195], v[106:109]
	s_waitcnt lgkmcnt(3)
	v_mfma_f32_16x16x32_bf16 v[94:97], v[152:155], v[200:203], v[94:97]
	v_mfma_f32_16x16x32_bf16 v[90:93], v[160:163], v[200:203], v[90:93]
	s_waitcnt lgkmcnt(1)
	v_mfma_f32_16x16x32_bf16 v[78:81], v[152:155], v[208:211], v[78:81]
	v_mfma_f32_16x16x32_bf16 v[74:77], v[160:163], v[208:211], v[74:77]
	v_mfma_f32_16x16x32_bf16 v[126:129], v[156:159], v[188:191], v[126:129]
	v_mfma_f32_16x16x32_bf16 v[122:125], v[164:167], v[188:191], v[122:125]
	v_mfma_f32_16x16x32_bf16 v[110:113], v[156:159], v[196:199], v[110:113]
	v_mfma_f32_16x16x32_bf16 v[106:109], v[164:167], v[196:199], v[106:109]
	v_mfma_f32_16x16x32_bf16 v[94:97], v[156:159], v[204:207], v[94:97]
	v_mfma_f32_16x16x32_bf16 v[90:93], v[164:167], v[204:207], v[90:93]
	s_waitcnt lgkmcnt(0)
	v_mfma_f32_16x16x32_bf16 v[78:81], v[156:159], v[212:215], v[78:81]
	v_mfma_f32_16x16x32_bf16 v[74:77], v[164:167], v[212:215], v[74:77]
	s_setprio 0
	s_setprio 1
	v_mfma_f32_16x16x32_bf16 v[118:121], v[168:171], v[184:187], v[118:121]
	v_mfma_f32_16x16x32_bf16 v[114:117], v[176:179], v[184:187], v[114:117]
	v_mfma_f32_16x16x32_bf16 v[102:105], v[168:171], v[192:195], v[102:105]
	v_mfma_f32_16x16x32_bf16 v[98:101], v[176:179], v[192:195], v[98:101]
	v_mfma_f32_16x16x32_bf16 v[86:89], v[168:171], v[200:203], v[86:89]
	v_mfma_f32_16x16x32_bf16 v[82:85], v[176:179], v[200:203], v[82:85]
	v_mfma_f32_16x16x32_bf16 v[70:73], v[168:171], v[208:211], v[70:73]
	v_mfma_f32_16x16x32_bf16 v[66:69], v[176:179], v[208:211], v[66:69]
	v_mfma_f32_16x16x32_bf16 v[118:121], v[172:175], v[188:191], v[118:121]
	v_mfma_f32_16x16x32_bf16 v[114:117], v[248:251], v[188:191], v[114:117]
	v_mfma_f32_16x16x32_bf16 v[102:105], v[172:175], v[196:199], v[102:105]
	v_mfma_f32_16x16x32_bf16 v[98:101], v[248:251], v[196:199], v[98:101]
	v_mfma_f32_16x16x32_bf16 v[86:89], v[172:175], v[204:207], v[86:89]
	v_mfma_f32_16x16x32_bf16 v[82:85], v[248:251], v[204:207], v[82:85]
	v_mfma_f32_16x16x32_bf16 v[70:73], v[172:175], v[212:215], v[70:73]
	s_setprio 2
	s_barrier
; #define PG8_STAGE(bufoff, gbase, voff) do { _Pragma("unroll") for (int _i = 0; _i < 2; ++_i) \
;         asm volatile("s_mov_b32 m0, %2\n\ts_nop 0\n\tglobal_load_lds_dwordx4 %0, %1" :: "v"((voff)[_i]), "s"((const char*)(gbase)), "s"(ldsbase + (unsigned)(bufoff) + ldsw + (unsigned)_i * 8192u) : "memory", "m0"); } while (0)
; #define PG8_LDA(dst, b, h) do { _Pragma("unroll") for (int m = 0; m < 4; ++m) _Pragma("unroll") for (int k = 0; k < 2; ++k) dst[m][k] = *(const PG8_LAS bf16x8*)(lds + PG8_SA(b, h) + aoff + m * 2048 + k * 1024); } while (0)
; #define PG8_MMA(ai, bj, At, Bt) do { __builtin_amdgcn_s_setprio(1); _Pragma("unroll") for (int m = 0; m < 4; ++m) _Pragma("unroll") for (int n = 0; n < 2; ++n) _Pragma("unroll") for (int k = 0; k < 2; ++k) \
;         acc[ai][bj][m][n] = __builtin_amdgcn_mfma_f32_16x16x32_bf16(Bt[n][k], At[m][k], acc[ai][bj][m][n], 0, 0, 0); __builtin_amdgcn_s_setprio(0); } while (0)
; #define PG8_WAIT_V(n) asm volatile("s_waitcnt vmcnt(" #n ")" ::: "memory")
; #define PG8_WAIT_L(n) asm volatile("s_waitcnt lgkmcnt(" #n ")" ::: "memory")
; #define PG8_BAR __builtin_amdgcn_s_barrier()
; #define PG8_SCHED __builtin_amdgcn_sched_barrier(0)
; template <class Epi, class Sched, bool ALIGN_EPI = false, bool SP2 = false>
; __device__ __forceinline__ void gemm_phase(PG8_LAS unsigned char* lds, const Gemm g, const Sched& S, const Epi& E) {
;     ...
;             PG8_LDA(At, 1, 1); PG8_STAGE(PG8_SB(1, 0), b3, voffB); PG8_STAGE(PG8_SB(1, 1), b3 + hstep, voffB); PG8_STAGE(PG8_SA(1, 0), a3, voffA);
;             PG8_WAIT_V(8); PG8_WAIT_L(0); PG8_BAR; PG8_MMA(1, 0, At, B0); PG8_MMA(1, 1, At, B1); PG8_BAR; PG8_SCHED;
	v_mfma_f32_16x16x32_bf16 v[66:69], v[248:251], v[212:215], v[66:69]
	s_setprio 0
	ds_read_b128 v[184:187], v150 offset:49152
	ds_read_b128 v[188:191], v150 offset:50176
	ds_read_b128 v[192:195], v150 offset:51200
	ds_read_b128 v[196:199], v150 offset:52224
	ds_read_b128 v[200:203], v150 offset:53248
	ds_read_b128 v[204:207], v150 offset:54272
	ds_read_b128 v[208:211], v150 offset:55296
	ds_read_b128 v[252:255], v150 offset:56320
	s_mov_b32 m0, s56
	s_nop 0
	global_load_lds_dwordx4 v140, s[44:45]
	s_add_u32 s38, s38, 0x100080
	s_mov_b32 m0, s57
	s_nop 0
	global_load_lds_dwordx4 v142, s[44:45]
	s_addc_u32 s39, s39, 0
	s_mov_b32 m0, s62
	s_nop 0
	global_load_lds_dwordx4 v140, s[38:39]
	s_nop 0
	s_mov_b32 m0, s63
	s_nop 0
	global_load_lds_dwordx4 v142, s[38:39]
	s_nop 0
	s_mov_b32 m0, s60
	s_nop 0
	global_load_lds_dwordx4 v139, s[42:43]
	s_nop 0
	s_mov_b32 m0, s61
	s_nop 0
	global_load_lds_dwordx4 v141, s[42:43]
	s_waitcnt vmcnt(8)
	s_waitcnt lgkmcnt(0)
	v_mfma_f32_16x16x32_bf16 v[62:65], v[152:155], v[184:187], v[62:65]
	s_barrier
	s_setprio 1
	s_waitcnt lgkmcnt(7)
	v_mfma_f32_16x16x32_bf16 v[58:61], v[160:163], v[184:187], v[58:61]
	s_waitcnt lgkmcnt(5)
	v_mfma_f32_16x16x32_bf16 v[46:49], v[152:155], v[192:195], v[46:49]
	v_mfma_f32_16x16x32_bf16 v[42:45], v[160:163], v[192:195], v[42:45]
	s_waitcnt lgkmcnt(3)
	v_mfma_f32_16x16x32_bf16 v[30:33], v[152:155], v[200:203], v[30:33]
	v_mfma_f32_16x16x32_bf16 v[26:29], v[160:163], v[200:203], v[26:29]
	s_waitcnt lgkmcnt(1)
	v_mfma_f32_16x16x32_bf16 v[14:17], v[152:155], v[208:211], v[14:17]
	v_mfma_f32_16x16x32_bf16 v[10:13], v[160:163], v[208:211], v[10:13]
	v_mfma_f32_16x16x32_bf16 v[62:65], v[156:159], v[188:191], v[62:65]
	v_mfma_f32_16x16x32_bf16 v[58:61], v[164:167], v[188:191], v[58:61]
	v_mfma_f32_16x16x32_bf16 v[46:49], v[156:159], v[196:199], v[46:49]
	v_mfma_f32_16x16x32_bf16 v[42:45], v[164:167], v[196:199], v[42:45]
	v_mfma_f32_16x16x32_bf16 v[30:33], v[156:159], v[204:207], v[30:33]
	v_mfma_f32_16x16x32_bf16 v[26:29], v[164:167], v[204:207], v[26:29]
	s_waitcnt lgkmcnt(0)
	v_mfma_f32_16x16x32_bf16 v[14:17], v[156:159], v[252:255], v[14:17]
	v_mfma_f32_16x16x32_bf16 v[10:13], v[164:167], v[252:255], v[10:13]
	s_setprio 0
	s_setprio 1
	v_mfma_f32_16x16x32_bf16 v[54:57], v[168:171], v[184:187], v[54:57]
	v_mfma_f32_16x16x32_bf16 v[50:53], v[176:179], v[184:187], v[50:53]
	v_mfma_f32_16x16x32_bf16 v[38:41], v[168:171], v[192:195], v[38:41]
	v_mfma_f32_16x16x32_bf16 v[34:37], v[176:179], v[192:195], v[34:37]
	v_mfma_f32_16x16x32_bf16 v[22:25], v[168:171], v[200:203], v[22:25]
	v_mfma_f32_16x16x32_bf16 v[18:21], v[176:179], v[200:203], v[18:21]
	v_mfma_f32_16x16x32_bf16 v[6:9], v[168:171], v[208:211], v[6:9]
	v_mfma_f32_16x16x32_bf16 v[2:5], v[176:179], v[208:211], v[2:5]
	v_mfma_f32_16x16x32_bf16 v[54:57], v[172:175], v[188:191], v[54:57]
	v_mfma_f32_16x16x32_bf16 v[50:53], v[248:251], v[188:191], v[50:53]
	v_mfma_f32_16x16x32_bf16 v[38:41], v[172:175], v[196:199], v[38:41]
	v_mfma_f32_16x16x32_bf16 v[34:37], v[248:251], v[196:199], v[34:37]
	v_mfma_f32_16x16x32_bf16 v[22:25], v[172:175], v[204:207], v[22:25]
	v_mfma_f32_16x16x32_bf16 v[18:21], v[248:251], v[204:207], v[18:21]
	v_mfma_f32_16x16x32_bf16 v[6:9], v[172:175], v[252:255], v[6:9]
	s_setprio 2
	s_barrier
	v_mfma_f32_16x16x32_bf16 v[2:5], v[248:251], v[252:255], v[2:5]
	s_setprio 0
	s_add_i32 s76, s76, 2
	s_add_u32 s74, s74, 0x100
	s_addc_u32 s75, s75, 0
	s_cmp_gt_u32 s76, 61
	s_cbranch_scc1 .LBB0_780
	s_mov_b64 s[40:41], s[8:9]
	s_branch .LBB0_784

; #define PG8_STAGE(bufoff, gbase, voff) do { _Pragma("unroll") for (int _i = 0; _i < 2; ++_i) \
;         asm volatile("s_mov_b32 m0, %2\n\ts_nop 0\n\tglobal_load_lds_dwordx4 %0, %1" :: "v"((voff)[_i]), "s"((const char*)(gbase)), "s"(ldsbase + (unsigned)(bufoff) + ldsw + (unsigned)_i * 8192u) : "memory", "m0"); } while (0)
; #define PG8_LDA(dst, b, h) do { _Pragma("unroll") for (int m = 0; m < 4; ++m) _Pragma("unroll") for (int k = 0; k < 2; ++k) dst[m][k] = *(const PG8_LAS bf16x8*)(lds + PG8_SA(b, h) + aoff + m * 2048 + k * 1024); } while (0)
; #define PG8_LDB(dst, b, h) do { _Pragma("unroll") for (int n = 0; n < 2; ++n) _Pragma("unroll") for (int k = 0; k < 2; ++k) dst[n][k] = *(const PG8_LAS bf16x8*)(lds + PG8_SB(b, h) + boff + n * 2048 + k * 1024); } while (0)
; #define PG8_MMA(ai, bj, At, Bt) do { __builtin_amdgcn_s_setprio(1); _Pragma("unroll") for (int m = 0; m < 4; ++m) _Pragma("unroll") for (int n = 0; n < 2; ++n) _Pragma("unroll") for (int k = 0; k < 2; ++k) \
;         acc[ai][bj][m][n] = __builtin_amdgcn_mfma_f32_16x16x32_bf16(Bt[n][k], At[m][k], acc[ai][bj][m][n], 0, 0, 0); __builtin_amdgcn_s_setprio(0); } while (0)
; template <class Epi, class Sched, bool ALIGN_EPI = false, bool SP2 = false>
; __device__ __forceinline__ void gemm_phase(PG8_LAS unsigned char* lds, const Gemm g, const Sched& S, const Epi& E) {
;     ...
;             const bool last = (t == nt - 2);
;             const char* a1 = cA + (size_t)(t + 1) * kstep;
;             const char* a2 = last ? nA : cA + (size_t)(t + 2) * kstep; const char* b2 = last ? nB : cB + (size_t)(t + 2) * kstep;
;             const char* a3 = a2 + kstep; const char* b3 = b2 + kstep;
;             if (last && has_next) S.a_ready(nxt);
;             if constexpr (epi_has_mid<Epi>::value) { if (t == Epi::MID_T) E.mid(acc, cur, wr, wc, fr, fq); }
;             if constexpr (SP2) {
;             PG8_LDB(B0, 0, 0); PG8_LDB(B1, 0, 1); PG8_SCHED; PG8_LDA(At, 0, 0); PG8_STAGE(PG8_SA(1, 1), a1 + hstep, voffA);
;             PG8_WAIT_V(8); PG8_WAIT_L(0); PG8_BAR; PG8_MMA(0, 0, At, B0); PG8_MMA(0, 1, At, B1); PG8_BAR; PG8_SCHED;
;             PG8_LDA(At, 0, 1); PG8_STAGE(PG8_SB(0, 0), b2, voffB); PG8_STAGE(PG8_SB(0, 1), b2 + hstep, voffB); PG8_STAGE(PG8_SA(0, 0), a2, voffA);
;             PG8_WAIT_V(8); PG8_WAIT_L(0); PG8_BAR; PG8_MMA(1, 0, At, B0); PG8_MMA(1, 1, At, B1); PG8_BAR; PG8_SCHED;
.LBB0_873:
	ds_read_b128 v[134:137], v145
	ds_read_b128 v[150:153], v145 offset:1024
	ds_read_b128 v[154:157], v145 offset:2048
	ds_read_b128 v[158:161], v145 offset:3072
	ds_read_b128 v[162:165], v146
	ds_read_b128 v[166:169], v146 offset:1024
	ds_read_b128 v[170:173], v146 offset:2048
	ds_read_b128 v[174:177], v146 offset:3072
	s_add_u32 s38, s36, 0x100
	s_addc_u32 s39, s37, 0
	s_cmpk_eq_i32 s69, 0xa8
	s_cselect_b32 s44, s4, s38
	s_cselect_b32 s45, s5, s39
	s_cselect_b32 s42, s22, s67
	s_cselect_b32 s43, s23, s68
	s_add_u32 s40, s44, 0x80
	s_addc_u32 s41, s45, 0
	ds_read_b128 v[178:181], v147
	ds_read_b128 v[182:185], v147 offset:1024
	ds_read_b128 v[186:189], v147 offset:2048
	ds_read_b128 v[190:193], v147 offset:3072
	ds_read_b128 v[194:197], v147 offset:4096
	ds_read_b128 v[198:201], v147 offset:5120
	ds_read_b128 v[202:205], v147 offset:6144
	ds_read_b128 v[206:209], v147 offset:7168
	s_add_u32 s36, s36, 0x2b0080
	s_addc_u32 s37, s37, 0
	s_mov_b32 m0, s60
	s_nop 0
	global_load_lds_dwordx4 v1, s[36:37]
	s_nop 0
	s_mov_b32 m0, s61
	s_nop 0
	global_load_lds_dwordx4 v141, s[36:37]
	s_waitcnt vmcnt(8)
	s_waitcnt lgkmcnt(0)
	v_mfma_f32_16x16x32_bf16 v[126:129], v[134:137], v[178:181], v[126:129]
	s_barrier
	s_setprio 1
	s_waitcnt lgkmcnt(7)
	v_mfma_f32_16x16x32_bf16 v[122:125], v[154:157], v[178:181], v[122:125]
	s_waitcnt lgkmcnt(5)
	v_mfma_f32_16x16x32_bf16 v[110:113], v[134:137], v[186:189], v[110:113]
	v_mfma_f32_16x16x32_bf16 v[106:109], v[154:157], v[186:189], v[106:109]
	s_waitcnt lgkmcnt(3)
	v_mfma_f32_16x16x32_bf16 v[94:97], v[134:137], v[194:197], v[94:97]
	v_mfma_f32_16x16x32_bf16 v[90:93], v[154:157], v[194:197], v[90:93]
	s_waitcnt lgkmcnt(1)
	v_mfma_f32_16x16x32_bf16 v[78:81], v[134:137], v[202:205], v[78:81]
	v_mfma_f32_16x16x32_bf16 v[74:77], v[154:157], v[202:205], v[74:77]
	v_mfma_f32_16x16x32_bf16 v[126:129], v[150:153], v[182:185], v[126:129]
	v_mfma_f32_16x16x32_bf16 v[122:125], v[158:161], v[182:185], v[122:125]
	v_mfma_f32_16x16x32_bf16 v[110:113], v[150:153], v[190:193], v[110:113]
	v_mfma_f32_16x16x32_bf16 v[106:109], v[158:161], v[190:193], v[106:109]
	v_mfma_f32_16x16x32_bf16 v[94:97], v[150:153], v[198:201], v[94:97]
	v_mfma_f32_16x16x32_bf16 v[90:93], v[158:161], v[198:201], v[90:93]
	s_waitcnt lgkmcnt(0)
	v_mfma_f32_16x16x32_bf16 v[78:81], v[150:153], v[206:209], v[78:81]
	v_mfma_f32_16x16x32_bf16 v[74:77], v[158:161], v[206:209], v[74:77]
	s_setprio 0
	s_setprio 1
	v_mfma_f32_16x16x32_bf16 v[118:121], v[162:165], v[178:181], v[118:121]
	v_mfma_f32_16x16x32_bf16 v[114:117], v[170:173], v[178:181], v[114:117]
	v_mfma_f32_16x16x32_bf16 v[102:105], v[162:165], v[186:189], v[102:105]
	v_mfma_f32_16x16x32_bf16 v[98:101], v[170:173], v[186:189], v[98:101]
	v_mfma_f32_16x16x32_bf16 v[86:89], v[162:165], v[194:197], v[86:89]
	v_mfma_f32_16x16x32_bf16 v[82:85], v[170:173], v[194:197], v[82:85]
	v_mfma_f32_16x16x32_bf16 v[70:73], v[162:165], v[202:205], v[70:73]
	v_mfma_f32_16x16x32_bf16 v[66:69], v[170:173], v[202:205], v[66:69]
	v_mfma_f32_16x16x32_bf16 v[118:121], v[166:169], v[182:185], v[118:121]
	v_mfma_f32_16x16x32_bf16 v[114:117], v[174:177], v[182:185], v[114:117]
	v_mfma_f32_16x16x32_bf16 v[102:105], v[166:169], v[190:193], v[102:105]
	v_mfma_f32_16x16x32_bf16 v[98:101], v[174:177], v[190:193], v[98:101]
	v_mfma_f32_16x16x32_bf16 v[86:89], v[166:169], v[198:201], v[86:89]
	v_mfma_f32_16x16x32_bf16 v[82:85], v[174:177], v[198:201], v[82:85]
	v_mfma_f32_16x16x32_bf16 v[70:73], v[166:169], v[206:209], v[70:73]
	s_setprio 2
	s_barrier
	v_mfma_f32_16x16x32_bf16 v[66:69], v[174:177], v[206:209], v[66:69]
	s_setprio 0
	ds_read_b128 v[178:181], v147 offset:16384
	ds_read_b128 v[182:185], v147 offset:17408
	ds_read_b128 v[186:189], v147 offset:18432
	ds_read_b128 v[190:193], v147 offset:19456
	ds_read_b128 v[194:197], v147 offset:20480
	ds_read_b128 v[198:201], v147 offset:21504
	ds_read_b128 v[202:205], v147 offset:22528
	ds_read_b128 v[252:255], v147 offset:23552
	s_mov_b32 m0, s47
	s_nop 0
	global_load_lds_dwordx4 v140, s[42:43]
	s_add_u32 s36, s42, 0x2b0000
	s_mov_b32 m0, s48
	s_nop 0
	global_load_lds_dwordx4 v142, s[42:43]
	s_addc_u32 s37, s43, 0
	s_mov_b32 m0, s49
	s_nop 0
	global_load_lds_dwordx4 v140, s[36:37]
	s_nop 0
	s_mov_b32 m0, s50
	s_nop 0
	global_load_lds_dwordx4 v142, s[36:37]
	s_nop 0
	s_mov_b32 m0, s46
	s_nop 0
	global_load_lds_dwordx4 v1, s[44:45]
	s_nop 0
	s_mov_b32 m0, s51
	s_nop 0
	global_load_lds_dwordx4 v141, s[44:45]
	s_waitcnt vmcnt(8)
	s_waitcnt lgkmcnt(0)
	v_mfma_f32_16x16x32_bf16 v[62:65], v[134:137], v[178:181], v[62:65]
	s_barrier
; #define PG8_STAGE(bufoff, gbase, voff) do { _Pragma("unroll") for (int _i = 0; _i < 2; ++_i) \
;         asm volatile("s_mov_b32 m0, %2\n\ts_nop 0\n\tglobal_load_lds_dwordx4 %0, %1" :: "v"((voff)[_i]), "s"((const char*)(gbase)), "s"(ldsbase + (unsigned)(bufoff) + ldsw + (unsigned)_i * 8192u) : "memory", "m0"); } while (0)
; #define PG8_LDA(dst, b, h) do { _Pragma("unroll") for (int m = 0; m < 4; ++m) _Pragma("unroll") for (int k = 0; k < 2; ++k) dst[m][k] = *(const PG8_LAS bf16x8*)(lds + PG8_SA(b, h) + aoff + m * 2048 + k * 1024); } while (0)
; #define PG8_LDB(dst, b, h) do { _Pragma("unroll") for (int n = 0; n < 2; ++n) _Pragma("unroll") for (int k = 0; k < 2; ++k) dst[n][k] = *(const PG8_LAS bf16x8*)(lds + PG8_SB(b, h) + boff + n * 2048 + k * 1024); } while (0)
; #define PG8_MMA(ai, bj, At, Bt) do { __builtin_amdgcn_s_setprio(1); _Pragma("unroll") for (int m = 0; m < 4; ++m) _Pragma("unroll") for (int n = 0; n < 2; ++n) _Pragma("unroll") for (int k = 0; k < 2; ++k) \
;         acc[ai][bj][m][n] = __builtin_amdgcn_mfma_f32_16x16x32_bf16(Bt[n][k], At[m][k], acc[ai][bj][m][n], 0, 0, 0); __builtin_amdgcn_s_setprio(0); } while (0)
; #define PG8_WAIT_V(n) asm volatile("s_waitcnt vmcnt(" #n ")" ::: "memory")
; #define PG8_WAIT_L(n) asm volatile("s_waitcnt lgkmcnt(" #n ")" ::: "memory")
; #define PG8_BAR __builtin_amdgcn_s_barrier()
; #define PG8_SCHED __builtin_amdgcn_sched_barrier(0)
; template <class Epi, class Sched, bool ALIGN_EPI = false, bool SP2 = false>
; __device__ __forceinline__ void gemm_phase(PG8_LAS unsigned char* lds, const Gemm g, const Sched& S, const Epi& E) {
;     ...
;             PG8_WAIT_V(8); PG8_WAIT_L(0); PG8_BAR; PG8_MMA(0, 0, At, B0); PG8_MMA(0, 1, At, B1); PG8_BAR; PG8_SCHED;
;             PG8_LDA(At, 0, 1); PG8_STAGE(PG8_SB(0, 0), b2, voffB); PG8_STAGE(PG8_SB(0, 1), b2 + hstep, voffB); PG8_STAGE(PG8_SA(0, 0), a2, voffA);
;             PG8_WAIT_V(8); PG8_WAIT_L(0); PG8_BAR; PG8_MMA(1, 0, At, B0); PG8_MMA(1, 1, At, B1); PG8_BAR; PG8_SCHED;
;             PG8_LDB(B0, 1, 0); PG8_LDB(B1, 1, 1); PG8_SCHED; PG8_LDA(At, 1, 0); PG8_STAGE(PG8_SA(0, 1), a2 + hstep, voffA);
;             PG8_WAIT_V(8); PG8_WAIT_L(0); PG8_BAR; PG8_MMA(0, 0, At, B0); PG8_MMA(0, 1, At, B1); PG8_BAR; PG8_SCHED;
	s_setprio 1
	s_waitcnt lgkmcnt(7)
	v_mfma_f32_16x16x32_bf16 v[58:61], v[154:157], v[178:181], v[58:61]
	s_waitcnt lgkmcnt(5)
	v_mfma_f32_16x16x32_bf16 v[46:49], v[134:137], v[186:189], v[46:49]
	v_mfma_f32_16x16x32_bf16 v[42:45], v[154:157], v[186:189], v[42:45]
	s_waitcnt lgkmcnt(3)
	v_mfma_f32_16x16x32_bf16 v[30:33], v[134:137], v[194:197], v[30:33]
	v_mfma_f32_16x16x32_bf16 v[26:29], v[154:157], v[194:197], v[26:29]
	s_waitcnt lgkmcnt(1)
	v_mfma_f32_16x16x32_bf16 v[14:17], v[134:137], v[202:205], v[14:17]
	v_mfma_f32_16x16x32_bf16 v[10:13], v[154:157], v[202:205], v[10:13]
	v_mfma_f32_16x16x32_bf16 v[62:65], v[150:153], v[182:185], v[62:65]
	v_mfma_f32_16x16x32_bf16 v[58:61], v[158:161], v[182:185], v[58:61]
	v_mfma_f32_16x16x32_bf16 v[46:49], v[150:153], v[190:193], v[46:49]
	v_mfma_f32_16x16x32_bf16 v[42:45], v[158:161], v[190:193], v[42:45]
	v_mfma_f32_16x16x32_bf16 v[30:33], v[150:153], v[198:201], v[30:33]
	v_mfma_f32_16x16x32_bf16 v[26:29], v[158:161], v[198:201], v[26:29]
	s_waitcnt lgkmcnt(0)
	v_mfma_f32_16x16x32_bf16 v[14:17], v[150:153], v[252:255], v[14:17]
	v_mfma_f32_16x16x32_bf16 v[10:13], v[158:161], v[252:255], v[10:13]
	s_setprio 0
	s_setprio 1
	v_mfma_f32_16x16x32_bf16 v[54:57], v[162:165], v[178:181], v[54:57]
	v_mfma_f32_16x16x32_bf16 v[50:53], v[170:173], v[178:181], v[50:53]
	v_mfma_f32_16x16x32_bf16 v[38:41], v[162:165], v[186:189], v[38:41]
	v_mfma_f32_16x16x32_bf16 v[34:37], v[170:173], v[186:189], v[34:37]
	v_mfma_f32_16x16x32_bf16 v[22:25], v[162:165], v[194:197], v[22:25]
	v_mfma_f32_16x16x32_bf16 v[18:21], v[170:173], v[194:197], v[18:21]
	v_mfma_f32_16x16x32_bf16 v[6:9], v[162:165], v[202:205], v[6:9]
	v_mfma_f32_16x16x32_bf16 v[2:5], v[170:173], v[202:205], v[2:5]
	v_mfma_f32_16x16x32_bf16 v[54:57], v[166:169], v[182:185], v[54:57]
	v_mfma_f32_16x16x32_bf16 v[50:53], v[174:177], v[182:185], v[50:53]
	v_mfma_f32_16x16x32_bf16 v[38:41], v[166:169], v[190:193], v[38:41]
	v_mfma_f32_16x16x32_bf16 v[34:37], v[174:177], v[190:193], v[34:37]
	v_mfma_f32_16x16x32_bf16 v[22:25], v[166:169], v[198:201], v[22:25]
	v_mfma_f32_16x16x32_bf16 v[18:21], v[174:177], v[198:201], v[18:21]
	v_mfma_f32_16x16x32_bf16 v[6:9], v[166:169], v[252:255], v[6:9]
	s_setprio 2
	s_barrier
	v_mfma_f32_16x16x32_bf16 v[2:5], v[174:177], v[252:255], v[2:5]
	s_setprio 0
	ds_read_b128 v[134:137], v148
	ds_read_b128 v[150:153], v148 offset:1024
	ds_read_b128 v[154:157], v148 offset:2048
	ds_read_b128 v[158:161], v148 offset:3072
	ds_read_b128 v[162:165], v149
	ds_read_b128 v[166:169], v149 offset:1024
	ds_read_b128 v[170:173], v149 offset:2048
	ds_read_b128 v[248:251], v149 offset:3072
	ds_read_b128 v[178:181], v147 offset:32768
	ds_read_b128 v[182:185], v147 offset:33792
	ds_read_b128 v[186:189], v147 offset:34816
	ds_read_b128 v[190:193], v147 offset:35840
	ds_read_b128 v[194:197], v147 offset:36864
	ds_read_b128 v[198:201], v147 offset:37888
	ds_read_b128 v[202:205], v147 offset:38912
	ds_read_b128 v[206:209], v147 offset:39936
	s_add_u32 s36, s44, 0x2b0000
	s_addc_u32 s37, s45, 0
	s_mov_b32 m0, s52
	s_nop 0
	global_load_lds_dwordx4 v1, s[36:37]
	s_nop 0
	s_mov_b32 m0, s53
	s_nop 0
	global_load_lds_dwordx4 v141, s[36:37]
	s_waitcnt vmcnt(8)
	s_waitcnt lgkmcnt(0)
	v_mfma_f32_16x16x32_bf16 v[126:129], v[134:137], v[178:181], v[126:129]
	s_barrier
	s_setprio 1
	s_waitcnt lgkmcnt(7)
	v_mfma_f32_16x16x32_bf16 v[122:125], v[154:157], v[178:181], v[122:125]
	s_waitcnt lgkmcnt(5)
	v_mfma_f32_16x16x32_bf16 v[110:113], v[134:137], v[186:189], v[110:113]
	v_mfma_f32_16x16x32_bf16 v[106:109], v[154:157], v[186:189], v[106:109]
	s_waitcnt lgkmcnt(3)
	v_mfma_f32_16x16x32_bf16 v[94:97], v[134:137], v[194:197], v[94:97]
	v_mfma_f32_16x16x32_bf16 v[90:93], v[154:157], v[194:197], v[90:93]
	s_waitcnt lgkmcnt(1)
	v_mfma_f32_16x16x32_bf16 v[78:81], v[134:137], v[202:205], v[78:81]
	v_mfma_f32_16x16x32_bf16 v[74:77], v[154:157], v[202:205], v[74:77]
	v_mfma_f32_16x16x32_bf16 v[126:129], v[150:153], v[182:185], v[126:129]
	v_mfma_f32_16x16x32_bf16 v[122:125], v[158:161], v[182:185], v[122:125]
	v_mfma_f32_16x16x32_bf16 v[110:113], v[150:153], v[190:193], v[110:113]
	v_mfma_f32_16x16x32_bf16 v[106:109], v[158:161], v[190:193], v[106:109]
	v_mfma_f32_16x16x32_bf16 v[94:97], v[150:153], v[198:201], v[94:97]
	v_mfma_f32_16x16x32_bf16 v[90:93], v[158:161], v[198:201], v[90:93]
	s_waitcnt lgkmcnt(0)
	v_mfma_f32_16x16x32_bf16 v[78:81], v[150:153], v[206:209], v[78:81]
	v_mfma_f32_16x16x32_bf16 v[74:77], v[158:161], v[206:209], v[74:77]
	s_setprio 0
	s_setprio 1
	v_mfma_f32_16x16x32_bf16 v[118:121], v[162:165], v[178:181], v[118:121]
	v_mfma_f32_16x16x32_bf16 v[114:117], v[170:173], v[178:181], v[114:117]
	v_mfma_f32_16x16x32_bf16 v[102:105], v[162:165], v[186:189], v[102:105]
	v_mfma_f32_16x16x32_bf16 v[98:101], v[170:173], v[186:189], v[98:101]
	v_mfma_f32_16x16x32_bf16 v[86:89], v[162:165], v[194:197], v[86:89]
	v_mfma_f32_16x16x32_bf16 v[82:85], v[170:173], v[194:197], v[82:85]
	v_mfma_f32_16x16x32_bf16 v[70:73], v[162:165], v[202:205], v[70:73]
	v_mfma_f32_16x16x32_bf16 v[66:69], v[170:173], v[202:205], v[66:69]
	v_mfma_f32_16x16x32_bf16 v[118:121], v[166:169], v[182:185], v[118:121]
	v_mfma_f32_16x16x32_bf16 v[114:117], v[248:251], v[182:185], v[114:117]
	v_mfma_f32_16x16x32_bf16 v[102:105], v[166:169], v[190:193], v[102:105]
	v_mfma_f32_16x16x32_bf16 v[98:101], v[248:251], v[190:193], v[98:101]
	v_mfma_f32_16x16x32_bf16 v[86:89], v[166:169], v[198:201], v[86:89]
	v_mfma_f32_16x16x32_bf16 v[82:85], v[248:251], v[198:201], v[82:85]
	v_mfma_f32_16x16x32_bf16 v[70:73], v[166:169], v[206:209], v[70:73]
	s_setprio 2
	s_barrier
; #define PG8_STAGE(bufoff, gbase, voff) do { _Pragma("unroll") for (int _i = 0; _i < 2; ++_i) \
;         asm volatile("s_mov_b32 m0, %2\n\ts_nop 0\n\tglobal_load_lds_dwordx4 %0, %1" :: "v"((voff)[_i]), "s"((const char*)(gbase)), "s"(ldsbase + (unsigned)(bufoff) + ldsw + (unsigned)_i * 8192u) : "memory", "m0"); } while (0)
; #define PG8_LDA(dst, b, h) do { _Pragma("unroll") for (int m = 0; m < 4; ++m) _Pragma("unroll") for (int k = 0; k < 2; ++k) dst[m][k] = *(const PG8_LAS bf16x8*)(lds + PG8_SA(b, h) + aoff + m * 2048 + k * 1024); } while (0)
; #define PG8_MMA(ai, bj, At, Bt) do { __builtin_amdgcn_s_setprio(1); _Pragma("unroll") for (int m = 0; m < 4; ++m) _Pragma("unroll") for (int n = 0; n < 2; ++n) _Pragma("unroll") for (int k = 0; k < 2; ++k) \
;         acc[ai][bj][m][n] = __builtin_amdgcn_mfma_f32_16x16x32_bf16(Bt[n][k], At[m][k], acc[ai][bj][m][n], 0, 0, 0); __builtin_amdgcn_s_setprio(0); } while (0)
; #define PG8_WAIT_V(n) asm volatile("s_waitcnt vmcnt(" #n ")" ::: "memory")
; #define PG8_WAIT_L(n) asm volatile("s_waitcnt lgkmcnt(" #n ")" ::: "memory")
; #define PG8_BAR __builtin_amdgcn_s_barrier()
; #define PG8_SCHED __builtin_amdgcn_sched_barrier(0)
; template <class Epi, class Sched, bool ALIGN_EPI = false, bool SP2 = false>
; __device__ __forceinline__ void gemm_phase(PG8_LAS unsigned char* lds, const Gemm g, const Sched& S, const Epi& E) {
;     ...
;             PG8_LDA(At, 1, 1); PG8_STAGE(PG8_SB(1, 0), b3, voffB); PG8_STAGE(PG8_SB(1, 1), b3 + hstep, voffB); PG8_STAGE(PG8_SA(1, 0), a3, voffA);
;             PG8_WAIT_V(8); PG8_WAIT_L(0); PG8_BAR; PG8_MMA(1, 0, At, B0); PG8_MMA(1, 1, At, B1); PG8_BAR; PG8_SCHED;
;     ...
;         if constexpr (ALIGN_EPI) { if (wr == 0) PG8_BAR; }
	v_mfma_f32_16x16x32_bf16 v[66:69], v[248:251], v[206:209], v[66:69]
	s_setprio 0
	ds_read_b128 v[178:181], v147 offset:49152
	ds_read_b128 v[182:185], v147 offset:50176
	ds_read_b128 v[186:189], v147 offset:51200
	ds_read_b128 v[190:193], v147 offset:52224
	ds_read_b128 v[194:197], v147 offset:53248
	ds_read_b128 v[198:201], v147 offset:54272
	ds_read_b128 v[202:205], v147 offset:55296
	ds_read_b128 v[252:255], v147 offset:56320
	s_add_u32 s36, s42, 0x80
	s_addc_u32 s37, s43, 0
	s_mov_b32 m0, s54
	s_nop 0
	global_load_lds_dwordx4 v140, s[36:37]
	s_nop 0
	s_mov_b32 m0, s55
	s_nop 0
	global_load_lds_dwordx4 v142, s[36:37]
	s_add_u32 s36, s42, 0x2b0080
	s_addc_u32 s37, s43, 0
	s_mov_b32 m0, s58
	s_nop 0
	global_load_lds_dwordx4 v140, s[36:37]
	s_nop 0
	s_mov_b32 m0, s59
	s_nop 0
	global_load_lds_dwordx4 v142, s[36:37]
	s_nop 0
	s_mov_b32 m0, s56
	s_nop 0
	global_load_lds_dwordx4 v1, s[40:41]
	s_nop 0
	s_mov_b32 m0, s57
	s_nop 0
	global_load_lds_dwordx4 v141, s[40:41]
	s_waitcnt vmcnt(8)
	s_waitcnt lgkmcnt(0)
	v_mfma_f32_16x16x32_bf16 v[62:65], v[134:137], v[178:181], v[62:65]
	s_barrier
	s_setprio 1
	s_waitcnt lgkmcnt(7)
	v_mfma_f32_16x16x32_bf16 v[58:61], v[154:157], v[178:181], v[58:61]
	s_waitcnt lgkmcnt(5)
	v_mfma_f32_16x16x32_bf16 v[46:49], v[134:137], v[186:189], v[46:49]
	v_mfma_f32_16x16x32_bf16 v[42:45], v[154:157], v[186:189], v[42:45]
	s_waitcnt lgkmcnt(3)
	v_mfma_f32_16x16x32_bf16 v[30:33], v[134:137], v[194:197], v[30:33]
	v_mfma_f32_16x16x32_bf16 v[26:29], v[154:157], v[194:197], v[26:29]
	s_waitcnt lgkmcnt(1)
	v_mfma_f32_16x16x32_bf16 v[14:17], v[134:137], v[202:205], v[14:17]
	v_mfma_f32_16x16x32_bf16 v[10:13], v[154:157], v[202:205], v[10:13]
	v_mfma_f32_16x16x32_bf16 v[62:65], v[150:153], v[182:185], v[62:65]
	v_mfma_f32_16x16x32_bf16 v[58:61], v[158:161], v[182:185], v[58:61]
	v_mfma_f32_16x16x32_bf16 v[46:49], v[150:153], v[190:193], v[46:49]
	v_mfma_f32_16x16x32_bf16 v[42:45], v[158:161], v[190:193], v[42:45]
	v_mfma_f32_16x16x32_bf16 v[30:33], v[150:153], v[198:201], v[30:33]
	v_mfma_f32_16x16x32_bf16 v[26:29], v[158:161], v[198:201], v[26:29]
	s_waitcnt lgkmcnt(0)
	v_mfma_f32_16x16x32_bf16 v[14:17], v[150:153], v[252:255], v[14:17]
	v_mfma_f32_16x16x32_bf16 v[10:13], v[158:161], v[252:255], v[10:13]
	s_setprio 0
	s_setprio 1
	v_mfma_f32_16x16x32_bf16 v[54:57], v[162:165], v[178:181], v[54:57]
	v_mfma_f32_16x16x32_bf16 v[50:53], v[170:173], v[178:181], v[50:53]
	v_mfma_f32_16x16x32_bf16 v[38:41], v[162:165], v[186:189], v[38:41]
	v_mfma_f32_16x16x32_bf16 v[34:37], v[170:173], v[186:189], v[34:37]
	v_mfma_f32_16x16x32_bf16 v[22:25], v[162:165], v[194:197], v[22:25]
	v_mfma_f32_16x16x32_bf16 v[18:21], v[170:173], v[194:197], v[18:21]
	v_mfma_f32_16x16x32_bf16 v[6:9], v[162:165], v[202:205], v[6:9]
	v_mfma_f32_16x16x32_bf16 v[2:5], v[170:173], v[202:205], v[2:5]
	v_mfma_f32_16x16x32_bf16 v[54:57], v[166:169], v[182:185], v[54:57]
	v_mfma_f32_16x16x32_bf16 v[50:53], v[248:251], v[182:185], v[50:53]
	v_mfma_f32_16x16x32_bf16 v[38:41], v[166:169], v[190:193], v[38:41]
	v_mfma_f32_16x16x32_bf16 v[34:37], v[248:251], v[190:193], v[34:37]
	v_mfma_f32_16x16x32_bf16 v[22:25], v[166:169], v[198:201], v[22:25]
	v_mfma_f32_16x16x32_bf16 v[18:21], v[248:251], v[198:201], v[18:21]
	v_mfma_f32_16x16x32_bf16 v[6:9], v[166:169], v[252:255], v[6:9]
	s_setprio 2
	s_barrier
	v_mfma_f32_16x16x32_bf16 v[2:5], v[248:251], v[252:255], v[2:5]
	s_setprio 0
	s_add_i32 s69, s69, 2
	s_add_u32 s67, s67, 0x100
	s_addc_u32 s68, s68, 0
	s_cmpk_gt_u32 s69, 0xa9
	s_mov_b64 s[36:37], s[38:39]
	s_cbranch_scc0 .LBB0_873
	s_and_b64 vcc, exec, s[10:11]
	s_cbranch_vccz .LBB0_876
	s_barrier
